# K-loop priorities shifted up: MMA wave prio 2, LD wave prio 1, epilogue/transition prio 0
# speedup vs baseline: 1.0004x; 1.0004x over previous
; #define PG8_STAGE(bufoff, gbase, voff) do { _Pragma("unroll") for (int _i = 0; _i < 2; ++_i) \
;         __builtin_amdgcn_global_load_lds((const unsigned*)((const char*)(gbase) + (voff)[_i]), (PG8_LAS unsigned*)(lds + (bufoff) + ldsw + _i * 8192), 16, 0, 0); } while (0)
; #define PG8_LDA(dst, b, h) do { _Pragma("unroll") for (int m = 0; m < 4; ++m) _Pragma("unroll") for (int k = 0; k < 2; ++k) dst[m][k] = *(const PG8_LAS bf16x8*)(lds + PG8_SA(b, h) + aoff + m * 2048 + k * 1024); } while (0)
; #define PG8_LDB(dst, b, h) do { _Pragma("unroll") for (int n = 0; n < 2; ++n) _Pragma("unroll") for (int k = 0; k < 2; ++k) dst[n][k] = *(const PG8_LAS bf16x8*)(lds + PG8_SB(b, h) + boff + n * 2048 + k * 1024); } while (0)
; #define PG8_WAIT_V(n) asm volatile("s_waitcnt vmcnt(" #n ")" ::: "memory")
; #define PG8_WAIT_L(n) asm volatile("s_waitcnt lgkmcnt(" #n ")" ::: "memory")
; #define PG8_BAR __builtin_amdgcn_s_barrier()
; #define PG8_SCHED __builtin_amdgcn_sched_barrier(0)
; template <class Epi, class Sched, bool ALIGN_EPI = false, bool SP2 = false, bool F16 = false>
; __device__ __forceinline__ void gemm_phase(PG8_LAS unsigned char* lds, const Gemm g, const Sched& S, const Epi& E) {
;     ...
;             if constexpr (SP2) {
;             PG8_LDB(B0, 0, 0); PG8_LDB(B1, 0, 1); PG8_SCHED; PG8_LDA(At, 0, 0); PG8_STAGE(PG8_SA(1, 1), a1 + hstepA, voffA);
;             PG8_WAIT_V(8); PG8_WAIT_L(0); PG8_BAR; PG8_MMA(0, 0, At, B0); PG8_MMA(0, 1, At, B1); PG8_BAR; PG8_SCHED;
;             PG8_LDA(At, 0, 1); PG8_STAGE(PG8_SB(0, 0), b2, voffB); PG8_STAGE(PG8_SB(0, 1), b2 + hstepB, voffB); PG8_STAGE(PG8_SA(0, 0), a2, voffA);
;             PG8_WAIT_V(8); PG8_WAIT_L(0); PG8_BAR; PG8_MMA(1, 0, At, B0); PG8_MMA(1, 1, At, B1); PG8_BAR; PG8_SCHED;
.Lpk_gu:
	s_setprio 1
	s_add_i32 s82, s54, 2
	s_add_u32 s83, s52, 0x80
	s_addc_u32 s55, s53, 0
	s_add_i32 vcc_lo, 0, 0x10000
	s_cmp_eq_u32 s74, s54
	s_cselect_b32 s55, s39, s55
	s_cselect_b32 s54, s38, s83
	s_cselect_b32 s95, s47, s81
	s_cselect_b32 s94, s46, s80
	s_add_i32 s83, 0, 0x14000
	ds_read_b128 v[130:133], v139
	ds_read_b128 v[134:137], v139 offset:1024
	ds_read_b128 v[152:155], v139 offset:2048
	ds_read_b128 v[156:159], v139 offset:3072
	ds_read_b128 v[160:163], v141
	ds_read_b128 v[166:169], v141 offset:1024
	ds_read_b128 v[184:187], v141 offset:2048
	ds_read_b128 v[188:191], v141 offset:3072
	s_add_i32 m0, s22, 0xc000
	ds_read_b128 v[192:195], v183
	ds_read_b128 v[204:207], v183 offset:1024
	ds_read_b128 v[208:211], v183 offset:2048
	ds_read_b128 v[212:215], v183 offset:3072
	ds_read_b128 v[216:219], v183 offset:4096
	ds_read_b128 v[220:223], v183 offset:5120
	ds_read_b128 v[224:227], v183 offset:6144
	ds_read_b128 v[228:231], v183 offset:7168
	global_load_lds_dwordx4 v148, s[52:53]
	s_add_i32 m0, s22, 0xe000
	s_nop 0
	global_load_lds_dwordx4 v150, s[52:53]
	s_waitcnt vmcnt(8)
	s_waitcnt lgkmcnt(0)
	s_setprio 2
	s_barrier
	v_mfma_f32_16x16x32_f16 v[122:125], v[130:133], v[192:195], 0
	v_mfma_f32_16x16x32_f16 v[114:117], v[152:155], v[192:195], 0
	v_mfma_f32_16x16x32_f16 v[106:109], v[130:133], v[208:211], 0
	v_mfma_f32_16x16x32_f16 v[98:101], v[152:155], v[208:211], 0
	v_mfma_f32_16x16x32_f16 v[90:93], v[130:133], v[216:219], 0
	v_mfma_f32_16x16x32_f16 v[82:85], v[152:155], v[216:219], 0
	v_mfma_f32_16x16x32_f16 v[74:77], v[130:133], v[224:227], 0
	v_mfma_f32_16x16x32_f16 v[66:69], v[152:155], v[224:227], 0
	v_mfma_f32_16x16x32_f16 v[122:125], v[134:137], v[204:207], v[122:125]
	v_mfma_f32_16x16x32_f16 v[114:117], v[156:159], v[204:207], v[114:117]
	v_mfma_f32_16x16x32_f16 v[106:109], v[134:137], v[212:215], v[106:109]
	v_mfma_f32_16x16x32_f16 v[98:101], v[156:159], v[212:215], v[98:101]
	v_mfma_f32_16x16x32_f16 v[90:93], v[134:137], v[220:223], v[90:93]
	v_mfma_f32_16x16x32_f16 v[82:85], v[156:159], v[220:223], v[82:85]
	v_mfma_f32_16x16x32_f16 v[74:77], v[134:137], v[228:231], v[74:77]
	v_mfma_f32_16x16x32_f16 v[66:69], v[156:159], v[228:231], v[66:69]
	v_mfma_f32_16x16x32_f16 v[126:129], v[160:163], v[192:195], 0
	v_mfma_f32_16x16x32_f16 v[118:121], v[184:187], v[192:195], 0
	v_mfma_f32_16x16x32_f16 v[110:113], v[160:163], v[208:211], 0
	v_mfma_f32_16x16x32_f16 v[102:105], v[184:187], v[208:211], 0
	v_mfma_f32_16x16x32_f16 v[94:97], v[160:163], v[216:219], 0
	v_mfma_f32_16x16x32_f16 v[86:89], v[184:187], v[216:219], 0
	v_mfma_f32_16x16x32_f16 v[78:81], v[160:163], v[224:227], 0
	v_mfma_f32_16x16x32_f16 v[70:73], v[184:187], v[224:227], 0
	v_mfma_f32_16x16x32_f16 v[126:129], v[166:169], v[204:207], v[126:129]
	v_mfma_f32_16x16x32_f16 v[118:121], v[188:191], v[204:207], v[118:121]
	v_mfma_f32_16x16x32_f16 v[110:113], v[166:169], v[212:215], v[110:113]
	v_mfma_f32_16x16x32_f16 v[102:105], v[188:191], v[212:215], v[102:105]
	v_mfma_f32_16x16x32_f16 v[94:97], v[166:169], v[220:223], v[94:97]
	v_mfma_f32_16x16x32_f16 v[86:89], v[188:191], v[220:223], v[86:89]
	v_mfma_f32_16x16x32_f16 v[78:81], v[166:169], v[228:231], v[78:81]
	v_mfma_f32_16x16x32_f16 v[70:73], v[188:191], v[228:231], v[70:73]
	s_barrier
	s_setprio 1
	s_add_i32 vcc_lo, vcc_lo, s2
	s_mov_b32 m0, vcc_lo
	s_nop 0
	global_load_lds_dwordx4 v142, s[94:95]
	ds_read_b128 v[192:195], v183 offset:16384
	ds_read_b128 v[204:207], v183 offset:17408
	ds_read_b128 v[208:211], v183 offset:18432
	ds_read_b128 v[212:215], v183 offset:19456
	ds_read_b128 v[216:219], v183 offset:20480
	ds_read_b128 v[220:223], v183 offset:21504
	ds_read_b128 v[224:227], v183 offset:22528
	ds_read_b128 v[228:231], v183 offset:23552
	s_add_i32 m0, vcc_lo, 0x2000
	s_nop 0
	global_load_lds_dwordx4 v138, s[94:95]
	s_add_i32 s83, s83, s2
	s_add_u32 s94, s94, s48
	s_addc_u32 s95, s95, 0
	s_mov_b32 m0, s83
	s_nop 0
	global_load_lds_dwordx4 v142, s[94:95]
	s_add_i32 m0, s83, 0x2000
	s_nop 0
	global_load_lds_dwordx4 v138, s[94:95]
	s_mov_b32 m0, s22
	s_nop 0
	global_load_lds_dwordx4 v144, s[54:55]
	s_mov_b32 m0, s33
	s_nop 0
	global_load_lds_dwordx4 v140, s[54:55]
	s_waitcnt vmcnt(8)
	s_waitcnt lgkmcnt(0)
	s_setprio 2
	s_barrier
	v_mfma_f32_16x16x32_f16 v[58:61], v[130:133], v[192:195], 0
	v_mfma_f32_16x16x32_f16 v[50:53], v[152:155], v[192:195], 0
	v_mfma_f32_16x16x32_f16 v[42:45], v[130:133], v[208:211], 0
	v_mfma_f32_16x16x32_f16 v[34:37], v[152:155], v[208:211], 0
	v_mfma_f32_16x16x32_f16 v[26:29], v[130:133], v[216:219], 0
	v_mfma_f32_16x16x32_f16 v[18:21], v[152:155], v[216:219], 0
	v_mfma_f32_16x16x32_f16 v[10:13], v[130:133], v[224:227], 0
	v_mfma_f32_16x16x32_f16 v[6:9], v[152:155], v[224:227], 0
	v_mfma_f32_16x16x32_f16 v[58:61], v[134:137], v[204:207], v[58:61]
	v_mfma_f32_16x16x32_f16 v[50:53], v[156:159], v[204:207], v[50:53]
	v_mfma_f32_16x16x32_f16 v[42:45], v[134:137], v[212:215], v[42:45]
	v_mfma_f32_16x16x32_f16 v[34:37], v[156:159], v[212:215], v[34:37]
	v_mfma_f32_16x16x32_f16 v[26:29], v[134:137], v[220:223], v[26:29]
	v_mfma_f32_16x16x32_f16 v[18:21], v[156:159], v[220:223], v[18:21]
	v_mfma_f32_16x16x32_f16 v[10:13], v[134:137], v[228:231], v[10:13]
	v_mfma_f32_16x16x32_f16 v[6:9], v[156:159], v[228:231], v[6:9]
	v_mfma_f32_16x16x32_f16 v[62:65], v[160:163], v[192:195], 0
	v_mfma_f32_16x16x32_f16 v[54:57], v[184:187], v[192:195], 0
	v_mfma_f32_16x16x32_f16 v[46:49], v[160:163], v[208:211], 0
	v_mfma_f32_16x16x32_f16 v[38:41], v[184:187], v[208:211], 0
	v_mfma_f32_16x16x32_f16 v[30:33], v[160:163], v[216:219], 0
	v_mfma_f32_16x16x32_f16 v[22:25], v[184:187], v[216:219], 0
	v_mfma_f32_16x16x32_f16 v[14:17], v[160:163], v[224:227], 0
	v_mfma_f32_16x16x32_f16 v[2:5], v[184:187], v[224:227], 0
	v_mfma_f32_16x16x32_f16 v[62:65], v[166:169], v[204:207], v[62:65]
	v_mfma_f32_16x16x32_f16 v[54:57], v[188:191], v[204:207], v[54:57]
	v_mfma_f32_16x16x32_f16 v[46:49], v[166:169], v[212:215], v[46:49]
	v_mfma_f32_16x16x32_f16 v[38:41], v[188:191], v[212:215], v[38:41]
	v_mfma_f32_16x16x32_f16 v[30:33], v[166:169], v[220:223], v[30:33]
	v_mfma_f32_16x16x32_f16 v[22:25], v[188:191], v[220:223], v[22:25]
	v_mfma_f32_16x16x32_f16 v[14:17], v[166:169], v[228:231], v[14:17]
	v_mfma_f32_16x16x32_f16 v[2:5], v[188:191], v[228:231], v[2:5]
	s_barrier
; #define PG8_STAGE(bufoff, gbase, voff) do { _Pragma("unroll") for (int _i = 0; _i < 2; ++_i) \
;         __builtin_amdgcn_global_load_lds((const unsigned*)((const char*)(gbase) + (voff)[_i]), (PG8_LAS unsigned*)(lds + (bufoff) + ldsw + _i * 8192), 16, 0, 0); } while (0)
; #define PG8_LDA(dst, b, h) do { _Pragma("unroll") for (int m = 0; m < 4; ++m) _Pragma("unroll") for (int k = 0; k < 2; ++k) dst[m][k] = *(const PG8_LAS bf16x8*)(lds + PG8_SA(b, h) + aoff + m * 2048 + k * 1024); } while (0)
; #define PG8_LDB(dst, b, h) do { _Pragma("unroll") for (int n = 0; n < 2; ++n) _Pragma("unroll") for (int k = 0; k < 2; ++k) dst[n][k] = *(const PG8_LAS bf16x8*)(lds + PG8_SB(b, h) + boff + n * 2048 + k * 1024); } while (0)
; #define PG8_WAIT_V(n) asm volatile("s_waitcnt vmcnt(" #n ")" ::: "memory")
; #define PG8_WAIT_L(n) asm volatile("s_waitcnt lgkmcnt(" #n ")" ::: "memory")
; #define PG8_BAR __builtin_amdgcn_s_barrier()
; #define PG8_SCHED __builtin_amdgcn_sched_barrier(0)
; template <class Epi, class Sched, bool ALIGN_EPI = false, bool SP2 = false, bool F16 = false>
; __device__ __forceinline__ void gemm_phase(PG8_LAS unsigned char* lds, const Gemm g, const Sched& S, const Epi& E) {
;     ...
;             PG8_LDB(B0, 1, 0); PG8_LDB(B1, 1, 1); PG8_SCHED; PG8_LDA(At, 1, 0); PG8_STAGE(PG8_SA(0, 1), a2 + hstepA, voffA);
;             PG8_WAIT_V(8); PG8_WAIT_L(0); PG8_BAR; PG8_MMA(0, 0, At, B0); PG8_MMA(0, 1, At, B1); PG8_BAR; PG8_SCHED;
;             PG8_LDA(At, 1, 1); PG8_STAGE(PG8_SB(1, 0), b3, voffB); PG8_STAGE(PG8_SB(1, 1), b3 + hstepB, voffB); PG8_STAGE(PG8_SA(1, 0), a3, voffA);
;             PG8_WAIT_V(8); PG8_WAIT_L(0); PG8_BAR; PG8_MMA(1, 0, At, B0); PG8_MMA(1, 1, At, B1); PG8_BAR; PG8_SCHED;
	s_setprio 1
	s_add_i32 s83, 0, 0x18000
	s_add_i32 s94, 0, 0x1c000
	ds_read_b128 v[130:133], v143
	ds_read_b128 v[134:137], v143 offset:1024
	ds_read_b128 v[152:155], v143 offset:2048
	ds_read_b128 v[156:159], v143 offset:3072
	ds_read_b128 v[160:163], v145
	ds_read_b128 v[166:169], v145 offset:1024
	ds_read_b128 v[184:187], v145 offset:2048
	ds_read_b128 v[188:191], v145 offset:3072
	s_add_u32 s54, s54, s8
	s_addc_u32 s55, s55, 0
	s_mov_b32 m0, s12
	ds_read_b128 v[192:195], v183 offset:32768
	ds_read_b128 v[204:207], v183 offset:33792
	ds_read_b128 v[208:211], v183 offset:34816
	ds_read_b128 v[212:215], v183 offset:35840
	ds_read_b128 v[216:219], v183 offset:36864
	ds_read_b128 v[220:223], v183 offset:37888
	ds_read_b128 v[224:227], v183 offset:38912
	ds_read_b128 v[228:231], v183 offset:39936
	global_load_lds_dwordx4 v144, s[54:55]
	s_mov_b32 m0, s13
	s_nop 0
	global_load_lds_dwordx4 v140, s[54:55]
	s_waitcnt vmcnt(8)
	s_waitcnt lgkmcnt(0)
	s_setprio 2
	s_barrier
	v_mfma_f32_16x16x32_f16 v[122:125], v[130:133], v[192:195], v[122:125]
	v_mfma_f32_16x16x32_f16 v[114:117], v[152:155], v[192:195], v[114:117]
	v_mfma_f32_16x16x32_f16 v[106:109], v[130:133], v[208:211], v[106:109]
	v_mfma_f32_16x16x32_f16 v[98:101], v[152:155], v[208:211], v[98:101]
	v_mfma_f32_16x16x32_f16 v[90:93], v[130:133], v[216:219], v[90:93]
	v_mfma_f32_16x16x32_f16 v[82:85], v[152:155], v[216:219], v[82:85]
	v_mfma_f32_16x16x32_f16 v[74:77], v[130:133], v[224:227], v[74:77]
	v_mfma_f32_16x16x32_f16 v[66:69], v[152:155], v[224:227], v[66:69]
	v_mfma_f32_16x16x32_f16 v[122:125], v[134:137], v[204:207], v[122:125]
	v_mfma_f32_16x16x32_f16 v[114:117], v[156:159], v[204:207], v[114:117]
	v_mfma_f32_16x16x32_f16 v[106:109], v[134:137], v[212:215], v[106:109]
	v_mfma_f32_16x16x32_f16 v[98:101], v[156:159], v[212:215], v[98:101]
	v_mfma_f32_16x16x32_f16 v[90:93], v[134:137], v[220:223], v[90:93]
	v_mfma_f32_16x16x32_f16 v[82:85], v[156:159], v[220:223], v[82:85]
	v_mfma_f32_16x16x32_f16 v[74:77], v[134:137], v[228:231], v[74:77]
	v_mfma_f32_16x16x32_f16 v[66:69], v[156:159], v[228:231], v[66:69]
	v_mfma_f32_16x16x32_f16 v[126:129], v[160:163], v[192:195], v[126:129]
	v_mfma_f32_16x16x32_f16 v[118:121], v[184:187], v[192:195], v[118:121]
	v_mfma_f32_16x16x32_f16 v[110:113], v[160:163], v[208:211], v[110:113]
	v_mfma_f32_16x16x32_f16 v[102:105], v[184:187], v[208:211], v[102:105]
	v_mfma_f32_16x16x32_f16 v[94:97], v[160:163], v[216:219], v[94:97]
	v_mfma_f32_16x16x32_f16 v[86:89], v[184:187], v[216:219], v[86:89]
	v_mfma_f32_16x16x32_f16 v[78:81], v[160:163], v[224:227], v[78:81]
	v_mfma_f32_16x16x32_f16 v[70:73], v[184:187], v[224:227], v[70:73]
	v_mfma_f32_16x16x32_f16 v[126:129], v[166:169], v[204:207], v[126:129]
	v_mfma_f32_16x16x32_f16 v[118:121], v[188:191], v[204:207], v[118:121]
	v_mfma_f32_16x16x32_f16 v[110:113], v[166:169], v[212:215], v[110:113]
	v_mfma_f32_16x16x32_f16 v[102:105], v[188:191], v[212:215], v[102:105]
	v_mfma_f32_16x16x32_f16 v[94:97], v[166:169], v[220:223], v[94:97]
	v_mfma_f32_16x16x32_f16 v[86:89], v[188:191], v[220:223], v[86:89]
	v_mfma_f32_16x16x32_f16 v[78:81], v[166:169], v[228:231], v[78:81]
	v_mfma_f32_16x16x32_f16 v[70:73], v[188:191], v[228:231], v[70:73]
	s_barrier
	s_setprio 1
	s_add_i32 s54, s83, s2
	s_add_i32 vcc_hi, s82, -2
	s_cmp_eq_u32 s74, vcc_hi
	s_cselect_b32 s99, s47, s81
	s_cselect_b32 s98, s46, s80
	s_add_u32 s98, s98, s92
	s_addc_u32 s99, s99, s93
	s_mov_b32 m0, s54
	s_nop 0
	global_load_lds_dwordx4 v142, s[98:99]
	ds_read_b128 v[192:195], v183 offset:49152
	ds_read_b128 v[204:207], v183 offset:50176
	ds_read_b128 v[208:211], v183 offset:51200
	ds_read_b128 v[212:215], v183 offset:52224
	ds_read_b128 v[216:219], v183 offset:53248
	ds_read_b128 v[220:223], v183 offset:54272
	ds_read_b128 v[224:227], v183 offset:55296
	ds_read_b128 v[228:231], v183 offset:56320
	s_add_i32 m0, s54, 0x2000
	s_nop 0
	global_load_lds_dwordx4 v138, s[98:99]
	s_add_i32 s54, s94, s2
	s_add_u32 s98, s98, s48
	s_addc_u32 s99, s99, 0
	s_mov_b32 m0, s54
	s_nop 0
	global_load_lds_dwordx4 v142, s[98:99]
	s_add_i32 m0, s54, 0x2000
	s_nop 0
	global_load_lds_dwordx4 v138, s[98:99]
	s_add_u32 s98, s52, 0x80
	s_addc_u32 s99, s53, 0
	s_cmp_eq_u32 s74, vcc_hi
	s_cselect_b32 s99, s39, s99
	s_cselect_b32 s98, s38, s98
	s_add_u32 s98, s98, s92
	s_addc_u32 s99, s99, s93
	s_mov_b32 m0, s35
	s_nop 0
	global_load_lds_dwordx4 v144, s[98:99]
	s_mov_b32 m0, s59
	s_nop 0
	global_load_lds_dwordx4 v140, s[98:99]
	s_waitcnt vmcnt(8)
	s_waitcnt lgkmcnt(0)
	s_setprio 2
	s_barrier
	v_mfma_f32_16x16x32_f16 v[58:61], v[130:133], v[192:195], v[58:61]
	v_mfma_f32_16x16x32_f16 v[50:53], v[152:155], v[192:195], v[50:53]
	v_mfma_f32_16x16x32_f16 v[42:45], v[130:133], v[208:211], v[42:45]
	v_mfma_f32_16x16x32_f16 v[34:37], v[152:155], v[208:211], v[34:37]
	v_mfma_f32_16x16x32_f16 v[26:29], v[130:133], v[216:219], v[26:29]
	v_mfma_f32_16x16x32_f16 v[18:21], v[152:155], v[216:219], v[18:21]
	v_mfma_f32_16x16x32_f16 v[10:13], v[130:133], v[224:227], v[10:13]
	v_mfma_f32_16x16x32_f16 v[6:9], v[152:155], v[224:227], v[6:9]
	v_mfma_f32_16x16x32_f16 v[58:61], v[134:137], v[204:207], v[58:61]
	v_mfma_f32_16x16x32_f16 v[50:53], v[156:159], v[204:207], v[50:53]
	v_mfma_f32_16x16x32_f16 v[42:45], v[134:137], v[212:215], v[42:45]
	v_mfma_f32_16x16x32_f16 v[34:37], v[156:159], v[212:215], v[34:37]
	v_mfma_f32_16x16x32_f16 v[26:29], v[134:137], v[220:223], v[26:29]
	v_mfma_f32_16x16x32_f16 v[18:21], v[156:159], v[220:223], v[18:21]
	v_mfma_f32_16x16x32_f16 v[10:13], v[134:137], v[228:231], v[10:13]
	v_mfma_f32_16x16x32_f16 v[6:9], v[156:159], v[228:231], v[6:9]
	v_mfma_f32_16x16x32_f16 v[62:65], v[160:163], v[192:195], v[62:65]
	v_mfma_f32_16x16x32_f16 v[54:57], v[184:187], v[192:195], v[54:57]
	v_mfma_f32_16x16x32_f16 v[46:49], v[160:163], v[208:211], v[46:49]
	v_mfma_f32_16x16x32_f16 v[38:41], v[184:187], v[208:211], v[38:41]
	v_mfma_f32_16x16x32_f16 v[30:33], v[160:163], v[216:219], v[30:33]
	v_mfma_f32_16x16x32_f16 v[22:25], v[184:187], v[216:219], v[22:25]
	v_mfma_f32_16x16x32_f16 v[14:17], v[160:163], v[224:227], v[14:17]
	v_mfma_f32_16x16x32_f16 v[2:5], v[184:187], v[224:227], v[2:5]
	v_mfma_f32_16x16x32_f16 v[62:65], v[166:169], v[204:207], v[62:65]
	v_mfma_f32_16x16x32_f16 v[54:57], v[188:191], v[204:207], v[54:57]
	v_mfma_f32_16x16x32_f16 v[46:49], v[166:169], v[212:215], v[46:49]
	v_mfma_f32_16x16x32_f16 v[38:41], v[188:191], v[212:215], v[38:41]
	v_mfma_f32_16x16x32_f16 v[30:33], v[166:169], v[220:223], v[30:33]
	v_mfma_f32_16x16x32_f16 v[22:25], v[188:191], v[220:223], v[22:25]
	v_mfma_f32_16x16x32_f16 v[14:17], v[166:169], v[228:231], v[14:17]
	v_mfma_f32_16x16x32_f16 v[2:5], v[188:191], v[228:231], v[2:5]
	s_barrier
	s_setprio 1
	s_add_u32 s52, s52, 0x100
	s_addc_u32 s53, s53, 0
	s_add_u32 s80, s80, 0x100
	s_addc_u32 s81, s81, 0
	s_cmp_ge_u32 s82, s65
	s_mov_b32 s54, s82
	s_cbranch_scc1 .LBB0_311
; #define PG8_STAGE(bufoff, gbase, voff) do { _Pragma("unroll") for (int _i = 0; _i < 2; ++_i) \
;         __builtin_amdgcn_global_load_lds((const unsigned*)((const char*)(gbase) + (voff)[_i]), (PG8_LAS unsigned*)(lds + (bufoff) + ldsw + _i * 8192), 16, 0, 0); } while (0)
; #define PG8_LDA(dst, b, h) do { _Pragma("unroll") for (int m = 0; m < 4; ++m) _Pragma("unroll") for (int k = 0; k < 2; ++k) dst[m][k] = *(const PG8_LAS bf16x8*)(lds + PG8_SA(b, h) + aoff + m * 2048 + k * 1024); } while (0)
; #define PG8_LDB(dst, b, h) do { _Pragma("unroll") for (int n = 0; n < 2; ++n) _Pragma("unroll") for (int k = 0; k < 2; ++k) dst[n][k] = *(const PG8_LAS bf16x8*)(lds + PG8_SB(b, h) + boff + n * 2048 + k * 1024); } while (0)
; #define PG8_WAIT_V(n) asm volatile("s_waitcnt vmcnt(" #n ")" ::: "memory")
; #define PG8_WAIT_L(n) asm volatile("s_waitcnt lgkmcnt(" #n ")" ::: "memory")
; #define PG8_BAR __builtin_amdgcn_s_barrier()
; #define PG8_SCHED __builtin_amdgcn_sched_barrier(0)
; template <class Epi, class Sched, bool ALIGN_EPI = false, bool SP2 = false, bool F16 = false>
; __device__ __forceinline__ void gemm_phase(PG8_LAS unsigned char* lds, const Gemm g, const Sched& S, const Epi& E) {
;     ...
;             if constexpr (SP2) {
;             PG8_LDB(B0, 0, 0); PG8_LDB(B1, 0, 1); PG8_SCHED; PG8_LDA(At, 0, 0); PG8_STAGE(PG8_SA(1, 1), a1 + hstepA, voffA);
;             PG8_WAIT_V(8); PG8_WAIT_L(0); PG8_BAR; PG8_MMA(0, 0, At, B0); PG8_MMA(0, 1, At, B1); PG8_BAR; PG8_SCHED;
;             PG8_LDA(At, 0, 1); PG8_STAGE(PG8_SB(0, 0), b2, voffB); PG8_STAGE(PG8_SB(0, 1), b2 + hstepB, voffB); PG8_STAGE(PG8_SA(0, 0), a2, voffA);
;             PG8_WAIT_V(8); PG8_WAIT_L(0); PG8_BAR; PG8_MMA(1, 0, At, B0); PG8_MMA(1, 1, At, B1); PG8_BAR; PG8_SCHED;
.LBB0_310:
	s_add_i32 s82, s54, 2
	s_add_u32 s83, s52, 0x80
	s_addc_u32 s55, s53, 0
	s_add_i32 vcc_lo, 0, 0x10000
	s_cmp_eq_u32 s74, s54
	s_cselect_b32 s55, s39, s55
	s_cselect_b32 s54, s38, s83
	s_cselect_b32 s95, s47, s81
	s_cselect_b32 s94, s46, s80
	s_add_i32 s83, 0, 0x14000
	ds_read_b128 v[130:133], v139
	ds_read_b128 v[134:137], v139 offset:1024
	ds_read_b128 v[152:155], v139 offset:2048
	ds_read_b128 v[156:159], v139 offset:3072
	ds_read_b128 v[160:163], v141
	ds_read_b128 v[166:169], v141 offset:1024
	ds_read_b128 v[184:187], v141 offset:2048
	ds_read_b128 v[188:191], v141 offset:3072
	s_add_i32 m0, s22, 0xc000
	ds_read_b128 v[192:195], v183
	ds_read_b128 v[204:207], v183 offset:1024
	ds_read_b128 v[208:211], v183 offset:2048
	ds_read_b128 v[212:215], v183 offset:3072
	ds_read_b128 v[216:219], v183 offset:4096
	ds_read_b128 v[220:223], v183 offset:5120
	ds_read_b128 v[224:227], v183 offset:6144
	ds_read_b128 v[228:231], v183 offset:7168
	global_load_lds_dwordx4 v148, s[52:53]
	s_add_i32 m0, s22, 0xe000
	s_nop 0
	global_load_lds_dwordx4 v150, s[52:53]
	s_waitcnt vmcnt(8)
	s_waitcnt lgkmcnt(0)
	s_setprio 2
	s_barrier
	v_mfma_f32_16x16x32_f16 v[122:125], v[130:133], v[192:195], v[122:125]
	v_mfma_f32_16x16x32_f16 v[114:117], v[152:155], v[192:195], v[114:117]
	v_mfma_f32_16x16x32_f16 v[106:109], v[130:133], v[208:211], v[106:109]
	v_mfma_f32_16x16x32_f16 v[98:101], v[152:155], v[208:211], v[98:101]
	v_mfma_f32_16x16x32_f16 v[90:93], v[130:133], v[216:219], v[90:93]
	v_mfma_f32_16x16x32_f16 v[82:85], v[152:155], v[216:219], v[82:85]
	v_mfma_f32_16x16x32_f16 v[74:77], v[130:133], v[224:227], v[74:77]
	v_mfma_f32_16x16x32_f16 v[66:69], v[152:155], v[224:227], v[66:69]
	v_mfma_f32_16x16x32_f16 v[122:125], v[134:137], v[204:207], v[122:125]
	v_mfma_f32_16x16x32_f16 v[114:117], v[156:159], v[204:207], v[114:117]
	v_mfma_f32_16x16x32_f16 v[106:109], v[134:137], v[212:215], v[106:109]
	v_mfma_f32_16x16x32_f16 v[98:101], v[156:159], v[212:215], v[98:101]
	v_mfma_f32_16x16x32_f16 v[90:93], v[134:137], v[220:223], v[90:93]
	v_mfma_f32_16x16x32_f16 v[82:85], v[156:159], v[220:223], v[82:85]
	v_mfma_f32_16x16x32_f16 v[74:77], v[134:137], v[228:231], v[74:77]
	v_mfma_f32_16x16x32_f16 v[66:69], v[156:159], v[228:231], v[66:69]
	v_mfma_f32_16x16x32_f16 v[126:129], v[160:163], v[192:195], v[126:129]
	v_mfma_f32_16x16x32_f16 v[118:121], v[184:187], v[192:195], v[118:121]
	v_mfma_f32_16x16x32_f16 v[110:113], v[160:163], v[208:211], v[110:113]
	v_mfma_f32_16x16x32_f16 v[102:105], v[184:187], v[208:211], v[102:105]
	v_mfma_f32_16x16x32_f16 v[94:97], v[160:163], v[216:219], v[94:97]
	v_mfma_f32_16x16x32_f16 v[86:89], v[184:187], v[216:219], v[86:89]
	v_mfma_f32_16x16x32_f16 v[78:81], v[160:163], v[224:227], v[78:81]
	v_mfma_f32_16x16x32_f16 v[70:73], v[184:187], v[224:227], v[70:73]
	v_mfma_f32_16x16x32_f16 v[126:129], v[166:169], v[204:207], v[126:129]
	v_mfma_f32_16x16x32_f16 v[118:121], v[188:191], v[204:207], v[118:121]
	v_mfma_f32_16x16x32_f16 v[110:113], v[166:169], v[212:215], v[110:113]
	v_mfma_f32_16x16x32_f16 v[102:105], v[188:191], v[212:215], v[102:105]
	v_mfma_f32_16x16x32_f16 v[94:97], v[166:169], v[220:223], v[94:97]
	v_mfma_f32_16x16x32_f16 v[86:89], v[188:191], v[220:223], v[86:89]
	v_mfma_f32_16x16x32_f16 v[78:81], v[166:169], v[228:231], v[78:81]
	v_mfma_f32_16x16x32_f16 v[70:73], v[188:191], v[228:231], v[70:73]
	s_barrier
	s_setprio 1
	s_add_i32 vcc_lo, vcc_lo, s2
	s_mov_b32 m0, vcc_lo
	s_nop 0
	global_load_lds_dwordx4 v142, s[94:95]
	ds_read_b128 v[192:195], v183 offset:16384
	ds_read_b128 v[204:207], v183 offset:17408
	ds_read_b128 v[208:211], v183 offset:18432
	ds_read_b128 v[212:215], v183 offset:19456
	ds_read_b128 v[216:219], v183 offset:20480
	ds_read_b128 v[220:223], v183 offset:21504
	ds_read_b128 v[224:227], v183 offset:22528
	ds_read_b128 v[228:231], v183 offset:23552
	s_add_i32 m0, vcc_lo, 0x2000
	s_nop 0
	global_load_lds_dwordx4 v138, s[94:95]
	s_add_i32 s83, s83, s2
	s_add_u32 s94, s94, s48
	s_addc_u32 s95, s95, 0
	s_mov_b32 m0, s83
	s_nop 0
	global_load_lds_dwordx4 v142, s[94:95]
	s_add_i32 m0, s83, 0x2000
	s_nop 0
	global_load_lds_dwordx4 v138, s[94:95]
	s_mov_b32 m0, s22
	s_nop 0
	global_load_lds_dwordx4 v144, s[54:55]
	s_mov_b32 m0, s33
	s_nop 0
	global_load_lds_dwordx4 v140, s[54:55]
	s_waitcnt vmcnt(8)
	s_waitcnt lgkmcnt(0)
	s_setprio 2
	s_barrier
	v_mfma_f32_16x16x32_f16 v[58:61], v[130:133], v[192:195], v[58:61]
	v_mfma_f32_16x16x32_f16 v[50:53], v[152:155], v[192:195], v[50:53]
	v_mfma_f32_16x16x32_f16 v[42:45], v[130:133], v[208:211], v[42:45]
	v_mfma_f32_16x16x32_f16 v[34:37], v[152:155], v[208:211], v[34:37]
	v_mfma_f32_16x16x32_f16 v[26:29], v[130:133], v[216:219], v[26:29]
	v_mfma_f32_16x16x32_f16 v[18:21], v[152:155], v[216:219], v[18:21]
	v_mfma_f32_16x16x32_f16 v[10:13], v[130:133], v[224:227], v[10:13]
	v_mfma_f32_16x16x32_f16 v[6:9], v[152:155], v[224:227], v[6:9]
	v_mfma_f32_16x16x32_f16 v[58:61], v[134:137], v[204:207], v[58:61]
	v_mfma_f32_16x16x32_f16 v[50:53], v[156:159], v[204:207], v[50:53]
	v_mfma_f32_16x16x32_f16 v[42:45], v[134:137], v[212:215], v[42:45]
	v_mfma_f32_16x16x32_f16 v[34:37], v[156:159], v[212:215], v[34:37]
	v_mfma_f32_16x16x32_f16 v[26:29], v[134:137], v[220:223], v[26:29]
	v_mfma_f32_16x16x32_f16 v[18:21], v[156:159], v[220:223], v[18:21]
	v_mfma_f32_16x16x32_f16 v[10:13], v[134:137], v[228:231], v[10:13]
	v_mfma_f32_16x16x32_f16 v[6:9], v[156:159], v[228:231], v[6:9]
	v_mfma_f32_16x16x32_f16 v[62:65], v[160:163], v[192:195], v[62:65]
	v_mfma_f32_16x16x32_f16 v[54:57], v[184:187], v[192:195], v[54:57]
	v_mfma_f32_16x16x32_f16 v[46:49], v[160:163], v[208:211], v[46:49]
	v_mfma_f32_16x16x32_f16 v[38:41], v[184:187], v[208:211], v[38:41]
	v_mfma_f32_16x16x32_f16 v[30:33], v[160:163], v[216:219], v[30:33]
	v_mfma_f32_16x16x32_f16 v[22:25], v[184:187], v[216:219], v[22:25]
	v_mfma_f32_16x16x32_f16 v[14:17], v[160:163], v[224:227], v[14:17]
	v_mfma_f32_16x16x32_f16 v[2:5], v[184:187], v[224:227], v[2:5]
	v_mfma_f32_16x16x32_f16 v[62:65], v[166:169], v[204:207], v[62:65]
	v_mfma_f32_16x16x32_f16 v[54:57], v[188:191], v[204:207], v[54:57]
	v_mfma_f32_16x16x32_f16 v[46:49], v[166:169], v[212:215], v[46:49]
	v_mfma_f32_16x16x32_f16 v[38:41], v[188:191], v[212:215], v[38:41]
	v_mfma_f32_16x16x32_f16 v[30:33], v[166:169], v[220:223], v[30:33]
	v_mfma_f32_16x16x32_f16 v[22:25], v[188:191], v[220:223], v[22:25]
	v_mfma_f32_16x16x32_f16 v[14:17], v[166:169], v[228:231], v[14:17]
	v_mfma_f32_16x16x32_f16 v[2:5], v[188:191], v[228:231], v[2:5]
	s_barrier
; #define PG8_STAGE(bufoff, gbase, voff) do { _Pragma("unroll") for (int _i = 0; _i < 2; ++_i) \
;         __builtin_amdgcn_global_load_lds((const unsigned*)((const char*)(gbase) + (voff)[_i]), (PG8_LAS unsigned*)(lds + (bufoff) + ldsw + _i * 8192), 16, 0, 0); } while (0)
; #define PG8_LDA(dst, b, h) do { _Pragma("unroll") for (int m = 0; m < 4; ++m) _Pragma("unroll") for (int k = 0; k < 2; ++k) dst[m][k] = *(const PG8_LAS bf16x8*)(lds + PG8_SA(b, h) + aoff + m * 2048 + k * 1024); } while (0)
; #define PG8_LDB(dst, b, h) do { _Pragma("unroll") for (int n = 0; n < 2; ++n) _Pragma("unroll") for (int k = 0; k < 2; ++k) dst[n][k] = *(const PG8_LAS bf16x8*)(lds + PG8_SB(b, h) + boff + n * 2048 + k * 1024); } while (0)
; #define PG8_WAIT_V(n) asm volatile("s_waitcnt vmcnt(" #n ")" ::: "memory")
; #define PG8_WAIT_L(n) asm volatile("s_waitcnt lgkmcnt(" #n ")" ::: "memory")
; #define PG8_BAR __builtin_amdgcn_s_barrier()
; #define PG8_SCHED __builtin_amdgcn_sched_barrier(0)
; template <class Epi, class Sched, bool ALIGN_EPI = false, bool SP2 = false, bool F16 = false>
; __device__ __forceinline__ void gemm_phase(PG8_LAS unsigned char* lds, const Gemm g, const Sched& S, const Epi& E) {
;     ...
;             PG8_LDB(B0, 1, 0); PG8_LDB(B1, 1, 1); PG8_SCHED; PG8_LDA(At, 1, 0); PG8_STAGE(PG8_SA(0, 1), a2 + hstepA, voffA);
;             PG8_WAIT_V(8); PG8_WAIT_L(0); PG8_BAR; PG8_MMA(0, 0, At, B0); PG8_MMA(0, 1, At, B1); PG8_BAR; PG8_SCHED;
;             PG8_LDA(At, 1, 1); PG8_STAGE(PG8_SB(1, 0), b3, voffB); PG8_STAGE(PG8_SB(1, 1), b3 + hstepB, voffB); PG8_STAGE(PG8_SA(1, 0), a3, voffA);
;             PG8_WAIT_V(8); PG8_WAIT_L(0); PG8_BAR; PG8_MMA(1, 0, At, B0); PG8_MMA(1, 1, At, B1); PG8_BAR; PG8_SCHED;
;     ...
;         if constexpr (ALIGN_EPI) { if (wr == 0) PG8_BAR; }
	s_setprio 1
	s_add_i32 s83, 0, 0x18000
	s_add_i32 s94, 0, 0x1c000
	ds_read_b128 v[130:133], v143
	ds_read_b128 v[134:137], v143 offset:1024
	ds_read_b128 v[152:155], v143 offset:2048
	ds_read_b128 v[156:159], v143 offset:3072
	ds_read_b128 v[160:163], v145
	ds_read_b128 v[166:169], v145 offset:1024
	ds_read_b128 v[184:187], v145 offset:2048
	ds_read_b128 v[188:191], v145 offset:3072
	s_add_u32 s54, s54, s8
	s_addc_u32 s55, s55, 0
	s_mov_b32 m0, s12
	ds_read_b128 v[192:195], v183 offset:32768
	ds_read_b128 v[204:207], v183 offset:33792
	ds_read_b128 v[208:211], v183 offset:34816
	ds_read_b128 v[212:215], v183 offset:35840
	ds_read_b128 v[216:219], v183 offset:36864
	ds_read_b128 v[220:223], v183 offset:37888
	ds_read_b128 v[224:227], v183 offset:38912
	ds_read_b128 v[228:231], v183 offset:39936
	global_load_lds_dwordx4 v144, s[54:55]
	s_mov_b32 m0, s13
	s_nop 0
	global_load_lds_dwordx4 v140, s[54:55]
	s_waitcnt vmcnt(8)
	s_waitcnt lgkmcnt(0)
	s_setprio 2
	s_barrier
	v_mfma_f32_16x16x32_f16 v[122:125], v[130:133], v[192:195], v[122:125]
	v_mfma_f32_16x16x32_f16 v[114:117], v[152:155], v[192:195], v[114:117]
	v_mfma_f32_16x16x32_f16 v[106:109], v[130:133], v[208:211], v[106:109]
	v_mfma_f32_16x16x32_f16 v[98:101], v[152:155], v[208:211], v[98:101]
	v_mfma_f32_16x16x32_f16 v[90:93], v[130:133], v[216:219], v[90:93]
	v_mfma_f32_16x16x32_f16 v[82:85], v[152:155], v[216:219], v[82:85]
	v_mfma_f32_16x16x32_f16 v[74:77], v[130:133], v[224:227], v[74:77]
	v_mfma_f32_16x16x32_f16 v[66:69], v[152:155], v[224:227], v[66:69]
	v_mfma_f32_16x16x32_f16 v[122:125], v[134:137], v[204:207], v[122:125]
	v_mfma_f32_16x16x32_f16 v[114:117], v[156:159], v[204:207], v[114:117]
	v_mfma_f32_16x16x32_f16 v[106:109], v[134:137], v[212:215], v[106:109]
	v_mfma_f32_16x16x32_f16 v[98:101], v[156:159], v[212:215], v[98:101]
	v_mfma_f32_16x16x32_f16 v[90:93], v[134:137], v[220:223], v[90:93]
	v_mfma_f32_16x16x32_f16 v[82:85], v[156:159], v[220:223], v[82:85]
	v_mfma_f32_16x16x32_f16 v[74:77], v[134:137], v[228:231], v[74:77]
	v_mfma_f32_16x16x32_f16 v[66:69], v[156:159], v[228:231], v[66:69]
	v_mfma_f32_16x16x32_f16 v[126:129], v[160:163], v[192:195], v[126:129]
	v_mfma_f32_16x16x32_f16 v[118:121], v[184:187], v[192:195], v[118:121]
	v_mfma_f32_16x16x32_f16 v[110:113], v[160:163], v[208:211], v[110:113]
	v_mfma_f32_16x16x32_f16 v[102:105], v[184:187], v[208:211], v[102:105]
	v_mfma_f32_16x16x32_f16 v[94:97], v[160:163], v[216:219], v[94:97]
	v_mfma_f32_16x16x32_f16 v[86:89], v[184:187], v[216:219], v[86:89]
	v_mfma_f32_16x16x32_f16 v[78:81], v[160:163], v[224:227], v[78:81]
	v_mfma_f32_16x16x32_f16 v[70:73], v[184:187], v[224:227], v[70:73]
	v_mfma_f32_16x16x32_f16 v[126:129], v[166:169], v[204:207], v[126:129]
	v_mfma_f32_16x16x32_f16 v[118:121], v[188:191], v[204:207], v[118:121]
	v_mfma_f32_16x16x32_f16 v[110:113], v[166:169], v[212:215], v[110:113]
	v_mfma_f32_16x16x32_f16 v[102:105], v[188:191], v[212:215], v[102:105]
	v_mfma_f32_16x16x32_f16 v[94:97], v[166:169], v[220:223], v[94:97]
	v_mfma_f32_16x16x32_f16 v[86:89], v[188:191], v[220:223], v[86:89]
	v_mfma_f32_16x16x32_f16 v[78:81], v[166:169], v[228:231], v[78:81]
	v_mfma_f32_16x16x32_f16 v[70:73], v[188:191], v[228:231], v[70:73]
	s_barrier
	s_setprio 1
	s_add_i32 s54, s83, s2
	s_add_i32 vcc_hi, s82, -2
	s_cmp_eq_u32 s74, vcc_hi
	s_cselect_b32 s99, s47, s81
	s_cselect_b32 s98, s46, s80
	s_add_u32 s98, s98, s92
	s_addc_u32 s99, s99, s93
	s_mov_b32 m0, s54
	s_nop 0
	global_load_lds_dwordx4 v142, s[98:99]
	ds_read_b128 v[192:195], v183 offset:49152
	ds_read_b128 v[204:207], v183 offset:50176
	ds_read_b128 v[208:211], v183 offset:51200
	ds_read_b128 v[212:215], v183 offset:52224
	ds_read_b128 v[216:219], v183 offset:53248
	ds_read_b128 v[220:223], v183 offset:54272
	ds_read_b128 v[224:227], v183 offset:55296
	ds_read_b128 v[228:231], v183 offset:56320
	s_add_i32 m0, s54, 0x2000
	s_nop 0
	global_load_lds_dwordx4 v138, s[98:99]
	s_add_i32 s54, s94, s2
	s_add_u32 s98, s98, s48
	s_addc_u32 s99, s99, 0
	s_mov_b32 m0, s54
	s_nop 0
	global_load_lds_dwordx4 v142, s[98:99]
	s_add_i32 m0, s54, 0x2000
	s_nop 0
	global_load_lds_dwordx4 v138, s[98:99]
	s_add_u32 s98, s52, 0x80
	s_addc_u32 s99, s53, 0
	s_cmp_eq_u32 s74, vcc_hi
	s_cselect_b32 s99, s39, s99
	s_cselect_b32 s98, s38, s98
	s_add_u32 s98, s98, s92
	s_addc_u32 s99, s99, s93
	s_mov_b32 m0, s35
	s_nop 0
	global_load_lds_dwordx4 v144, s[98:99]
	s_mov_b32 m0, s59
	s_nop 0
	global_load_lds_dwordx4 v140, s[98:99]
	s_waitcnt vmcnt(8)
	s_waitcnt lgkmcnt(0)
	s_setprio 2
	s_barrier
	v_mfma_f32_16x16x32_f16 v[58:61], v[130:133], v[192:195], v[58:61]
	v_mfma_f32_16x16x32_f16 v[50:53], v[152:155], v[192:195], v[50:53]
	v_mfma_f32_16x16x32_f16 v[42:45], v[130:133], v[208:211], v[42:45]
	v_mfma_f32_16x16x32_f16 v[34:37], v[152:155], v[208:211], v[34:37]
	v_mfma_f32_16x16x32_f16 v[26:29], v[130:133], v[216:219], v[26:29]
	v_mfma_f32_16x16x32_f16 v[18:21], v[152:155], v[216:219], v[18:21]
	v_mfma_f32_16x16x32_f16 v[10:13], v[130:133], v[224:227], v[10:13]
	v_mfma_f32_16x16x32_f16 v[6:9], v[152:155], v[224:227], v[6:9]
	v_mfma_f32_16x16x32_f16 v[58:61], v[134:137], v[204:207], v[58:61]
	v_mfma_f32_16x16x32_f16 v[50:53], v[156:159], v[204:207], v[50:53]
	v_mfma_f32_16x16x32_f16 v[42:45], v[134:137], v[212:215], v[42:45]
	v_mfma_f32_16x16x32_f16 v[34:37], v[156:159], v[212:215], v[34:37]
	v_mfma_f32_16x16x32_f16 v[26:29], v[134:137], v[220:223], v[26:29]
	v_mfma_f32_16x16x32_f16 v[18:21], v[156:159], v[220:223], v[18:21]
	v_mfma_f32_16x16x32_f16 v[10:13], v[134:137], v[228:231], v[10:13]
	v_mfma_f32_16x16x32_f16 v[6:9], v[156:159], v[228:231], v[6:9]
	v_mfma_f32_16x16x32_f16 v[62:65], v[160:163], v[192:195], v[62:65]
	v_mfma_f32_16x16x32_f16 v[54:57], v[184:187], v[192:195], v[54:57]
	v_mfma_f32_16x16x32_f16 v[46:49], v[160:163], v[208:211], v[46:49]
	v_mfma_f32_16x16x32_f16 v[38:41], v[184:187], v[208:211], v[38:41]
	v_mfma_f32_16x16x32_f16 v[30:33], v[160:163], v[216:219], v[30:33]
	v_mfma_f32_16x16x32_f16 v[22:25], v[184:187], v[216:219], v[22:25]
	v_mfma_f32_16x16x32_f16 v[14:17], v[160:163], v[224:227], v[14:17]
	v_mfma_f32_16x16x32_f16 v[2:5], v[184:187], v[224:227], v[2:5]
	v_mfma_f32_16x16x32_f16 v[62:65], v[166:169], v[204:207], v[62:65]
	v_mfma_f32_16x16x32_f16 v[54:57], v[188:191], v[204:207], v[54:57]
	v_mfma_f32_16x16x32_f16 v[46:49], v[166:169], v[212:215], v[46:49]
	v_mfma_f32_16x16x32_f16 v[38:41], v[188:191], v[212:215], v[38:41]
	v_mfma_f32_16x16x32_f16 v[30:33], v[166:169], v[220:223], v[30:33]
	v_mfma_f32_16x16x32_f16 v[22:25], v[188:191], v[220:223], v[22:25]
	v_mfma_f32_16x16x32_f16 v[14:17], v[166:169], v[228:231], v[14:17]
	v_mfma_f32_16x16x32_f16 v[2:5], v[188:191], v[228:231], v[2:5]
	s_barrier
	s_setprio 1
	s_add_u32 s52, s52, 0x100
	s_addc_u32 s53, s53, 0
	s_add_u32 s80, s80, 0x100
	s_addc_u32 s81, s81, 0
	s_cmp_ge_u32 s82, s65
	s_mov_b32 s54, s82
	s_cbranch_scc0 .LBB0_310
.LBB0_311:
	s_setprio 0
	s_and_b64 vcc, exec, s[40:41]
	s_cbranch_vccz .LBB0_313
	s_barrier

; #define PG8_STAGE(bufoff, gbase, voff) do { _Pragma("unroll") for (int _i = 0; _i < 2; ++_i) \
;         __builtin_amdgcn_global_load_lds((const unsigned*)((const char*)(gbase) + (voff)[_i]), (PG8_LAS unsigned*)(lds + (bufoff) + ldsw + _i * 8192), 16, 0, 0); } while (0)
; #define PG8_LDA(dst, b, h) do { _Pragma("unroll") for (int m = 0; m < 4; ++m) _Pragma("unroll") for (int k = 0; k < 2; ++k) dst[m][k] = *(const PG8_LAS bf16x8*)(lds + PG8_SA(b, h) + aoff + m * 2048 + k * 1024); } while (0)
; #define PG8_LDB(dst, b, h) do { _Pragma("unroll") for (int n = 0; n < 2; ++n) _Pragma("unroll") for (int k = 0; k < 2; ++k) dst[n][k] = *(const PG8_LAS bf16x8*)(lds + PG8_SB(b, h) + boff + n * 2048 + k * 1024); } while (0)
; #define PG8_WAIT_V(n) asm volatile("s_waitcnt vmcnt(" #n ")" ::: "memory")
; #define PG8_WAIT_L(n) asm volatile("s_waitcnt lgkmcnt(" #n ")" ::: "memory")
; #define PG8_BAR __builtin_amdgcn_s_barrier()
; #define PG8_SCHED __builtin_amdgcn_sched_barrier(0)
; template <class Epi, class Sched, bool ALIGN_EPI = false, bool SP2 = false, bool F16 = false>
; __device__ __forceinline__ void gemm_phase(PG8_LAS unsigned char* lds, const Gemm g, const Sched& S, const Epi& E) {
;     ...
;         for (int t = 0; t < nt; t += 2) {
;             const bool last = (t == nt - 2);
;             const char* a1 = cA + (size_t)(t + 1) * kstep;
;             const char* a2 = last ? nA : cA + (size_t)(t + 2) * kstep; const char* b2 = last ? nB : cB + (size_t)(t + 2) * kstep;
;             const char* a3 = a2 + kstep; const char* b3 = b2 + kstep;
;             if (last && has_next) S.a_ready(nxt);
;             if constexpr (SP2) {
;             PG8_LDB(B0, 0, 0); PG8_LDB(B1, 0, 1); PG8_SCHED; PG8_LDA(At, 0, 0); PG8_STAGE(PG8_SA(1, 1), a1 + hstepA, voffA);
;             PG8_WAIT_V(8); PG8_WAIT_L(0); PG8_BAR; PG8_MMA(0, 0, At, B0); PG8_MMA(0, 1, At, B1); PG8_BAR; PG8_SCHED;
;             PG8_LDA(At, 0, 1); PG8_STAGE(PG8_SB(0, 0), b2, voffB); PG8_STAGE(PG8_SB(0, 1), b2 + hstepB, voffB); PG8_STAGE(PG8_SA(0, 0), a2, voffA);
;             PG8_WAIT_V(8); PG8_WAIT_L(0); PG8_BAR; PG8_MMA(1, 0, At, B0); PG8_MMA(1, 1, At, B1); PG8_BAR; PG8_SCHED;
.Lpk_rs:
	s_setprio 1
	s_add_i32 s81, s54, 2
	s_add_u32 s82, s52, 0x80
	s_addc_u32 s55, s53, 0
	s_add_i32 s94, 0, 0x10000
	s_cmp_eq_u32 s74, s54
	s_cselect_b32 s55, s41, s55
	s_cselect_b32 s54, s40, s82
	s_cselect_b32 s83, s47, s80
	s_cselect_b32 s82, s46, s79
	s_add_i32 s95, 0, 0x14000
	ds_read_b128 v[130:133], v139
	ds_read_b128 v[134:137], v139 offset:1024
	ds_read_b128 v[148:151], v139 offset:2048
	ds_read_b128 v[152:155], v139 offset:3072
	ds_read_b128 v[162:165], v141
	ds_read_b128 v[166:169], v141 offset:1024
	ds_read_b128 v[170:173], v141 offset:2048
	ds_read_b128 v[182:185], v141 offset:3072
	s_add_i32 m0, s3, 0xc000
	ds_read_b128 v[186:189], v160
	ds_read_b128 v[190:193], v160 offset:1024
	ds_read_b128 v[194:197], v160 offset:2048
	ds_read_b128 v[204:207], v160 offset:3072
	ds_read_b128 v[208:211], v160 offset:4096
	ds_read_b128 v[212:215], v160 offset:5120
	ds_read_b128 v[216:219], v160 offset:6144
	ds_read_b128 v[220:223], v160 offset:7168
	global_load_lds_dwordx4 v144, s[52:53]
	s_add_i32 m0, s3, 0xe000
	s_nop 0
	global_load_lds_dwordx4 v146, s[52:53]
	s_waitcnt vmcnt(8)
	s_waitcnt lgkmcnt(0)
	s_setprio 2
	s_barrier
	v_mfma_f32_16x16x32_bf16 v[122:125], v[130:133], v[186:189], 0
	v_mfma_f32_16x16x32_bf16 v[126:129], v[148:151], v[186:189], 0
	v_mfma_f32_16x16x32_bf16 v[110:113], v[130:133], v[194:197], 0
	v_mfma_f32_16x16x32_bf16 v[106:109], v[148:151], v[194:197], 0
	v_mfma_f32_16x16x32_bf16 v[94:97], v[130:133], v[208:211], 0
	v_mfma_f32_16x16x32_bf16 v[90:93], v[148:151], v[208:211], 0
	v_mfma_f32_16x16x32_bf16 v[78:81], v[130:133], v[216:219], 0
	v_mfma_f32_16x16x32_bf16 v[74:77], v[148:151], v[216:219], 0
	v_mfma_f32_16x16x32_bf16 v[122:125], v[134:137], v[190:193], v[122:125]
	v_mfma_f32_16x16x32_bf16 v[126:129], v[152:155], v[190:193], v[126:129]
	v_mfma_f32_16x16x32_bf16 v[110:113], v[134:137], v[204:207], v[110:113]
	v_mfma_f32_16x16x32_bf16 v[106:109], v[152:155], v[204:207], v[106:109]
	v_mfma_f32_16x16x32_bf16 v[94:97], v[134:137], v[212:215], v[94:97]
	v_mfma_f32_16x16x32_bf16 v[90:93], v[152:155], v[212:215], v[90:93]
	v_mfma_f32_16x16x32_bf16 v[78:81], v[134:137], v[220:223], v[78:81]
	v_mfma_f32_16x16x32_bf16 v[74:77], v[152:155], v[220:223], v[74:77]
	v_mfma_f32_16x16x32_bf16 v[118:121], v[162:165], v[186:189], 0
	v_mfma_f32_16x16x32_bf16 v[114:117], v[170:173], v[186:189], 0
	v_mfma_f32_16x16x32_bf16 v[102:105], v[162:165], v[194:197], 0
	v_mfma_f32_16x16x32_bf16 v[98:101], v[170:173], v[194:197], 0
	v_mfma_f32_16x16x32_bf16 v[86:89], v[162:165], v[208:211], 0
	v_mfma_f32_16x16x32_bf16 v[82:85], v[170:173], v[208:211], 0
	v_mfma_f32_16x16x32_bf16 v[70:73], v[162:165], v[216:219], 0
	v_mfma_f32_16x16x32_bf16 v[66:69], v[170:173], v[216:219], 0
	v_mfma_f32_16x16x32_bf16 v[118:121], v[166:169], v[190:193], v[118:121]
	v_mfma_f32_16x16x32_bf16 v[114:117], v[182:185], v[190:193], v[114:117]
	v_mfma_f32_16x16x32_bf16 v[102:105], v[166:169], v[204:207], v[102:105]
	v_mfma_f32_16x16x32_bf16 v[98:101], v[182:185], v[204:207], v[98:101]
	v_mfma_f32_16x16x32_bf16 v[86:89], v[166:169], v[212:215], v[86:89]
	v_mfma_f32_16x16x32_bf16 v[82:85], v[182:185], v[212:215], v[82:85]
	v_mfma_f32_16x16x32_bf16 v[70:73], v[166:169], v[220:223], v[70:73]
	v_mfma_f32_16x16x32_bf16 v[66:69], v[182:185], v[220:223], v[66:69]
	s_barrier
	s_setprio 1
	s_add_i32 s94, s94, s2
	s_mov_b32 m0, s94
	s_nop 0
	global_load_lds_dwordx4 v174, s[82:83]
	ds_read_b128 v[186:189], v160 offset:16384
	ds_read_b128 v[190:193], v160 offset:17408
	ds_read_b128 v[194:197], v160 offset:18432
	ds_read_b128 v[204:207], v160 offset:19456
	ds_read_b128 v[208:211], v160 offset:20480
	ds_read_b128 v[212:215], v160 offset:21504
	ds_read_b128 v[216:219], v160 offset:22528
	ds_read_b128 v[220:223], v160 offset:23552
	s_add_i32 m0, s94, 0x2000
	s_nop 0
	global_load_lds_dwordx4 v142, s[82:83]
	s_add_i32 s94, s95, s2
	s_add_u32 s82, s82, s48
	s_addc_u32 s83, s83, 0
	s_mov_b32 m0, s94
	s_nop 0
	global_load_lds_dwordx4 v174, s[82:83]
	s_add_i32 m0, s94, 0x2000
	s_nop 0
	global_load_lds_dwordx4 v142, s[82:83]
	s_mov_b32 m0, s3
	s_nop 0
	global_load_lds_dwordx4 v138, s[54:55]
	s_mov_b32 m0, s12
	s_nop 0
	global_load_lds_dwordx4 v140, s[54:55]
	s_waitcnt vmcnt(8)
	s_waitcnt lgkmcnt(0)
	s_setprio 2
	s_barrier
	v_mfma_f32_16x16x32_bf16 v[62:65], v[130:133], v[186:189], 0
	v_mfma_f32_16x16x32_bf16 v[58:61], v[148:151], v[186:189], 0
	v_mfma_f32_16x16x32_bf16 v[46:49], v[130:133], v[194:197], 0
	v_mfma_f32_16x16x32_bf16 v[42:45], v[148:151], v[194:197], 0
	v_mfma_f32_16x16x32_bf16 v[30:33], v[130:133], v[208:211], 0
	v_mfma_f32_16x16x32_bf16 v[26:29], v[148:151], v[208:211], 0
	v_mfma_f32_16x16x32_bf16 v[14:17], v[130:133], v[216:219], 0
	v_mfma_f32_16x16x32_bf16 v[10:13], v[148:151], v[216:219], 0
	v_mfma_f32_16x16x32_bf16 v[62:65], v[134:137], v[190:193], v[62:65]
	v_mfma_f32_16x16x32_bf16 v[58:61], v[152:155], v[190:193], v[58:61]
	v_mfma_f32_16x16x32_bf16 v[46:49], v[134:137], v[204:207], v[46:49]
	v_mfma_f32_16x16x32_bf16 v[42:45], v[152:155], v[204:207], v[42:45]
	v_mfma_f32_16x16x32_bf16 v[30:33], v[134:137], v[212:215], v[30:33]
	v_mfma_f32_16x16x32_bf16 v[26:29], v[152:155], v[212:215], v[26:29]
	v_mfma_f32_16x16x32_bf16 v[14:17], v[134:137], v[220:223], v[14:17]
	v_mfma_f32_16x16x32_bf16 v[10:13], v[152:155], v[220:223], v[10:13]
	v_mfma_f32_16x16x32_bf16 v[54:57], v[162:165], v[186:189], 0
	v_mfma_f32_16x16x32_bf16 v[50:53], v[170:173], v[186:189], 0
	v_mfma_f32_16x16x32_bf16 v[38:41], v[162:165], v[194:197], 0
	v_mfma_f32_16x16x32_bf16 v[34:37], v[170:173], v[194:197], 0
	v_mfma_f32_16x16x32_bf16 v[22:25], v[162:165], v[208:211], 0
	v_mfma_f32_16x16x32_bf16 v[18:21], v[170:173], v[208:211], 0
	v_mfma_f32_16x16x32_bf16 v[6:9], v[162:165], v[216:219], 0
	v_mfma_f32_16x16x32_bf16 v[2:5], v[170:173], v[216:219], 0
	v_mfma_f32_16x16x32_bf16 v[54:57], v[166:169], v[190:193], v[54:57]
	v_mfma_f32_16x16x32_bf16 v[50:53], v[182:185], v[190:193], v[50:53]
	v_mfma_f32_16x16x32_bf16 v[38:41], v[166:169], v[204:207], v[38:41]
	v_mfma_f32_16x16x32_bf16 v[34:37], v[182:185], v[204:207], v[34:37]
	v_mfma_f32_16x16x32_bf16 v[22:25], v[166:169], v[212:215], v[22:25]
	v_mfma_f32_16x16x32_bf16 v[18:21], v[182:185], v[212:215], v[18:21]
	v_mfma_f32_16x16x32_bf16 v[6:9], v[166:169], v[220:223], v[6:9]
	v_mfma_f32_16x16x32_bf16 v[2:5], v[182:185], v[220:223], v[2:5]
	s_barrier
; #define PG8_STAGE(bufoff, gbase, voff) do { _Pragma("unroll") for (int _i = 0; _i < 2; ++_i) \
;         __builtin_amdgcn_global_load_lds((const unsigned*)((const char*)(gbase) + (voff)[_i]), (PG8_LAS unsigned*)(lds + (bufoff) + ldsw + _i * 8192), 16, 0, 0); } while (0)
; #define PG8_LDA(dst, b, h) do { _Pragma("unroll") for (int m = 0; m < 4; ++m) _Pragma("unroll") for (int k = 0; k < 2; ++k) dst[m][k] = *(const PG8_LAS bf16x8*)(lds + PG8_SA(b, h) + aoff + m * 2048 + k * 1024); } while (0)
; #define PG8_LDB(dst, b, h) do { _Pragma("unroll") for (int n = 0; n < 2; ++n) _Pragma("unroll") for (int k = 0; k < 2; ++k) dst[n][k] = *(const PG8_LAS bf16x8*)(lds + PG8_SB(b, h) + boff + n * 2048 + k * 1024); } while (0)
; #define PG8_WAIT_V(n) asm volatile("s_waitcnt vmcnt(" #n ")" ::: "memory")
; #define PG8_WAIT_L(n) asm volatile("s_waitcnt lgkmcnt(" #n ")" ::: "memory")
; #define PG8_BAR __builtin_amdgcn_s_barrier()
; #define PG8_SCHED __builtin_amdgcn_sched_barrier(0)
; template <class Epi, class Sched, bool ALIGN_EPI = false, bool SP2 = false, bool F16 = false>
; __device__ __forceinline__ void gemm_phase(PG8_LAS unsigned char* lds, const Gemm g, const Sched& S, const Epi& E) {
;     ...
;             PG8_LDB(B0, 1, 0); PG8_LDB(B1, 1, 1); PG8_SCHED; PG8_LDA(At, 1, 0); PG8_STAGE(PG8_SA(0, 1), a2 + hstepA, voffA);
;             PG8_WAIT_V(8); PG8_WAIT_L(0); PG8_BAR; PG8_MMA(0, 0, At, B0); PG8_MMA(0, 1, At, B1); PG8_BAR; PG8_SCHED;
;             PG8_LDA(At, 1, 1); PG8_STAGE(PG8_SB(1, 0), b3, voffB); PG8_STAGE(PG8_SB(1, 1), b3 + hstepB, voffB); PG8_STAGE(PG8_SA(1, 0), a3, voffA);
;             PG8_WAIT_V(8); PG8_WAIT_L(0); PG8_BAR; PG8_MMA(1, 0, At, B0); PG8_MMA(1, 1, At, B1); PG8_BAR; PG8_SCHED;
	s_setprio 1
	s_add_i32 s82, 0, 0x18000
	s_add_i32 s83, 0, 0x1c000
	ds_read_b128 v[130:133], v143
	ds_read_b128 v[134:137], v143 offset:1024
	ds_read_b128 v[148:151], v143 offset:2048
	ds_read_b128 v[152:155], v143 offset:3072
	ds_read_b128 v[162:165], v157
	ds_read_b128 v[166:169], v157 offset:1024
	ds_read_b128 v[170:173], v157 offset:2048
	ds_read_b128 v[182:185], v157 offset:3072
	s_add_u32 s54, s54, s8
	s_addc_u32 s55, s55, 0
	s_mov_b32 m0, s13
	ds_read_b128 v[186:189], v160 offset:32768
	ds_read_b128 v[190:193], v160 offset:33792
	ds_read_b128 v[194:197], v160 offset:34816
	ds_read_b128 v[204:207], v160 offset:35840
	ds_read_b128 v[208:211], v160 offset:36864
	ds_read_b128 v[212:215], v160 offset:37888
	ds_read_b128 v[216:219], v160 offset:38912
	ds_read_b128 v[220:223], v160 offset:39936
	global_load_lds_dwordx4 v138, s[54:55]
	s_mov_b32 m0, s22
	s_nop 0
	global_load_lds_dwordx4 v140, s[54:55]
	s_waitcnt vmcnt(8)
	s_waitcnt lgkmcnt(0)
	s_setprio 2
	s_barrier
	v_mfma_f32_16x16x32_bf16 v[122:125], v[130:133], v[186:189], v[122:125]
	v_mfma_f32_16x16x32_bf16 v[126:129], v[148:151], v[186:189], v[126:129]
	v_mfma_f32_16x16x32_bf16 v[110:113], v[130:133], v[194:197], v[110:113]
	v_mfma_f32_16x16x32_bf16 v[106:109], v[148:151], v[194:197], v[106:109]
	v_mfma_f32_16x16x32_bf16 v[94:97], v[130:133], v[208:211], v[94:97]
	v_mfma_f32_16x16x32_bf16 v[90:93], v[148:151], v[208:211], v[90:93]
	v_mfma_f32_16x16x32_bf16 v[78:81], v[130:133], v[216:219], v[78:81]
	v_mfma_f32_16x16x32_bf16 v[74:77], v[148:151], v[216:219], v[74:77]
	v_mfma_f32_16x16x32_bf16 v[122:125], v[134:137], v[190:193], v[122:125]
	v_mfma_f32_16x16x32_bf16 v[126:129], v[152:155], v[190:193], v[126:129]
	v_mfma_f32_16x16x32_bf16 v[110:113], v[134:137], v[204:207], v[110:113]
	v_mfma_f32_16x16x32_bf16 v[106:109], v[152:155], v[204:207], v[106:109]
	v_mfma_f32_16x16x32_bf16 v[94:97], v[134:137], v[212:215], v[94:97]
	v_mfma_f32_16x16x32_bf16 v[90:93], v[152:155], v[212:215], v[90:93]
	v_mfma_f32_16x16x32_bf16 v[78:81], v[134:137], v[220:223], v[78:81]
	v_mfma_f32_16x16x32_bf16 v[74:77], v[152:155], v[220:223], v[74:77]
	v_mfma_f32_16x16x32_bf16 v[118:121], v[162:165], v[186:189], v[118:121]
	v_mfma_f32_16x16x32_bf16 v[114:117], v[170:173], v[186:189], v[114:117]
	v_mfma_f32_16x16x32_bf16 v[102:105], v[162:165], v[194:197], v[102:105]
	v_mfma_f32_16x16x32_bf16 v[98:101], v[170:173], v[194:197], v[98:101]
	v_mfma_f32_16x16x32_bf16 v[86:89], v[162:165], v[208:211], v[86:89]
	v_mfma_f32_16x16x32_bf16 v[82:85], v[170:173], v[208:211], v[82:85]
	v_mfma_f32_16x16x32_bf16 v[70:73], v[162:165], v[216:219], v[70:73]
	v_mfma_f32_16x16x32_bf16 v[66:69], v[170:173], v[216:219], v[66:69]
	v_mfma_f32_16x16x32_bf16 v[118:121], v[166:169], v[190:193], v[118:121]
	v_mfma_f32_16x16x32_bf16 v[114:117], v[182:185], v[190:193], v[114:117]
	v_mfma_f32_16x16x32_bf16 v[102:105], v[166:169], v[204:207], v[102:105]
	v_mfma_f32_16x16x32_bf16 v[98:101], v[182:185], v[204:207], v[98:101]
	v_mfma_f32_16x16x32_bf16 v[86:89], v[166:169], v[212:215], v[86:89]
	v_mfma_f32_16x16x32_bf16 v[82:85], v[182:185], v[212:215], v[82:85]
	v_mfma_f32_16x16x32_bf16 v[70:73], v[166:169], v[220:223], v[70:73]
	v_mfma_f32_16x16x32_bf16 v[66:69], v[182:185], v[220:223], v[66:69]
	s_barrier
	s_setprio 1
	s_add_i32 s54, s82, s2
	s_add_i32 vcc_hi, s81, -2
	s_cmp_eq_u32 s74, vcc_hi
	s_cselect_b32 s99, s47, s80
	s_cselect_b32 s98, s46, s79
	s_add_u32 s98, s98, s92
	s_addc_u32 s99, s99, s93
	s_mov_b32 m0, s54
	s_nop 0
	global_load_lds_dwordx4 v174, s[98:99]
	ds_read_b128 v[186:189], v160 offset:49152
	ds_read_b128 v[190:193], v160 offset:50176
	ds_read_b128 v[194:197], v160 offset:51200
	ds_read_b128 v[204:207], v160 offset:52224
	ds_read_b128 v[208:211], v160 offset:53248
	ds_read_b128 v[212:215], v160 offset:54272
	ds_read_b128 v[216:219], v160 offset:55296
	ds_read_b128 v[220:223], v160 offset:56320
	s_add_i32 m0, s54, 0x2000
	s_nop 0
	global_load_lds_dwordx4 v142, s[98:99]
	s_add_i32 s54, s83, s2
	s_add_u32 s98, s98, s48
	s_addc_u32 s99, s99, 0
	s_mov_b32 m0, s54
	s_nop 0
	global_load_lds_dwordx4 v174, s[98:99]
	s_add_i32 m0, s54, 0x2000
	s_nop 0
	global_load_lds_dwordx4 v142, s[98:99]
	s_add_u32 s98, s52, 0x80
	s_addc_u32 s99, s53, 0
	s_cmp_eq_u32 s74, vcc_hi
	s_cselect_b32 s99, s41, s99
	s_cselect_b32 s98, s40, s98
	s_add_u32 s98, s98, s92
	s_addc_u32 s99, s99, s93
	s_mov_b32 m0, s33
	s_nop 0
	global_load_lds_dwordx4 v138, s[98:99]
	s_mov_b32 m0, s35
	s_nop 0
	global_load_lds_dwordx4 v140, s[98:99]
	s_waitcnt vmcnt(8)
	s_waitcnt lgkmcnt(0)
	s_setprio 2
	s_barrier
	v_mfma_f32_16x16x32_bf16 v[62:65], v[130:133], v[186:189], v[62:65]
	v_mfma_f32_16x16x32_bf16 v[58:61], v[148:151], v[186:189], v[58:61]
	v_mfma_f32_16x16x32_bf16 v[46:49], v[130:133], v[194:197], v[46:49]
	v_mfma_f32_16x16x32_bf16 v[42:45], v[148:151], v[194:197], v[42:45]
	v_mfma_f32_16x16x32_bf16 v[30:33], v[130:133], v[208:211], v[30:33]
	v_mfma_f32_16x16x32_bf16 v[26:29], v[148:151], v[208:211], v[26:29]
	v_mfma_f32_16x16x32_bf16 v[14:17], v[130:133], v[216:219], v[14:17]
	v_mfma_f32_16x16x32_bf16 v[10:13], v[148:151], v[216:219], v[10:13]
	v_mfma_f32_16x16x32_bf16 v[62:65], v[134:137], v[190:193], v[62:65]
	v_mfma_f32_16x16x32_bf16 v[58:61], v[152:155], v[190:193], v[58:61]
	v_mfma_f32_16x16x32_bf16 v[46:49], v[134:137], v[204:207], v[46:49]
	v_mfma_f32_16x16x32_bf16 v[42:45], v[152:155], v[204:207], v[42:45]
	v_mfma_f32_16x16x32_bf16 v[30:33], v[134:137], v[212:215], v[30:33]
	v_mfma_f32_16x16x32_bf16 v[26:29], v[152:155], v[212:215], v[26:29]
	v_mfma_f32_16x16x32_bf16 v[14:17], v[134:137], v[220:223], v[14:17]
	v_mfma_f32_16x16x32_bf16 v[10:13], v[152:155], v[220:223], v[10:13]
	v_mfma_f32_16x16x32_bf16 v[54:57], v[162:165], v[186:189], v[54:57]
	v_mfma_f32_16x16x32_bf16 v[50:53], v[170:173], v[186:189], v[50:53]
	v_mfma_f32_16x16x32_bf16 v[38:41], v[162:165], v[194:197], v[38:41]
	v_mfma_f32_16x16x32_bf16 v[34:37], v[170:173], v[194:197], v[34:37]
	v_mfma_f32_16x16x32_bf16 v[22:25], v[162:165], v[208:211], v[22:25]
	v_mfma_f32_16x16x32_bf16 v[18:21], v[170:173], v[208:211], v[18:21]
	v_mfma_f32_16x16x32_bf16 v[6:9], v[162:165], v[216:219], v[6:9]
	v_mfma_f32_16x16x32_bf16 v[2:5], v[170:173], v[216:219], v[2:5]
	v_mfma_f32_16x16x32_bf16 v[54:57], v[166:169], v[190:193], v[54:57]
	v_mfma_f32_16x16x32_bf16 v[50:53], v[182:185], v[190:193], v[50:53]
	v_mfma_f32_16x16x32_bf16 v[38:41], v[166:169], v[204:207], v[38:41]
	v_mfma_f32_16x16x32_bf16 v[34:37], v[182:185], v[204:207], v[34:37]
	v_mfma_f32_16x16x32_bf16 v[22:25], v[166:169], v[212:215], v[22:25]
	v_mfma_f32_16x16x32_bf16 v[18:21], v[182:185], v[212:215], v[18:21]
	v_mfma_f32_16x16x32_bf16 v[6:9], v[166:169], v[220:223], v[6:9]
	v_mfma_f32_16x16x32_bf16 v[2:5], v[182:185], v[220:223], v[2:5]
	s_barrier
	s_setprio 1
	s_add_u32 s52, s52, 0x100
	s_addc_u32 s53, s53, 0
	s_add_u32 s79, s79, 0x100
	s_addc_u32 s80, s80, 0
	s_cmp_ge_u32 s81, s65
	s_mov_b32 s54, s81
	s_cbranch_scc1 .LBB0_346
; #define PG8_STAGE(bufoff, gbase, voff) do { _Pragma("unroll") for (int _i = 0; _i < 2; ++_i) \
;         __builtin_amdgcn_global_load_lds((const unsigned*)((const char*)(gbase) + (voff)[_i]), (PG8_LAS unsigned*)(lds + (bufoff) + ldsw + _i * 8192), 16, 0, 0); } while (0)
; #define PG8_LDA(dst, b, h) do { _Pragma("unroll") for (int m = 0; m < 4; ++m) _Pragma("unroll") for (int k = 0; k < 2; ++k) dst[m][k] = *(const PG8_LAS bf16x8*)(lds + PG8_SA(b, h) + aoff + m * 2048 + k * 1024); } while (0)
; #define PG8_LDB(dst, b, h) do { _Pragma("unroll") for (int n = 0; n < 2; ++n) _Pragma("unroll") for (int k = 0; k < 2; ++k) dst[n][k] = *(const PG8_LAS bf16x8*)(lds + PG8_SB(b, h) + boff + n * 2048 + k * 1024); } while (0)
; #define PG8_WAIT_V(n) asm volatile("s_waitcnt vmcnt(" #n ")" ::: "memory")
; #define PG8_WAIT_L(n) asm volatile("s_waitcnt lgkmcnt(" #n ")" ::: "memory")
; #define PG8_BAR __builtin_amdgcn_s_barrier()
; #define PG8_SCHED __builtin_amdgcn_sched_barrier(0)
; template <class Epi, class Sched, bool ALIGN_EPI = false, bool SP2 = false, bool F16 = false>
; __device__ __forceinline__ void gemm_phase(PG8_LAS unsigned char* lds, const Gemm g, const Sched& S, const Epi& E) {
;     ...
;         for (int t = 0; t < nt; t += 2) {
;             const bool last = (t == nt - 2);
;             const char* a1 = cA + (size_t)(t + 1) * kstep;
;             const char* a2 = last ? nA : cA + (size_t)(t + 2) * kstep; const char* b2 = last ? nB : cB + (size_t)(t + 2) * kstep;
;             const char* a3 = a2 + kstep; const char* b3 = b2 + kstep;
;             if (last && has_next) S.a_ready(nxt);
;             if constexpr (SP2) {
;             PG8_LDB(B0, 0, 0); PG8_LDB(B1, 0, 1); PG8_SCHED; PG8_LDA(At, 0, 0); PG8_STAGE(PG8_SA(1, 1), a1 + hstepA, voffA);
;             PG8_WAIT_V(8); PG8_WAIT_L(0); PG8_BAR; PG8_MMA(0, 0, At, B0); PG8_MMA(0, 1, At, B1); PG8_BAR; PG8_SCHED;
;             PG8_LDA(At, 0, 1); PG8_STAGE(PG8_SB(0, 0), b2, voffB); PG8_STAGE(PG8_SB(0, 1), b2 + hstepB, voffB); PG8_STAGE(PG8_SA(0, 0), a2, voffA);
;             PG8_WAIT_V(8); PG8_WAIT_L(0); PG8_BAR; PG8_MMA(1, 0, At, B0); PG8_MMA(1, 1, At, B1); PG8_BAR; PG8_SCHED;
.LBB0_345:
	s_add_i32 s81, s54, 2
	s_add_u32 s82, s52, 0x80
	s_addc_u32 s55, s53, 0
	s_add_i32 s94, 0, 0x10000
	s_cmp_eq_u32 s74, s54
	s_cselect_b32 s55, s41, s55
	s_cselect_b32 s54, s40, s82
	s_cselect_b32 s83, s47, s80
	s_cselect_b32 s82, s46, s79
	s_add_i32 s95, 0, 0x14000
	ds_read_b128 v[130:133], v139
	ds_read_b128 v[134:137], v139 offset:1024
	ds_read_b128 v[148:151], v139 offset:2048
	ds_read_b128 v[152:155], v139 offset:3072
	ds_read_b128 v[162:165], v141
	ds_read_b128 v[166:169], v141 offset:1024
	ds_read_b128 v[170:173], v141 offset:2048
	ds_read_b128 v[182:185], v141 offset:3072
	s_add_i32 m0, s3, 0xc000
	ds_read_b128 v[186:189], v160
	ds_read_b128 v[190:193], v160 offset:1024
	ds_read_b128 v[194:197], v160 offset:2048
	ds_read_b128 v[204:207], v160 offset:3072
	ds_read_b128 v[208:211], v160 offset:4096
	ds_read_b128 v[212:215], v160 offset:5120
	ds_read_b128 v[216:219], v160 offset:6144
	ds_read_b128 v[220:223], v160 offset:7168
	global_load_lds_dwordx4 v144, s[52:53]
	s_add_i32 m0, s3, 0xe000
	s_nop 0
	global_load_lds_dwordx4 v146, s[52:53]
	s_waitcnt vmcnt(8)
	s_waitcnt lgkmcnt(0)
	s_setprio 2
	s_barrier
	v_mfma_f32_16x16x32_bf16 v[122:125], v[130:133], v[186:189], v[122:125]
	v_mfma_f32_16x16x32_bf16 v[126:129], v[148:151], v[186:189], v[126:129]
	v_mfma_f32_16x16x32_bf16 v[110:113], v[130:133], v[194:197], v[110:113]
	v_mfma_f32_16x16x32_bf16 v[106:109], v[148:151], v[194:197], v[106:109]
	v_mfma_f32_16x16x32_bf16 v[94:97], v[130:133], v[208:211], v[94:97]
	v_mfma_f32_16x16x32_bf16 v[90:93], v[148:151], v[208:211], v[90:93]
	v_mfma_f32_16x16x32_bf16 v[78:81], v[130:133], v[216:219], v[78:81]
	v_mfma_f32_16x16x32_bf16 v[74:77], v[148:151], v[216:219], v[74:77]
	v_mfma_f32_16x16x32_bf16 v[122:125], v[134:137], v[190:193], v[122:125]
	v_mfma_f32_16x16x32_bf16 v[126:129], v[152:155], v[190:193], v[126:129]
	v_mfma_f32_16x16x32_bf16 v[110:113], v[134:137], v[204:207], v[110:113]
	v_mfma_f32_16x16x32_bf16 v[106:109], v[152:155], v[204:207], v[106:109]
	v_mfma_f32_16x16x32_bf16 v[94:97], v[134:137], v[212:215], v[94:97]
	v_mfma_f32_16x16x32_bf16 v[90:93], v[152:155], v[212:215], v[90:93]
	v_mfma_f32_16x16x32_bf16 v[78:81], v[134:137], v[220:223], v[78:81]
	v_mfma_f32_16x16x32_bf16 v[74:77], v[152:155], v[220:223], v[74:77]
	v_mfma_f32_16x16x32_bf16 v[118:121], v[162:165], v[186:189], v[118:121]
	v_mfma_f32_16x16x32_bf16 v[114:117], v[170:173], v[186:189], v[114:117]
	v_mfma_f32_16x16x32_bf16 v[102:105], v[162:165], v[194:197], v[102:105]
	v_mfma_f32_16x16x32_bf16 v[98:101], v[170:173], v[194:197], v[98:101]
	v_mfma_f32_16x16x32_bf16 v[86:89], v[162:165], v[208:211], v[86:89]
	v_mfma_f32_16x16x32_bf16 v[82:85], v[170:173], v[208:211], v[82:85]
	v_mfma_f32_16x16x32_bf16 v[70:73], v[162:165], v[216:219], v[70:73]
	v_mfma_f32_16x16x32_bf16 v[66:69], v[170:173], v[216:219], v[66:69]
	v_mfma_f32_16x16x32_bf16 v[118:121], v[166:169], v[190:193], v[118:121]
	v_mfma_f32_16x16x32_bf16 v[114:117], v[182:185], v[190:193], v[114:117]
	v_mfma_f32_16x16x32_bf16 v[102:105], v[166:169], v[204:207], v[102:105]
	v_mfma_f32_16x16x32_bf16 v[98:101], v[182:185], v[204:207], v[98:101]
	v_mfma_f32_16x16x32_bf16 v[86:89], v[166:169], v[212:215], v[86:89]
	v_mfma_f32_16x16x32_bf16 v[82:85], v[182:185], v[212:215], v[82:85]
	v_mfma_f32_16x16x32_bf16 v[70:73], v[166:169], v[220:223], v[70:73]
	v_mfma_f32_16x16x32_bf16 v[66:69], v[182:185], v[220:223], v[66:69]
	s_barrier
	s_setprio 1
	s_add_i32 s94, s94, s2
	s_mov_b32 m0, s94
	s_nop 0
	global_load_lds_dwordx4 v174, s[82:83]
	ds_read_b128 v[186:189], v160 offset:16384
	ds_read_b128 v[190:193], v160 offset:17408
	ds_read_b128 v[194:197], v160 offset:18432
	ds_read_b128 v[204:207], v160 offset:19456
	ds_read_b128 v[208:211], v160 offset:20480
	ds_read_b128 v[212:215], v160 offset:21504
	ds_read_b128 v[216:219], v160 offset:22528
	ds_read_b128 v[220:223], v160 offset:23552
	s_add_i32 m0, s94, 0x2000
	s_nop 0
	global_load_lds_dwordx4 v142, s[82:83]
	s_add_i32 s94, s95, s2
	s_add_u32 s82, s82, s48
	s_addc_u32 s83, s83, 0
	s_mov_b32 m0, s94
	s_nop 0
	global_load_lds_dwordx4 v174, s[82:83]
	s_add_i32 m0, s94, 0x2000
	s_nop 0
	global_load_lds_dwordx4 v142, s[82:83]
	s_mov_b32 m0, s3
	s_nop 0
	global_load_lds_dwordx4 v138, s[54:55]
	s_mov_b32 m0, s12
	s_nop 0
	global_load_lds_dwordx4 v140, s[54:55]
	s_waitcnt vmcnt(8)
	s_waitcnt lgkmcnt(0)
	s_setprio 2
	s_barrier
	v_mfma_f32_16x16x32_bf16 v[62:65], v[130:133], v[186:189], v[62:65]
	v_mfma_f32_16x16x32_bf16 v[58:61], v[148:151], v[186:189], v[58:61]
	v_mfma_f32_16x16x32_bf16 v[46:49], v[130:133], v[194:197], v[46:49]
	v_mfma_f32_16x16x32_bf16 v[42:45], v[148:151], v[194:197], v[42:45]
	v_mfma_f32_16x16x32_bf16 v[30:33], v[130:133], v[208:211], v[30:33]
	v_mfma_f32_16x16x32_bf16 v[26:29], v[148:151], v[208:211], v[26:29]
	v_mfma_f32_16x16x32_bf16 v[14:17], v[130:133], v[216:219], v[14:17]
	v_mfma_f32_16x16x32_bf16 v[10:13], v[148:151], v[216:219], v[10:13]
	v_mfma_f32_16x16x32_bf16 v[62:65], v[134:137], v[190:193], v[62:65]
	v_mfma_f32_16x16x32_bf16 v[58:61], v[152:155], v[190:193], v[58:61]
	v_mfma_f32_16x16x32_bf16 v[46:49], v[134:137], v[204:207], v[46:49]
	v_mfma_f32_16x16x32_bf16 v[42:45], v[152:155], v[204:207], v[42:45]
	v_mfma_f32_16x16x32_bf16 v[30:33], v[134:137], v[212:215], v[30:33]
	v_mfma_f32_16x16x32_bf16 v[26:29], v[152:155], v[212:215], v[26:29]
	v_mfma_f32_16x16x32_bf16 v[14:17], v[134:137], v[220:223], v[14:17]
	v_mfma_f32_16x16x32_bf16 v[10:13], v[152:155], v[220:223], v[10:13]
	v_mfma_f32_16x16x32_bf16 v[54:57], v[162:165], v[186:189], v[54:57]
	v_mfma_f32_16x16x32_bf16 v[50:53], v[170:173], v[186:189], v[50:53]
	v_mfma_f32_16x16x32_bf16 v[38:41], v[162:165], v[194:197], v[38:41]
	v_mfma_f32_16x16x32_bf16 v[34:37], v[170:173], v[194:197], v[34:37]
	v_mfma_f32_16x16x32_bf16 v[22:25], v[162:165], v[208:211], v[22:25]
	v_mfma_f32_16x16x32_bf16 v[18:21], v[170:173], v[208:211], v[18:21]
	v_mfma_f32_16x16x32_bf16 v[6:9], v[162:165], v[216:219], v[6:9]
	v_mfma_f32_16x16x32_bf16 v[2:5], v[170:173], v[216:219], v[2:5]
	v_mfma_f32_16x16x32_bf16 v[54:57], v[166:169], v[190:193], v[54:57]
	v_mfma_f32_16x16x32_bf16 v[50:53], v[182:185], v[190:193], v[50:53]
	v_mfma_f32_16x16x32_bf16 v[38:41], v[166:169], v[204:207], v[38:41]
	v_mfma_f32_16x16x32_bf16 v[34:37], v[182:185], v[204:207], v[34:37]
	v_mfma_f32_16x16x32_bf16 v[22:25], v[166:169], v[212:215], v[22:25]
	v_mfma_f32_16x16x32_bf16 v[18:21], v[182:185], v[212:215], v[18:21]
	v_mfma_f32_16x16x32_bf16 v[6:9], v[166:169], v[220:223], v[6:9]
	v_mfma_f32_16x16x32_bf16 v[2:5], v[182:185], v[220:223], v[2:5]
	s_barrier
; #define PG8_STAGE(bufoff, gbase, voff) do { _Pragma("unroll") for (int _i = 0; _i < 2; ++_i) \
;         __builtin_amdgcn_global_load_lds((const unsigned*)((const char*)(gbase) + (voff)[_i]), (PG8_LAS unsigned*)(lds + (bufoff) + ldsw + _i * 8192), 16, 0, 0); } while (0)
; #define PG8_LDA(dst, b, h) do { _Pragma("unroll") for (int m = 0; m < 4; ++m) _Pragma("unroll") for (int k = 0; k < 2; ++k) dst[m][k] = *(const PG8_LAS bf16x8*)(lds + PG8_SA(b, h) + aoff + m * 2048 + k * 1024); } while (0)
; #define PG8_LDB(dst, b, h) do { _Pragma("unroll") for (int n = 0; n < 2; ++n) _Pragma("unroll") for (int k = 0; k < 2; ++k) dst[n][k] = *(const PG8_LAS bf16x8*)(lds + PG8_SB(b, h) + boff + n * 2048 + k * 1024); } while (0)
; #define PG8_WAIT_V(n) asm volatile("s_waitcnt vmcnt(" #n ")" ::: "memory")
; #define PG8_WAIT_L(n) asm volatile("s_waitcnt lgkmcnt(" #n ")" ::: "memory")
; #define PG8_BAR __builtin_amdgcn_s_barrier()
; #define PG8_SCHED __builtin_amdgcn_sched_barrier(0)
; template <class Epi, class Sched, bool ALIGN_EPI = false, bool SP2 = false, bool F16 = false>
; __device__ __forceinline__ void gemm_phase(PG8_LAS unsigned char* lds, const Gemm g, const Sched& S, const Epi& E) {
;     ...
;             PG8_LDB(B0, 1, 0); PG8_LDB(B1, 1, 1); PG8_SCHED; PG8_LDA(At, 1, 0); PG8_STAGE(PG8_SA(0, 1), a2 + hstepA, voffA);
;             PG8_WAIT_V(8); PG8_WAIT_L(0); PG8_BAR; PG8_MMA(0, 0, At, B0); PG8_MMA(0, 1, At, B1); PG8_BAR; PG8_SCHED;
;             PG8_LDA(At, 1, 1); PG8_STAGE(PG8_SB(1, 0), b3, voffB); PG8_STAGE(PG8_SB(1, 1), b3 + hstepB, voffB); PG8_STAGE(PG8_SA(1, 0), a3, voffA);
;             PG8_WAIT_V(8); PG8_WAIT_L(0); PG8_BAR; PG8_MMA(1, 0, At, B0); PG8_MMA(1, 1, At, B1); PG8_BAR; PG8_SCHED;
;     ...
;         if constexpr (ALIGN_EPI) { if (wr == 0) PG8_BAR; }
	s_setprio 1
	s_add_i32 s82, 0, 0x18000
	s_add_i32 s83, 0, 0x1c000
	ds_read_b128 v[130:133], v143
	ds_read_b128 v[134:137], v143 offset:1024
	ds_read_b128 v[148:151], v143 offset:2048
	ds_read_b128 v[152:155], v143 offset:3072
	ds_read_b128 v[162:165], v157
	ds_read_b128 v[166:169], v157 offset:1024
	ds_read_b128 v[170:173], v157 offset:2048
	ds_read_b128 v[182:185], v157 offset:3072
	s_add_u32 s54, s54, s8
	s_addc_u32 s55, s55, 0
	s_mov_b32 m0, s13
	ds_read_b128 v[186:189], v160 offset:32768
	ds_read_b128 v[190:193], v160 offset:33792
	ds_read_b128 v[194:197], v160 offset:34816
	ds_read_b128 v[204:207], v160 offset:35840
	ds_read_b128 v[208:211], v160 offset:36864
	ds_read_b128 v[212:215], v160 offset:37888
	ds_read_b128 v[216:219], v160 offset:38912
	ds_read_b128 v[220:223], v160 offset:39936
	global_load_lds_dwordx4 v138, s[54:55]
	s_mov_b32 m0, s22
	s_nop 0
	global_load_lds_dwordx4 v140, s[54:55]
	s_waitcnt vmcnt(8)
	s_waitcnt lgkmcnt(0)
	s_setprio 2
	s_barrier
	v_mfma_f32_16x16x32_bf16 v[122:125], v[130:133], v[186:189], v[122:125]
	v_mfma_f32_16x16x32_bf16 v[126:129], v[148:151], v[186:189], v[126:129]
	v_mfma_f32_16x16x32_bf16 v[110:113], v[130:133], v[194:197], v[110:113]
	v_mfma_f32_16x16x32_bf16 v[106:109], v[148:151], v[194:197], v[106:109]
	v_mfma_f32_16x16x32_bf16 v[94:97], v[130:133], v[208:211], v[94:97]
	v_mfma_f32_16x16x32_bf16 v[90:93], v[148:151], v[208:211], v[90:93]
	v_mfma_f32_16x16x32_bf16 v[78:81], v[130:133], v[216:219], v[78:81]
	v_mfma_f32_16x16x32_bf16 v[74:77], v[148:151], v[216:219], v[74:77]
	v_mfma_f32_16x16x32_bf16 v[122:125], v[134:137], v[190:193], v[122:125]
	v_mfma_f32_16x16x32_bf16 v[126:129], v[152:155], v[190:193], v[126:129]
	v_mfma_f32_16x16x32_bf16 v[110:113], v[134:137], v[204:207], v[110:113]
	v_mfma_f32_16x16x32_bf16 v[106:109], v[152:155], v[204:207], v[106:109]
	v_mfma_f32_16x16x32_bf16 v[94:97], v[134:137], v[212:215], v[94:97]
	v_mfma_f32_16x16x32_bf16 v[90:93], v[152:155], v[212:215], v[90:93]
	v_mfma_f32_16x16x32_bf16 v[78:81], v[134:137], v[220:223], v[78:81]
	v_mfma_f32_16x16x32_bf16 v[74:77], v[152:155], v[220:223], v[74:77]
	v_mfma_f32_16x16x32_bf16 v[118:121], v[162:165], v[186:189], v[118:121]
	v_mfma_f32_16x16x32_bf16 v[114:117], v[170:173], v[186:189], v[114:117]
	v_mfma_f32_16x16x32_bf16 v[102:105], v[162:165], v[194:197], v[102:105]
	v_mfma_f32_16x16x32_bf16 v[98:101], v[170:173], v[194:197], v[98:101]
	v_mfma_f32_16x16x32_bf16 v[86:89], v[162:165], v[208:211], v[86:89]
	v_mfma_f32_16x16x32_bf16 v[82:85], v[170:173], v[208:211], v[82:85]
	v_mfma_f32_16x16x32_bf16 v[70:73], v[162:165], v[216:219], v[70:73]
	v_mfma_f32_16x16x32_bf16 v[66:69], v[170:173], v[216:219], v[66:69]
	v_mfma_f32_16x16x32_bf16 v[118:121], v[166:169], v[190:193], v[118:121]
	v_mfma_f32_16x16x32_bf16 v[114:117], v[182:185], v[190:193], v[114:117]
	v_mfma_f32_16x16x32_bf16 v[102:105], v[166:169], v[204:207], v[102:105]
	v_mfma_f32_16x16x32_bf16 v[98:101], v[182:185], v[204:207], v[98:101]
	v_mfma_f32_16x16x32_bf16 v[86:89], v[166:169], v[212:215], v[86:89]
	v_mfma_f32_16x16x32_bf16 v[82:85], v[182:185], v[212:215], v[82:85]
	v_mfma_f32_16x16x32_bf16 v[70:73], v[166:169], v[220:223], v[70:73]
	v_mfma_f32_16x16x32_bf16 v[66:69], v[182:185], v[220:223], v[66:69]
	s_barrier
	s_setprio 1
	s_add_i32 s54, s82, s2
	s_add_i32 vcc_hi, s81, -2
	s_cmp_eq_u32 s74, vcc_hi
	s_cselect_b32 s99, s47, s80
	s_cselect_b32 s98, s46, s79
	s_add_u32 s98, s98, s92
	s_addc_u32 s99, s99, s93
	s_mov_b32 m0, s54
	s_nop 0
	global_load_lds_dwordx4 v174, s[98:99]
	ds_read_b128 v[186:189], v160 offset:49152
	ds_read_b128 v[190:193], v160 offset:50176
	ds_read_b128 v[194:197], v160 offset:51200
	ds_read_b128 v[204:207], v160 offset:52224
	ds_read_b128 v[208:211], v160 offset:53248
	ds_read_b128 v[212:215], v160 offset:54272
	ds_read_b128 v[216:219], v160 offset:55296
	ds_read_b128 v[220:223], v160 offset:56320
	s_add_i32 m0, s54, 0x2000
	s_nop 0
	global_load_lds_dwordx4 v142, s[98:99]
	s_add_i32 s54, s83, s2
	s_add_u32 s98, s98, s48
	s_addc_u32 s99, s99, 0
	s_mov_b32 m0, s54
	s_nop 0
	global_load_lds_dwordx4 v174, s[98:99]
	s_add_i32 m0, s54, 0x2000
	s_nop 0
	global_load_lds_dwordx4 v142, s[98:99]
	s_add_u32 s98, s52, 0x80
	s_addc_u32 s99, s53, 0
	s_cmp_eq_u32 s74, vcc_hi
	s_cselect_b32 s99, s41, s99
	s_cselect_b32 s98, s40, s98
	s_add_u32 s98, s98, s92
	s_addc_u32 s99, s99, s93
	s_mov_b32 m0, s33
	s_nop 0
	global_load_lds_dwordx4 v138, s[98:99]
	s_mov_b32 m0, s35
	s_nop 0
	global_load_lds_dwordx4 v140, s[98:99]
	s_waitcnt vmcnt(8)
	s_waitcnt lgkmcnt(0)
	s_setprio 2
	s_barrier
	v_mfma_f32_16x16x32_bf16 v[62:65], v[130:133], v[186:189], v[62:65]
	v_mfma_f32_16x16x32_bf16 v[58:61], v[148:151], v[186:189], v[58:61]
	v_mfma_f32_16x16x32_bf16 v[46:49], v[130:133], v[194:197], v[46:49]
	v_mfma_f32_16x16x32_bf16 v[42:45], v[148:151], v[194:197], v[42:45]
	v_mfma_f32_16x16x32_bf16 v[30:33], v[130:133], v[208:211], v[30:33]
	v_mfma_f32_16x16x32_bf16 v[26:29], v[148:151], v[208:211], v[26:29]
	v_mfma_f32_16x16x32_bf16 v[14:17], v[130:133], v[216:219], v[14:17]
	v_mfma_f32_16x16x32_bf16 v[10:13], v[148:151], v[216:219], v[10:13]
	v_mfma_f32_16x16x32_bf16 v[62:65], v[134:137], v[190:193], v[62:65]
	v_mfma_f32_16x16x32_bf16 v[58:61], v[152:155], v[190:193], v[58:61]
	v_mfma_f32_16x16x32_bf16 v[46:49], v[134:137], v[204:207], v[46:49]
	v_mfma_f32_16x16x32_bf16 v[42:45], v[152:155], v[204:207], v[42:45]
	v_mfma_f32_16x16x32_bf16 v[30:33], v[134:137], v[212:215], v[30:33]
	v_mfma_f32_16x16x32_bf16 v[26:29], v[152:155], v[212:215], v[26:29]
	v_mfma_f32_16x16x32_bf16 v[14:17], v[134:137], v[220:223], v[14:17]
	v_mfma_f32_16x16x32_bf16 v[10:13], v[152:155], v[220:223], v[10:13]
	v_mfma_f32_16x16x32_bf16 v[54:57], v[162:165], v[186:189], v[54:57]
	v_mfma_f32_16x16x32_bf16 v[50:53], v[170:173], v[186:189], v[50:53]
	v_mfma_f32_16x16x32_bf16 v[38:41], v[162:165], v[194:197], v[38:41]
	v_mfma_f32_16x16x32_bf16 v[34:37], v[170:173], v[194:197], v[34:37]
	v_mfma_f32_16x16x32_bf16 v[22:25], v[162:165], v[208:211], v[22:25]
	v_mfma_f32_16x16x32_bf16 v[18:21], v[170:173], v[208:211], v[18:21]
	v_mfma_f32_16x16x32_bf16 v[6:9], v[162:165], v[216:219], v[6:9]
	v_mfma_f32_16x16x32_bf16 v[2:5], v[170:173], v[216:219], v[2:5]
	v_mfma_f32_16x16x32_bf16 v[54:57], v[166:169], v[190:193], v[54:57]
	v_mfma_f32_16x16x32_bf16 v[50:53], v[182:185], v[190:193], v[50:53]
	v_mfma_f32_16x16x32_bf16 v[38:41], v[166:169], v[204:207], v[38:41]
	v_mfma_f32_16x16x32_bf16 v[34:37], v[182:185], v[204:207], v[34:37]
	v_mfma_f32_16x16x32_bf16 v[22:25], v[166:169], v[212:215], v[22:25]
	v_mfma_f32_16x16x32_bf16 v[18:21], v[182:185], v[212:215], v[18:21]
	v_mfma_f32_16x16x32_bf16 v[6:9], v[166:169], v[220:223], v[6:9]
	v_mfma_f32_16x16x32_bf16 v[2:5], v[182:185], v[220:223], v[2:5]
	s_barrier
	s_setprio 1
	s_add_u32 s52, s52, 0x100
	s_addc_u32 s53, s53, 0
	s_add_u32 s79, s79, 0x100
	s_addc_u32 s80, s80, 0
	s_cmp_ge_u32 s81, s65
	s_mov_b32 s54, s81
	s_cbranch_scc0 .LBB0_345
.LBB0_346:
	s_setprio 0
	s_and_b64 vcc, exec, s[16:17]
	s_cbranch_vccz .LBB0_348
	s_barrier

; #define PG8_STAGE(bufoff, gbase, voff) do { _Pragma("unroll") for (int _i = 0; _i < 2; ++_i) \
;         __builtin_amdgcn_global_load_lds((const unsigned*)((const char*)(gbase) + (voff)[_i]), (PG8_LAS unsigned*)(lds + (bufoff) + ldsw + _i * 8192), 16, 0, 0); } while (0)
; #define PG8_LDA(dst, b, h) do { _Pragma("unroll") for (int m = 0; m < 4; ++m) _Pragma("unroll") for (int k = 0; k < 2; ++k) dst[m][k] = *(const PG8_LAS bf16x8*)(lds + PG8_SA(b, h) + aoff + m * 2048 + k * 1024); } while (0)
; #define PG8_LDB(dst, b, h) do { _Pragma("unroll") for (int n = 0; n < 2; ++n) _Pragma("unroll") for (int k = 0; k < 2; ++k) dst[n][k] = *(const PG8_LAS bf16x8*)(lds + PG8_SB(b, h) + boff + n * 2048 + k * 1024); } while (0)
; #define PG8_WAIT_V(n) asm volatile("s_waitcnt vmcnt(" #n ")" ::: "memory")
; #define PG8_WAIT_L(n) asm volatile("s_waitcnt lgkmcnt(" #n ")" ::: "memory")
; #define PG8_BAR __builtin_amdgcn_s_barrier()
; #define PG8_SCHED __builtin_amdgcn_sched_barrier(0)
; template <class Epi, class Sched, bool ALIGN_EPI = false, bool SP2 = false, bool F16 = false>
; __device__ __forceinline__ void gemm_phase(PG8_LAS unsigned char* lds, const Gemm g, const Sched& S, const Epi& E) {
;     ...
;         for (int t = 0; t < nt; t += 2) {
;             const bool last = (t == nt - 2);
;             const char* a1 = cA + (size_t)(t + 1) * kstep;
;             const char* a2 = last ? nA : cA + (size_t)(t + 2) * kstep; const char* b2 = last ? nB : cB + (size_t)(t + 2) * kstep;
;             const char* a3 = a2 + kstep; const char* b3 = b2 + kstep;
;             if (last && has_next) S.a_ready(nxt);
;             if constexpr (SP2) {
;             PG8_LDB(B0, 0, 0); PG8_LDB(B1, 0, 1); PG8_SCHED; PG8_LDA(At, 0, 0); PG8_STAGE(PG8_SA(1, 1), a1 + hstepA, voffA);
;             PG8_WAIT_V(8); PG8_WAIT_L(0); PG8_BAR; PG8_MMA(0, 0, At, B0); PG8_MMA(0, 1, At, B1); PG8_BAR; PG8_SCHED;
;             PG8_LDA(At, 0, 1); PG8_STAGE(PG8_SB(0, 0), b2, voffB); PG8_STAGE(PG8_SB(0, 1), b2 + hstepB, voffB); PG8_STAGE(PG8_SA(0, 0), a2, voffA);
;             PG8_WAIT_V(8); PG8_WAIT_L(0); PG8_BAR; PG8_MMA(1, 0, At, B0); PG8_MMA(1, 1, At, B1); PG8_BAR; PG8_SCHED;
.Lpk_bf:
	s_setprio 1
	s_add_i32 s78, s72, 2
	s_add_u32 s79, s46, 0x80
	s_addc_u32 s73, s47, 0
	s_add_i32 vcc_lo, 0, 0x10000
	s_cmp_eq_u32 s74, s72
	s_cselect_b32 s73, s55, s73
	s_cselect_b32 s72, s54, s79
	s_cselect_b32 s95, s53, s24
	s_cselect_b32 s94, s52, s13
	s_add_i32 s79, 0, 0x14000
	ds_read_b128 v[130:133], v155
	ds_read_b128 v[134:137], v155 offset:1024
	ds_read_b128 v[138:141], v155 offset:2048
	ds_read_b128 v[142:145], v155 offset:3072
	ds_read_b128 v[146:149], v157
	ds_read_b128 v[150:153], v157 offset:1024
	ds_read_b128 v[182:185], v157 offset:2048
	ds_read_b128 v[186:189], v157 offset:3072
	s_add_i32 m0, s36, 0xc000
	ds_read_b128 v[190:193], v204
	ds_read_b128 v[194:197], v204 offset:1024
	ds_read_b128 v[206:209], v204 offset:2048
	ds_read_b128 v[210:213], v204 offset:3072
	ds_read_b128 v[214:217], v204 offset:4096
	ds_read_b128 v[218:221], v204 offset:5120
	ds_read_b128 v[222:225], v204 offset:6144
	ds_read_b128 v[226:229], v204 offset:7168
	global_load_lds_dwordx4 v168, s[46:47]
	s_add_i32 m0, s36, 0xe000
	s_nop 0
	global_load_lds_dwordx4 v170, s[46:47]
	s_waitcnt vmcnt(8)
	s_waitcnt lgkmcnt(0)
	s_setprio 2
	s_barrier
	v_mfma_f32_16x16x32_bf16 v[122:125], v[130:133], v[190:193], 0
	v_mfma_f32_16x16x32_bf16 v[126:129], v[138:141], v[190:193], 0
	v_mfma_f32_16x16x32_bf16 v[110:113], v[130:133], v[206:209], 0
	v_mfma_f32_16x16x32_bf16 v[106:109], v[138:141], v[206:209], 0
	v_mfma_f32_16x16x32_bf16 v[94:97], v[130:133], v[214:217], 0
	v_mfma_f32_16x16x32_bf16 v[90:93], v[138:141], v[214:217], 0
	v_mfma_f32_16x16x32_bf16 v[78:81], v[130:133], v[222:225], 0
	v_mfma_f32_16x16x32_bf16 v[74:77], v[138:141], v[222:225], 0
	v_mfma_f32_16x16x32_bf16 v[122:125], v[134:137], v[194:197], v[122:125]
	v_mfma_f32_16x16x32_bf16 v[126:129], v[142:145], v[194:197], v[126:129]
	v_mfma_f32_16x16x32_bf16 v[110:113], v[134:137], v[210:213], v[110:113]
	v_mfma_f32_16x16x32_bf16 v[106:109], v[142:145], v[210:213], v[106:109]
	v_mfma_f32_16x16x32_bf16 v[94:97], v[134:137], v[218:221], v[94:97]
	v_mfma_f32_16x16x32_bf16 v[90:93], v[142:145], v[218:221], v[90:93]
	v_mfma_f32_16x16x32_bf16 v[78:81], v[134:137], v[226:229], v[78:81]
	v_mfma_f32_16x16x32_bf16 v[74:77], v[142:145], v[226:229], v[74:77]
	v_mfma_f32_16x16x32_bf16 v[118:121], v[146:149], v[190:193], 0
	v_mfma_f32_16x16x32_bf16 v[114:117], v[182:185], v[190:193], 0
	v_mfma_f32_16x16x32_bf16 v[102:105], v[146:149], v[206:209], 0
	v_mfma_f32_16x16x32_bf16 v[98:101], v[182:185], v[206:209], 0
	v_mfma_f32_16x16x32_bf16 v[86:89], v[146:149], v[214:217], 0
	v_mfma_f32_16x16x32_bf16 v[82:85], v[182:185], v[214:217], 0
	v_mfma_f32_16x16x32_bf16 v[70:73], v[146:149], v[222:225], 0
	v_mfma_f32_16x16x32_bf16 v[66:69], v[182:185], v[222:225], 0
	v_mfma_f32_16x16x32_bf16 v[118:121], v[150:153], v[194:197], v[118:121]
	v_mfma_f32_16x16x32_bf16 v[114:117], v[186:189], v[194:197], v[114:117]
	v_mfma_f32_16x16x32_bf16 v[102:105], v[150:153], v[210:213], v[102:105]
	v_mfma_f32_16x16x32_bf16 v[98:101], v[186:189], v[210:213], v[98:101]
	v_mfma_f32_16x16x32_bf16 v[86:89], v[150:153], v[218:221], v[86:89]
	v_mfma_f32_16x16x32_bf16 v[82:85], v[186:189], v[218:221], v[82:85]
	v_mfma_f32_16x16x32_bf16 v[70:73], v[150:153], v[226:229], v[70:73]
	v_mfma_f32_16x16x32_bf16 v[66:69], v[186:189], v[226:229], v[66:69]
	s_barrier
	s_setprio 1
	s_add_i32 vcc_lo, vcc_lo, s75
	s_mov_b32 m0, vcc_lo
	s_nop 0
	global_load_lds_dwordx4 v156, s[94:95]
	ds_read_b128 v[190:193], v204 offset:16384
	ds_read_b128 v[194:197], v204 offset:17408
	ds_read_b128 v[206:209], v204 offset:18432
	ds_read_b128 v[210:213], v204 offset:19456
	ds_read_b128 v[214:217], v204 offset:20480
	ds_read_b128 v[218:221], v204 offset:21504
	ds_read_b128 v[222:225], v204 offset:22528
	ds_read_b128 v[226:229], v204 offset:23552
	s_add_i32 m0, vcc_lo, 0x2000
	s_nop 0
	global_load_lds_dwordx4 v160, s[94:95]
	s_add_i32 s79, s79, s75
	s_add_u32 s94, s94, s48
	s_addc_u32 s95, s95, 0
	s_mov_b32 m0, s79
	s_nop 0
	global_load_lds_dwordx4 v156, s[94:95]
	s_add_i32 m0, s79, 0x2000
	s_nop 0
	global_load_lds_dwordx4 v160, s[94:95]
	s_mov_b32 m0, s36
	s_nop 0
	global_load_lds_dwordx4 v154, s[72:73]
	s_mov_b32 m0, s37
	s_nop 0
	global_load_lds_dwordx4 v158, s[72:73]
	s_waitcnt vmcnt(8)
	s_waitcnt lgkmcnt(0)
	s_setprio 2
	s_barrier
	v_mfma_f32_16x16x32_bf16 v[62:65], v[130:133], v[190:193], 0
	v_mfma_f32_16x16x32_bf16 v[58:61], v[138:141], v[190:193], 0
	v_mfma_f32_16x16x32_bf16 v[46:49], v[130:133], v[206:209], 0
	v_mfma_f32_16x16x32_bf16 v[42:45], v[138:141], v[206:209], 0
	v_mfma_f32_16x16x32_bf16 v[30:33], v[130:133], v[214:217], 0
	v_mfma_f32_16x16x32_bf16 v[26:29], v[138:141], v[214:217], 0
	v_mfma_f32_16x16x32_bf16 v[14:17], v[130:133], v[222:225], 0
	v_mfma_f32_16x16x32_bf16 v[10:13], v[138:141], v[222:225], 0
	v_mfma_f32_16x16x32_bf16 v[62:65], v[134:137], v[194:197], v[62:65]
	v_mfma_f32_16x16x32_bf16 v[58:61], v[142:145], v[194:197], v[58:61]
	v_mfma_f32_16x16x32_bf16 v[46:49], v[134:137], v[210:213], v[46:49]
	v_mfma_f32_16x16x32_bf16 v[42:45], v[142:145], v[210:213], v[42:45]
	v_mfma_f32_16x16x32_bf16 v[30:33], v[134:137], v[218:221], v[30:33]
	v_mfma_f32_16x16x32_bf16 v[26:29], v[142:145], v[218:221], v[26:29]
	v_mfma_f32_16x16x32_bf16 v[14:17], v[134:137], v[226:229], v[14:17]
	v_mfma_f32_16x16x32_bf16 v[10:13], v[142:145], v[226:229], v[10:13]
	v_mfma_f32_16x16x32_bf16 v[54:57], v[146:149], v[190:193], 0
	v_mfma_f32_16x16x32_bf16 v[50:53], v[182:185], v[190:193], 0
	v_mfma_f32_16x16x32_bf16 v[38:41], v[146:149], v[206:209], 0
	v_mfma_f32_16x16x32_bf16 v[34:37], v[182:185], v[206:209], 0
	v_mfma_f32_16x16x32_bf16 v[22:25], v[146:149], v[214:217], 0
	v_mfma_f32_16x16x32_bf16 v[18:21], v[182:185], v[214:217], 0
	v_mfma_f32_16x16x32_bf16 v[6:9], v[146:149], v[222:225], 0
	v_mfma_f32_16x16x32_bf16 v[2:5], v[182:185], v[222:225], 0
	v_mfma_f32_16x16x32_bf16 v[54:57], v[150:153], v[194:197], v[54:57]
	v_mfma_f32_16x16x32_bf16 v[50:53], v[186:189], v[194:197], v[50:53]
	v_mfma_f32_16x16x32_bf16 v[38:41], v[150:153], v[210:213], v[38:41]
	v_mfma_f32_16x16x32_bf16 v[34:37], v[186:189], v[210:213], v[34:37]
	v_mfma_f32_16x16x32_bf16 v[22:25], v[150:153], v[218:221], v[22:25]
	v_mfma_f32_16x16x32_bf16 v[18:21], v[186:189], v[218:221], v[18:21]
	v_mfma_f32_16x16x32_bf16 v[6:9], v[150:153], v[226:229], v[6:9]
	v_mfma_f32_16x16x32_bf16 v[2:5], v[186:189], v[226:229], v[2:5]
	s_barrier
; #define PG8_STAGE(bufoff, gbase, voff) do { _Pragma("unroll") for (int _i = 0; _i < 2; ++_i) \
;         __builtin_amdgcn_global_load_lds((const unsigned*)((const char*)(gbase) + (voff)[_i]), (PG8_LAS unsigned*)(lds + (bufoff) + ldsw + _i * 8192), 16, 0, 0); } while (0)
; #define PG8_LDA(dst, b, h) do { _Pragma("unroll") for (int m = 0; m < 4; ++m) _Pragma("unroll") for (int k = 0; k < 2; ++k) dst[m][k] = *(const PG8_LAS bf16x8*)(lds + PG8_SA(b, h) + aoff + m * 2048 + k * 1024); } while (0)
; #define PG8_LDB(dst, b, h) do { _Pragma("unroll") for (int n = 0; n < 2; ++n) _Pragma("unroll") for (int k = 0; k < 2; ++k) dst[n][k] = *(const PG8_LAS bf16x8*)(lds + PG8_SB(b, h) + boff + n * 2048 + k * 1024); } while (0)
; #define PG8_WAIT_V(n) asm volatile("s_waitcnt vmcnt(" #n ")" ::: "memory")
; #define PG8_WAIT_L(n) asm volatile("s_waitcnt lgkmcnt(" #n ")" ::: "memory")
; #define PG8_BAR __builtin_amdgcn_s_barrier()
; #define PG8_SCHED __builtin_amdgcn_sched_barrier(0)
; template <class Epi, class Sched, bool ALIGN_EPI = false, bool SP2 = false, bool F16 = false>
; __device__ __forceinline__ void gemm_phase(PG8_LAS unsigned char* lds, const Gemm g, const Sched& S, const Epi& E) {
;     ...
;             PG8_LDB(B0, 1, 0); PG8_LDB(B1, 1, 1); PG8_SCHED; PG8_LDA(At, 1, 0); PG8_STAGE(PG8_SA(0, 1), a2 + hstepA, voffA);
;             PG8_WAIT_V(8); PG8_WAIT_L(0); PG8_BAR; PG8_MMA(0, 0, At, B0); PG8_MMA(0, 1, At, B1); PG8_BAR; PG8_SCHED;
;             PG8_LDA(At, 1, 1); PG8_STAGE(PG8_SB(1, 0), b3, voffB); PG8_STAGE(PG8_SB(1, 1), b3 + hstepB, voffB); PG8_STAGE(PG8_SA(1, 0), a3, voffA);
;             PG8_WAIT_V(8); PG8_WAIT_L(0); PG8_BAR; PG8_MMA(1, 0, At, B0); PG8_MMA(1, 1, At, B1); PG8_BAR; PG8_SCHED;
	s_setprio 1
	s_add_i32 s79, 0, 0x18000
	s_add_i32 s94, 0, 0x1c000
	ds_read_b128 v[130:133], v159
	ds_read_b128 v[134:137], v159 offset:1024
	ds_read_b128 v[138:141], v159 offset:2048
	ds_read_b128 v[142:145], v159 offset:3072
	ds_read_b128 v[146:149], v161
	ds_read_b128 v[150:153], v161 offset:1024
	ds_read_b128 v[182:185], v161 offset:2048
	ds_read_b128 v[186:189], v161 offset:3072
	s_add_u32 s72, s72, s8
	s_addc_u32 s73, s73, 0
	s_mov_b32 m0, s35
	ds_read_b128 v[190:193], v204 offset:32768
	ds_read_b128 v[194:197], v204 offset:33792
	ds_read_b128 v[206:209], v204 offset:34816
	ds_read_b128 v[210:213], v204 offset:35840
	ds_read_b128 v[214:217], v204 offset:36864
	ds_read_b128 v[218:221], v204 offset:37888
	ds_read_b128 v[222:225], v204 offset:38912
	ds_read_b128 v[226:229], v204 offset:39936
	global_load_lds_dwordx4 v154, s[72:73]
	s_mov_b32 m0, s2
	s_nop 0
	global_load_lds_dwordx4 v158, s[72:73]
	s_waitcnt vmcnt(8)
	s_waitcnt lgkmcnt(0)
	s_setprio 2
	s_barrier
	v_mfma_f32_16x16x32_bf16 v[122:125], v[130:133], v[190:193], v[122:125]
	v_mfma_f32_16x16x32_bf16 v[126:129], v[138:141], v[190:193], v[126:129]
	v_mfma_f32_16x16x32_bf16 v[110:113], v[130:133], v[206:209], v[110:113]
	v_mfma_f32_16x16x32_bf16 v[106:109], v[138:141], v[206:209], v[106:109]
	v_mfma_f32_16x16x32_bf16 v[94:97], v[130:133], v[214:217], v[94:97]
	v_mfma_f32_16x16x32_bf16 v[90:93], v[138:141], v[214:217], v[90:93]
	v_mfma_f32_16x16x32_bf16 v[78:81], v[130:133], v[222:225], v[78:81]
	v_mfma_f32_16x16x32_bf16 v[74:77], v[138:141], v[222:225], v[74:77]
	v_mfma_f32_16x16x32_bf16 v[122:125], v[134:137], v[194:197], v[122:125]
	v_mfma_f32_16x16x32_bf16 v[126:129], v[142:145], v[194:197], v[126:129]
	v_mfma_f32_16x16x32_bf16 v[110:113], v[134:137], v[210:213], v[110:113]
	v_mfma_f32_16x16x32_bf16 v[106:109], v[142:145], v[210:213], v[106:109]
	v_mfma_f32_16x16x32_bf16 v[94:97], v[134:137], v[218:221], v[94:97]
	v_mfma_f32_16x16x32_bf16 v[90:93], v[142:145], v[218:221], v[90:93]
	v_mfma_f32_16x16x32_bf16 v[78:81], v[134:137], v[226:229], v[78:81]
	v_mfma_f32_16x16x32_bf16 v[74:77], v[142:145], v[226:229], v[74:77]
	v_mfma_f32_16x16x32_bf16 v[118:121], v[146:149], v[190:193], v[118:121]
	v_mfma_f32_16x16x32_bf16 v[114:117], v[182:185], v[190:193], v[114:117]
	v_mfma_f32_16x16x32_bf16 v[102:105], v[146:149], v[206:209], v[102:105]
	v_mfma_f32_16x16x32_bf16 v[98:101], v[182:185], v[206:209], v[98:101]
	v_mfma_f32_16x16x32_bf16 v[86:89], v[146:149], v[214:217], v[86:89]
	v_mfma_f32_16x16x32_bf16 v[82:85], v[182:185], v[214:217], v[82:85]
	v_mfma_f32_16x16x32_bf16 v[70:73], v[146:149], v[222:225], v[70:73]
	v_mfma_f32_16x16x32_bf16 v[66:69], v[182:185], v[222:225], v[66:69]
	v_mfma_f32_16x16x32_bf16 v[118:121], v[150:153], v[194:197], v[118:121]
	v_mfma_f32_16x16x32_bf16 v[114:117], v[186:189], v[194:197], v[114:117]
	v_mfma_f32_16x16x32_bf16 v[102:105], v[150:153], v[210:213], v[102:105]
	v_mfma_f32_16x16x32_bf16 v[98:101], v[186:189], v[210:213], v[98:101]
	v_mfma_f32_16x16x32_bf16 v[86:89], v[150:153], v[218:221], v[86:89]
	v_mfma_f32_16x16x32_bf16 v[82:85], v[186:189], v[218:221], v[82:85]
	v_mfma_f32_16x16x32_bf16 v[70:73], v[150:153], v[226:229], v[70:73]
	v_mfma_f32_16x16x32_bf16 v[66:69], v[186:189], v[226:229], v[66:69]
	s_barrier
	s_setprio 1
	s_add_i32 s72, s79, s75
	s_add_i32 vcc_hi, s78, -2
	s_cmp_eq_u32 s74, vcc_hi
	s_cselect_b32 s99, s53, s24
	s_cselect_b32 s98, s52, s13
	s_add_u32 s98, s98, s92
	s_addc_u32 s99, s99, s93
	s_mov_b32 m0, s72
	s_nop 0
	global_load_lds_dwordx4 v156, s[98:99]
	ds_read_b128 v[190:193], v204 offset:49152
	ds_read_b128 v[194:197], v204 offset:50176
	ds_read_b128 v[206:209], v204 offset:51200
	ds_read_b128 v[210:213], v204 offset:52224
	ds_read_b128 v[214:217], v204 offset:53248
	ds_read_b128 v[218:221], v204 offset:54272
	ds_read_b128 v[222:225], v204 offset:55296
	ds_read_b128 v[226:229], v204 offset:56320
	s_add_i32 m0, s72, 0x2000
	s_nop 0
	global_load_lds_dwordx4 v160, s[98:99]
	s_add_i32 s72, s94, s75
	s_add_u32 s98, s98, s48
	s_addc_u32 s99, s99, 0
	s_mov_b32 m0, s72
	s_nop 0
	global_load_lds_dwordx4 v156, s[98:99]
	s_add_i32 m0, s72, 0x2000
	s_nop 0
	global_load_lds_dwordx4 v160, s[98:99]
	s_add_u32 s98, s46, 0x80
	s_addc_u32 s99, s47, 0
	s_cmp_eq_u32 s74, vcc_hi
	s_cselect_b32 s99, s55, s99
	s_cselect_b32 s98, s54, s98
	s_add_u32 s98, s98, s92
	s_addc_u32 s99, s99, s93
	s_mov_b32 m0, s22
	s_nop 0
	global_load_lds_dwordx4 v154, s[98:99]
	s_mov_b32 m0, s23
	s_nop 0
	global_load_lds_dwordx4 v158, s[98:99]
	s_waitcnt vmcnt(8)
	s_waitcnt lgkmcnt(0)
	s_setprio 2
	s_barrier
	v_mfma_f32_16x16x32_bf16 v[62:65], v[130:133], v[190:193], v[62:65]
	v_mfma_f32_16x16x32_bf16 v[58:61], v[138:141], v[190:193], v[58:61]
	v_mfma_f32_16x16x32_bf16 v[46:49], v[130:133], v[206:209], v[46:49]
	v_mfma_f32_16x16x32_bf16 v[42:45], v[138:141], v[206:209], v[42:45]
	v_mfma_f32_16x16x32_bf16 v[30:33], v[130:133], v[214:217], v[30:33]
	v_mfma_f32_16x16x32_bf16 v[26:29], v[138:141], v[214:217], v[26:29]
	v_mfma_f32_16x16x32_bf16 v[14:17], v[130:133], v[222:225], v[14:17]
	v_mfma_f32_16x16x32_bf16 v[10:13], v[138:141], v[222:225], v[10:13]
	v_mfma_f32_16x16x32_bf16 v[62:65], v[134:137], v[194:197], v[62:65]
	v_mfma_f32_16x16x32_bf16 v[58:61], v[142:145], v[194:197], v[58:61]
	v_mfma_f32_16x16x32_bf16 v[46:49], v[134:137], v[210:213], v[46:49]
	v_mfma_f32_16x16x32_bf16 v[42:45], v[142:145], v[210:213], v[42:45]
	v_mfma_f32_16x16x32_bf16 v[30:33], v[134:137], v[218:221], v[30:33]
	v_mfma_f32_16x16x32_bf16 v[26:29], v[142:145], v[218:221], v[26:29]
	v_mfma_f32_16x16x32_bf16 v[14:17], v[134:137], v[226:229], v[14:17]
	v_mfma_f32_16x16x32_bf16 v[10:13], v[142:145], v[226:229], v[10:13]
	v_mfma_f32_16x16x32_bf16 v[54:57], v[146:149], v[190:193], v[54:57]
	v_mfma_f32_16x16x32_bf16 v[50:53], v[182:185], v[190:193], v[50:53]
	v_mfma_f32_16x16x32_bf16 v[38:41], v[146:149], v[206:209], v[38:41]
	v_mfma_f32_16x16x32_bf16 v[34:37], v[182:185], v[206:209], v[34:37]
	v_mfma_f32_16x16x32_bf16 v[22:25], v[146:149], v[214:217], v[22:25]
	v_mfma_f32_16x16x32_bf16 v[18:21], v[182:185], v[214:217], v[18:21]
	v_mfma_f32_16x16x32_bf16 v[6:9], v[146:149], v[222:225], v[6:9]
	v_mfma_f32_16x16x32_bf16 v[2:5], v[182:185], v[222:225], v[2:5]
	v_mfma_f32_16x16x32_bf16 v[54:57], v[150:153], v[194:197], v[54:57]
	v_mfma_f32_16x16x32_bf16 v[50:53], v[186:189], v[194:197], v[50:53]
	v_mfma_f32_16x16x32_bf16 v[38:41], v[150:153], v[210:213], v[38:41]
	v_mfma_f32_16x16x32_bf16 v[34:37], v[186:189], v[210:213], v[34:37]
	v_mfma_f32_16x16x32_bf16 v[22:25], v[150:153], v[218:221], v[22:25]
	v_mfma_f32_16x16x32_bf16 v[18:21], v[186:189], v[218:221], v[18:21]
	v_mfma_f32_16x16x32_bf16 v[6:9], v[150:153], v[226:229], v[6:9]
	v_mfma_f32_16x16x32_bf16 v[2:5], v[186:189], v[226:229], v[2:5]
	s_barrier
	s_setprio 1
	s_add_u32 s46, s46, 0x100
	s_addc_u32 s47, s47, 0
	s_add_u32 s13, s13, 0x100
	s_addc_u32 s24, s24, 0
	s_cmp_ge_u32 s78, s65
	s_mov_b32 s72, s78
	s_cbranch_scc1 .LBB0_399
; #define PG8_STAGE(bufoff, gbase, voff) do { _Pragma("unroll") for (int _i = 0; _i < 2; ++_i) \
;         __builtin_amdgcn_global_load_lds((const unsigned*)((const char*)(gbase) + (voff)[_i]), (PG8_LAS unsigned*)(lds + (bufoff) + ldsw + _i * 8192), 16, 0, 0); } while (0)
; #define PG8_LDA(dst, b, h) do { _Pragma("unroll") for (int m = 0; m < 4; ++m) _Pragma("unroll") for (int k = 0; k < 2; ++k) dst[m][k] = *(const PG8_LAS bf16x8*)(lds + PG8_SA(b, h) + aoff + m * 2048 + k * 1024); } while (0)
; #define PG8_LDB(dst, b, h) do { _Pragma("unroll") for (int n = 0; n < 2; ++n) _Pragma("unroll") for (int k = 0; k < 2; ++k) dst[n][k] = *(const PG8_LAS bf16x8*)(lds + PG8_SB(b, h) + boff + n * 2048 + k * 1024); } while (0)
; #define PG8_WAIT_V(n) asm volatile("s_waitcnt vmcnt(" #n ")" ::: "memory")
; #define PG8_WAIT_L(n) asm volatile("s_waitcnt lgkmcnt(" #n ")" ::: "memory")
; #define PG8_BAR __builtin_amdgcn_s_barrier()
; #define PG8_SCHED __builtin_amdgcn_sched_barrier(0)
; template <class Epi, class Sched, bool ALIGN_EPI = false, bool SP2 = false, bool F16 = false>
; __device__ __forceinline__ void gemm_phase(PG8_LAS unsigned char* lds, const Gemm g, const Sched& S, const Epi& E) {
;     ...
;         for (int t = 0; t < nt; t += 2) {
;             const bool last = (t == nt - 2);
;             const char* a1 = cA + (size_t)(t + 1) * kstep;
;             const char* a2 = last ? nA : cA + (size_t)(t + 2) * kstep; const char* b2 = last ? nB : cB + (size_t)(t + 2) * kstep;
;             const char* a3 = a2 + kstep; const char* b3 = b2 + kstep;
;             if (last && has_next) S.a_ready(nxt);
;             if constexpr (SP2) {
;             PG8_LDB(B0, 0, 0); PG8_LDB(B1, 0, 1); PG8_SCHED; PG8_LDA(At, 0, 0); PG8_STAGE(PG8_SA(1, 1), a1 + hstepA, voffA);
;             PG8_WAIT_V(8); PG8_WAIT_L(0); PG8_BAR; PG8_MMA(0, 0, At, B0); PG8_MMA(0, 1, At, B1); PG8_BAR; PG8_SCHED;
;             PG8_LDA(At, 0, 1); PG8_STAGE(PG8_SB(0, 0), b2, voffB); PG8_STAGE(PG8_SB(0, 1), b2 + hstepB, voffB); PG8_STAGE(PG8_SA(0, 0), a2, voffA);
;             PG8_WAIT_V(8); PG8_WAIT_L(0); PG8_BAR; PG8_MMA(1, 0, At, B0); PG8_MMA(1, 1, At, B1); PG8_BAR; PG8_SCHED;
.LBB0_398:
	s_add_i32 s78, s72, 2
	s_add_u32 s79, s46, 0x80
	s_addc_u32 s73, s47, 0
	s_add_i32 vcc_lo, 0, 0x10000
	s_cmp_eq_u32 s74, s72
	s_cselect_b32 s73, s55, s73
	s_cselect_b32 s72, s54, s79
	s_cselect_b32 s95, s53, s24
	s_cselect_b32 s94, s52, s13
	s_add_i32 s79, 0, 0x14000
	ds_read_b128 v[130:133], v155
	ds_read_b128 v[134:137], v155 offset:1024
	ds_read_b128 v[138:141], v155 offset:2048
	ds_read_b128 v[142:145], v155 offset:3072
	ds_read_b128 v[146:149], v157
	ds_read_b128 v[150:153], v157 offset:1024
	ds_read_b128 v[182:185], v157 offset:2048
	ds_read_b128 v[186:189], v157 offset:3072
	s_add_i32 m0, s36, 0xc000
	ds_read_b128 v[190:193], v204
	ds_read_b128 v[194:197], v204 offset:1024
	ds_read_b128 v[206:209], v204 offset:2048
	ds_read_b128 v[210:213], v204 offset:3072
	ds_read_b128 v[214:217], v204 offset:4096
	ds_read_b128 v[218:221], v204 offset:5120
	ds_read_b128 v[222:225], v204 offset:6144
	ds_read_b128 v[226:229], v204 offset:7168
	global_load_lds_dwordx4 v168, s[46:47]
	s_add_i32 m0, s36, 0xe000
	s_nop 0
	global_load_lds_dwordx4 v170, s[46:47]
	s_waitcnt vmcnt(8)
	s_waitcnt lgkmcnt(0)
	s_setprio 2
	s_barrier
	v_mfma_f32_16x16x32_bf16 v[122:125], v[130:133], v[190:193], v[122:125]
	v_mfma_f32_16x16x32_bf16 v[126:129], v[138:141], v[190:193], v[126:129]
	v_mfma_f32_16x16x32_bf16 v[110:113], v[130:133], v[206:209], v[110:113]
	v_mfma_f32_16x16x32_bf16 v[106:109], v[138:141], v[206:209], v[106:109]
	v_mfma_f32_16x16x32_bf16 v[94:97], v[130:133], v[214:217], v[94:97]
	v_mfma_f32_16x16x32_bf16 v[90:93], v[138:141], v[214:217], v[90:93]
	v_mfma_f32_16x16x32_bf16 v[78:81], v[130:133], v[222:225], v[78:81]
	v_mfma_f32_16x16x32_bf16 v[74:77], v[138:141], v[222:225], v[74:77]
	v_mfma_f32_16x16x32_bf16 v[122:125], v[134:137], v[194:197], v[122:125]
	v_mfma_f32_16x16x32_bf16 v[126:129], v[142:145], v[194:197], v[126:129]
	v_mfma_f32_16x16x32_bf16 v[110:113], v[134:137], v[210:213], v[110:113]
	v_mfma_f32_16x16x32_bf16 v[106:109], v[142:145], v[210:213], v[106:109]
	v_mfma_f32_16x16x32_bf16 v[94:97], v[134:137], v[218:221], v[94:97]
	v_mfma_f32_16x16x32_bf16 v[90:93], v[142:145], v[218:221], v[90:93]
	v_mfma_f32_16x16x32_bf16 v[78:81], v[134:137], v[226:229], v[78:81]
	v_mfma_f32_16x16x32_bf16 v[74:77], v[142:145], v[226:229], v[74:77]
	v_mfma_f32_16x16x32_bf16 v[118:121], v[146:149], v[190:193], v[118:121]
	v_mfma_f32_16x16x32_bf16 v[114:117], v[182:185], v[190:193], v[114:117]
	v_mfma_f32_16x16x32_bf16 v[102:105], v[146:149], v[206:209], v[102:105]
	v_mfma_f32_16x16x32_bf16 v[98:101], v[182:185], v[206:209], v[98:101]
	v_mfma_f32_16x16x32_bf16 v[86:89], v[146:149], v[214:217], v[86:89]
	v_mfma_f32_16x16x32_bf16 v[82:85], v[182:185], v[214:217], v[82:85]
	v_mfma_f32_16x16x32_bf16 v[70:73], v[146:149], v[222:225], v[70:73]
	v_mfma_f32_16x16x32_bf16 v[66:69], v[182:185], v[222:225], v[66:69]
	v_mfma_f32_16x16x32_bf16 v[118:121], v[150:153], v[194:197], v[118:121]
	v_mfma_f32_16x16x32_bf16 v[114:117], v[186:189], v[194:197], v[114:117]
	v_mfma_f32_16x16x32_bf16 v[102:105], v[150:153], v[210:213], v[102:105]
	v_mfma_f32_16x16x32_bf16 v[98:101], v[186:189], v[210:213], v[98:101]
	v_mfma_f32_16x16x32_bf16 v[86:89], v[150:153], v[218:221], v[86:89]
	v_mfma_f32_16x16x32_bf16 v[82:85], v[186:189], v[218:221], v[82:85]
	v_mfma_f32_16x16x32_bf16 v[70:73], v[150:153], v[226:229], v[70:73]
	v_mfma_f32_16x16x32_bf16 v[66:69], v[186:189], v[226:229], v[66:69]
	s_barrier
	s_setprio 1
	s_add_i32 vcc_lo, vcc_lo, s75
	s_mov_b32 m0, vcc_lo
	s_nop 0
	global_load_lds_dwordx4 v156, s[94:95]
	ds_read_b128 v[190:193], v204 offset:16384
	ds_read_b128 v[194:197], v204 offset:17408
	ds_read_b128 v[206:209], v204 offset:18432
	ds_read_b128 v[210:213], v204 offset:19456
	ds_read_b128 v[214:217], v204 offset:20480
	ds_read_b128 v[218:221], v204 offset:21504
	ds_read_b128 v[222:225], v204 offset:22528
	ds_read_b128 v[226:229], v204 offset:23552
	s_add_i32 m0, vcc_lo, 0x2000
	s_nop 0
	global_load_lds_dwordx4 v160, s[94:95]
	s_add_i32 s79, s79, s75
	s_add_u32 s94, s94, s48
	s_addc_u32 s95, s95, 0
	s_mov_b32 m0, s79
	s_nop 0
	global_load_lds_dwordx4 v156, s[94:95]
	s_add_i32 m0, s79, 0x2000
	s_nop 0
	global_load_lds_dwordx4 v160, s[94:95]
	s_mov_b32 m0, s36
	s_nop 0
	global_load_lds_dwordx4 v154, s[72:73]
	s_mov_b32 m0, s37
	s_nop 0
	global_load_lds_dwordx4 v158, s[72:73]
	s_waitcnt vmcnt(8)
	s_waitcnt lgkmcnt(0)
	s_setprio 2
	s_barrier
	v_mfma_f32_16x16x32_bf16 v[62:65], v[130:133], v[190:193], v[62:65]
	v_mfma_f32_16x16x32_bf16 v[58:61], v[138:141], v[190:193], v[58:61]
	v_mfma_f32_16x16x32_bf16 v[46:49], v[130:133], v[206:209], v[46:49]
	v_mfma_f32_16x16x32_bf16 v[42:45], v[138:141], v[206:209], v[42:45]
	v_mfma_f32_16x16x32_bf16 v[30:33], v[130:133], v[214:217], v[30:33]
	v_mfma_f32_16x16x32_bf16 v[26:29], v[138:141], v[214:217], v[26:29]
	v_mfma_f32_16x16x32_bf16 v[14:17], v[130:133], v[222:225], v[14:17]
	v_mfma_f32_16x16x32_bf16 v[10:13], v[138:141], v[222:225], v[10:13]
	v_mfma_f32_16x16x32_bf16 v[62:65], v[134:137], v[194:197], v[62:65]
	v_mfma_f32_16x16x32_bf16 v[58:61], v[142:145], v[194:197], v[58:61]
	v_mfma_f32_16x16x32_bf16 v[46:49], v[134:137], v[210:213], v[46:49]
	v_mfma_f32_16x16x32_bf16 v[42:45], v[142:145], v[210:213], v[42:45]
	v_mfma_f32_16x16x32_bf16 v[30:33], v[134:137], v[218:221], v[30:33]
	v_mfma_f32_16x16x32_bf16 v[26:29], v[142:145], v[218:221], v[26:29]
	v_mfma_f32_16x16x32_bf16 v[14:17], v[134:137], v[226:229], v[14:17]
	v_mfma_f32_16x16x32_bf16 v[10:13], v[142:145], v[226:229], v[10:13]
	v_mfma_f32_16x16x32_bf16 v[54:57], v[146:149], v[190:193], v[54:57]
	v_mfma_f32_16x16x32_bf16 v[50:53], v[182:185], v[190:193], v[50:53]
	v_mfma_f32_16x16x32_bf16 v[38:41], v[146:149], v[206:209], v[38:41]
	v_mfma_f32_16x16x32_bf16 v[34:37], v[182:185], v[206:209], v[34:37]
	v_mfma_f32_16x16x32_bf16 v[22:25], v[146:149], v[214:217], v[22:25]
	v_mfma_f32_16x16x32_bf16 v[18:21], v[182:185], v[214:217], v[18:21]
	v_mfma_f32_16x16x32_bf16 v[6:9], v[146:149], v[222:225], v[6:9]
	v_mfma_f32_16x16x32_bf16 v[2:5], v[182:185], v[222:225], v[2:5]
	v_mfma_f32_16x16x32_bf16 v[54:57], v[150:153], v[194:197], v[54:57]
	v_mfma_f32_16x16x32_bf16 v[50:53], v[186:189], v[194:197], v[50:53]
	v_mfma_f32_16x16x32_bf16 v[38:41], v[150:153], v[210:213], v[38:41]
	v_mfma_f32_16x16x32_bf16 v[34:37], v[186:189], v[210:213], v[34:37]
	v_mfma_f32_16x16x32_bf16 v[22:25], v[150:153], v[218:221], v[22:25]
	v_mfma_f32_16x16x32_bf16 v[18:21], v[186:189], v[218:221], v[18:21]
	v_mfma_f32_16x16x32_bf16 v[6:9], v[150:153], v[226:229], v[6:9]
	v_mfma_f32_16x16x32_bf16 v[2:5], v[186:189], v[226:229], v[2:5]
	s_barrier
; #define PG8_STAGE(bufoff, gbase, voff) do { _Pragma("unroll") for (int _i = 0; _i < 2; ++_i) \
;         __builtin_amdgcn_global_load_lds((const unsigned*)((const char*)(gbase) + (voff)[_i]), (PG8_LAS unsigned*)(lds + (bufoff) + ldsw + _i * 8192), 16, 0, 0); } while (0)
; #define PG8_LDA(dst, b, h) do { _Pragma("unroll") for (int m = 0; m < 4; ++m) _Pragma("unroll") for (int k = 0; k < 2; ++k) dst[m][k] = *(const PG8_LAS bf16x8*)(lds + PG8_SA(b, h) + aoff + m * 2048 + k * 1024); } while (0)
; #define PG8_LDB(dst, b, h) do { _Pragma("unroll") for (int n = 0; n < 2; ++n) _Pragma("unroll") for (int k = 0; k < 2; ++k) dst[n][k] = *(const PG8_LAS bf16x8*)(lds + PG8_SB(b, h) + boff + n * 2048 + k * 1024); } while (0)
; #define PG8_WAIT_V(n) asm volatile("s_waitcnt vmcnt(" #n ")" ::: "memory")
; #define PG8_WAIT_L(n) asm volatile("s_waitcnt lgkmcnt(" #n ")" ::: "memory")
; #define PG8_BAR __builtin_amdgcn_s_barrier()
; #define PG8_SCHED __builtin_amdgcn_sched_barrier(0)
; template <class Epi, class Sched, bool ALIGN_EPI = false, bool SP2 = false, bool F16 = false>
; __device__ __forceinline__ void gemm_phase(PG8_LAS unsigned char* lds, const Gemm g, const Sched& S, const Epi& E) {
;     ...
;             PG8_LDB(B0, 1, 0); PG8_LDB(B1, 1, 1); PG8_SCHED; PG8_LDA(At, 1, 0); PG8_STAGE(PG8_SA(0, 1), a2 + hstepA, voffA);
;             PG8_WAIT_V(8); PG8_WAIT_L(0); PG8_BAR; PG8_MMA(0, 0, At, B0); PG8_MMA(0, 1, At, B1); PG8_BAR; PG8_SCHED;
;             PG8_LDA(At, 1, 1); PG8_STAGE(PG8_SB(1, 0), b3, voffB); PG8_STAGE(PG8_SB(1, 1), b3 + hstepB, voffB); PG8_STAGE(PG8_SA(1, 0), a3, voffA);
;             PG8_WAIT_V(8); PG8_WAIT_L(0); PG8_BAR; PG8_MMA(1, 0, At, B0); PG8_MMA(1, 1, At, B1); PG8_BAR; PG8_SCHED;
;     ...
;         if constexpr (ALIGN_EPI) { if (wr == 0) PG8_BAR; }
	s_setprio 1
	s_add_i32 s79, 0, 0x18000
	s_add_i32 s94, 0, 0x1c000
	ds_read_b128 v[130:133], v159
	ds_read_b128 v[134:137], v159 offset:1024
	ds_read_b128 v[138:141], v159 offset:2048
	ds_read_b128 v[142:145], v159 offset:3072
	ds_read_b128 v[146:149], v161
	ds_read_b128 v[150:153], v161 offset:1024
	ds_read_b128 v[182:185], v161 offset:2048
	ds_read_b128 v[186:189], v161 offset:3072
	s_add_u32 s72, s72, s8
	s_addc_u32 s73, s73, 0
	s_mov_b32 m0, s35
	ds_read_b128 v[190:193], v204 offset:32768
	ds_read_b128 v[194:197], v204 offset:33792
	ds_read_b128 v[206:209], v204 offset:34816
	ds_read_b128 v[210:213], v204 offset:35840
	ds_read_b128 v[214:217], v204 offset:36864
	ds_read_b128 v[218:221], v204 offset:37888
	ds_read_b128 v[222:225], v204 offset:38912
	ds_read_b128 v[226:229], v204 offset:39936
	global_load_lds_dwordx4 v154, s[72:73]
	s_mov_b32 m0, s2
	s_nop 0
	global_load_lds_dwordx4 v158, s[72:73]
	s_waitcnt vmcnt(8)
	s_waitcnt lgkmcnt(0)
	s_setprio 2
	s_barrier
	v_mfma_f32_16x16x32_bf16 v[122:125], v[130:133], v[190:193], v[122:125]
	v_mfma_f32_16x16x32_bf16 v[126:129], v[138:141], v[190:193], v[126:129]
	v_mfma_f32_16x16x32_bf16 v[110:113], v[130:133], v[206:209], v[110:113]
	v_mfma_f32_16x16x32_bf16 v[106:109], v[138:141], v[206:209], v[106:109]
	v_mfma_f32_16x16x32_bf16 v[94:97], v[130:133], v[214:217], v[94:97]
	v_mfma_f32_16x16x32_bf16 v[90:93], v[138:141], v[214:217], v[90:93]
	v_mfma_f32_16x16x32_bf16 v[78:81], v[130:133], v[222:225], v[78:81]
	v_mfma_f32_16x16x32_bf16 v[74:77], v[138:141], v[222:225], v[74:77]
	v_mfma_f32_16x16x32_bf16 v[122:125], v[134:137], v[194:197], v[122:125]
	v_mfma_f32_16x16x32_bf16 v[126:129], v[142:145], v[194:197], v[126:129]
	v_mfma_f32_16x16x32_bf16 v[110:113], v[134:137], v[210:213], v[110:113]
	v_mfma_f32_16x16x32_bf16 v[106:109], v[142:145], v[210:213], v[106:109]
	v_mfma_f32_16x16x32_bf16 v[94:97], v[134:137], v[218:221], v[94:97]
	v_mfma_f32_16x16x32_bf16 v[90:93], v[142:145], v[218:221], v[90:93]
	v_mfma_f32_16x16x32_bf16 v[78:81], v[134:137], v[226:229], v[78:81]
	v_mfma_f32_16x16x32_bf16 v[74:77], v[142:145], v[226:229], v[74:77]
	v_mfma_f32_16x16x32_bf16 v[118:121], v[146:149], v[190:193], v[118:121]
	v_mfma_f32_16x16x32_bf16 v[114:117], v[182:185], v[190:193], v[114:117]
	v_mfma_f32_16x16x32_bf16 v[102:105], v[146:149], v[206:209], v[102:105]
	v_mfma_f32_16x16x32_bf16 v[98:101], v[182:185], v[206:209], v[98:101]
	v_mfma_f32_16x16x32_bf16 v[86:89], v[146:149], v[214:217], v[86:89]
	v_mfma_f32_16x16x32_bf16 v[82:85], v[182:185], v[214:217], v[82:85]
	v_mfma_f32_16x16x32_bf16 v[70:73], v[146:149], v[222:225], v[70:73]
	v_mfma_f32_16x16x32_bf16 v[66:69], v[182:185], v[222:225], v[66:69]
	v_mfma_f32_16x16x32_bf16 v[118:121], v[150:153], v[194:197], v[118:121]
	v_mfma_f32_16x16x32_bf16 v[114:117], v[186:189], v[194:197], v[114:117]
	v_mfma_f32_16x16x32_bf16 v[102:105], v[150:153], v[210:213], v[102:105]
	v_mfma_f32_16x16x32_bf16 v[98:101], v[186:189], v[210:213], v[98:101]
	v_mfma_f32_16x16x32_bf16 v[86:89], v[150:153], v[218:221], v[86:89]
	v_mfma_f32_16x16x32_bf16 v[82:85], v[186:189], v[218:221], v[82:85]
	v_mfma_f32_16x16x32_bf16 v[70:73], v[150:153], v[226:229], v[70:73]
	v_mfma_f32_16x16x32_bf16 v[66:69], v[186:189], v[226:229], v[66:69]
	s_barrier
	s_setprio 1
	s_add_i32 s72, s79, s75
	s_add_i32 vcc_hi, s78, -2
	s_cmp_eq_u32 s74, vcc_hi
	s_cselect_b32 s99, s53, s24
	s_cselect_b32 s98, s52, s13
	s_add_u32 s98, s98, s92
	s_addc_u32 s99, s99, s93
	s_mov_b32 m0, s72
	s_nop 0
	global_load_lds_dwordx4 v156, s[98:99]
	ds_read_b128 v[190:193], v204 offset:49152
	ds_read_b128 v[194:197], v204 offset:50176
	ds_read_b128 v[206:209], v204 offset:51200
	ds_read_b128 v[210:213], v204 offset:52224
	ds_read_b128 v[214:217], v204 offset:53248
	ds_read_b128 v[218:221], v204 offset:54272
	ds_read_b128 v[222:225], v204 offset:55296
	ds_read_b128 v[226:229], v204 offset:56320
	s_add_i32 m0, s72, 0x2000
	s_nop 0
	global_load_lds_dwordx4 v160, s[98:99]
	s_add_i32 s72, s94, s75
	s_add_u32 s98, s98, s48
	s_addc_u32 s99, s99, 0
	s_mov_b32 m0, s72
	s_nop 0
	global_load_lds_dwordx4 v156, s[98:99]
	s_add_i32 m0, s72, 0x2000
	s_nop 0
	global_load_lds_dwordx4 v160, s[98:99]
	s_add_u32 s98, s46, 0x80
	s_addc_u32 s99, s47, 0
	s_cmp_eq_u32 s74, vcc_hi
	s_cselect_b32 s99, s55, s99
	s_cselect_b32 s98, s54, s98
	s_add_u32 s98, s98, s92
	s_addc_u32 s99, s99, s93
	s_mov_b32 m0, s22
	s_nop 0
	global_load_lds_dwordx4 v154, s[98:99]
	s_mov_b32 m0, s23
	s_nop 0
	global_load_lds_dwordx4 v158, s[98:99]
	s_waitcnt vmcnt(8)
	s_waitcnt lgkmcnt(0)
	s_setprio 2
	s_barrier
	v_mfma_f32_16x16x32_bf16 v[62:65], v[130:133], v[190:193], v[62:65]
	v_mfma_f32_16x16x32_bf16 v[58:61], v[138:141], v[190:193], v[58:61]
	v_mfma_f32_16x16x32_bf16 v[46:49], v[130:133], v[206:209], v[46:49]
	v_mfma_f32_16x16x32_bf16 v[42:45], v[138:141], v[206:209], v[42:45]
	v_mfma_f32_16x16x32_bf16 v[30:33], v[130:133], v[214:217], v[30:33]
	v_mfma_f32_16x16x32_bf16 v[26:29], v[138:141], v[214:217], v[26:29]
	v_mfma_f32_16x16x32_bf16 v[14:17], v[130:133], v[222:225], v[14:17]
	v_mfma_f32_16x16x32_bf16 v[10:13], v[138:141], v[222:225], v[10:13]
	v_mfma_f32_16x16x32_bf16 v[62:65], v[134:137], v[194:197], v[62:65]
	v_mfma_f32_16x16x32_bf16 v[58:61], v[142:145], v[194:197], v[58:61]
	v_mfma_f32_16x16x32_bf16 v[46:49], v[134:137], v[210:213], v[46:49]
	v_mfma_f32_16x16x32_bf16 v[42:45], v[142:145], v[210:213], v[42:45]
	v_mfma_f32_16x16x32_bf16 v[30:33], v[134:137], v[218:221], v[30:33]
	v_mfma_f32_16x16x32_bf16 v[26:29], v[142:145], v[218:221], v[26:29]
	v_mfma_f32_16x16x32_bf16 v[14:17], v[134:137], v[226:229], v[14:17]
	v_mfma_f32_16x16x32_bf16 v[10:13], v[142:145], v[226:229], v[10:13]
	v_mfma_f32_16x16x32_bf16 v[54:57], v[146:149], v[190:193], v[54:57]
	v_mfma_f32_16x16x32_bf16 v[50:53], v[182:185], v[190:193], v[50:53]
	v_mfma_f32_16x16x32_bf16 v[38:41], v[146:149], v[206:209], v[38:41]
	v_mfma_f32_16x16x32_bf16 v[34:37], v[182:185], v[206:209], v[34:37]
	v_mfma_f32_16x16x32_bf16 v[22:25], v[146:149], v[214:217], v[22:25]
	v_mfma_f32_16x16x32_bf16 v[18:21], v[182:185], v[214:217], v[18:21]
	v_mfma_f32_16x16x32_bf16 v[6:9], v[146:149], v[222:225], v[6:9]
	v_mfma_f32_16x16x32_bf16 v[2:5], v[182:185], v[222:225], v[2:5]
	v_mfma_f32_16x16x32_bf16 v[54:57], v[150:153], v[194:197], v[54:57]
	v_mfma_f32_16x16x32_bf16 v[50:53], v[186:189], v[194:197], v[50:53]
	v_mfma_f32_16x16x32_bf16 v[38:41], v[150:153], v[210:213], v[38:41]
	v_mfma_f32_16x16x32_bf16 v[34:37], v[186:189], v[210:213], v[34:37]
	v_mfma_f32_16x16x32_bf16 v[22:25], v[150:153], v[218:221], v[22:25]
	v_mfma_f32_16x16x32_bf16 v[18:21], v[186:189], v[218:221], v[18:21]
	v_mfma_f32_16x16x32_bf16 v[6:9], v[150:153], v[226:229], v[6:9]
	v_mfma_f32_16x16x32_bf16 v[2:5], v[186:189], v[226:229], v[2:5]
	s_barrier
	s_setprio 1
	s_add_u32 s46, s46, 0x100
	s_addc_u32 s47, s47, 0
	s_add_u32 s13, s13, 0x100
	s_addc_u32 s24, s24, 0
	s_cmp_ge_u32 s78, s65
	s_mov_b32 s72, s78
	s_cbranch_scc0 .LBB0_398
.LBB0_399:
	s_setprio 0
	s_and_b64 vcc, exec, s[80:81]
	s_cbranch_vccz .LBB0_401
	s_barrier

; #define PG8_STAGE(bufoff, gbase, voff) do { _Pragma("unroll") for (int _i = 0; _i < 2; ++_i) \
;         __builtin_amdgcn_global_load_lds((const unsigned*)((const char*)(gbase) + (voff)[_i]), (PG8_LAS unsigned*)(lds + (bufoff) + ldsw + _i * 8192), 16, 0, 0); } while (0)
; #define PG8_LDA(dst, b, h) do { _Pragma("unroll") for (int m = 0; m < 4; ++m) _Pragma("unroll") for (int k = 0; k < 2; ++k) dst[m][k] = *(const PG8_LAS bf16x8*)(lds + PG8_SA(b, h) + aoff + m * 2048 + k * 1024); } while (0)
; #define PG8_LDB(dst, b, h) do { _Pragma("unroll") for (int n = 0; n < 2; ++n) _Pragma("unroll") for (int k = 0; k < 2; ++k) dst[n][k] = *(const PG8_LAS bf16x8*)(lds + PG8_SB(b, h) + boff + n * 2048 + k * 1024); } while (0)
; #define PG8_WAIT_V(n) asm volatile("s_waitcnt vmcnt(" #n ")" ::: "memory")
; #define PG8_WAIT_L(n) asm volatile("s_waitcnt lgkmcnt(" #n ")" ::: "memory")
; #define PG8_BAR __builtin_amdgcn_s_barrier()
; #define PG8_SCHED __builtin_amdgcn_sched_barrier(0)
; template <class Epi, class Sched, bool ALIGN_EPI = false, bool SP2 = false, bool F16 = false>
; __device__ __forceinline__ void gemm_phase(PG8_LAS unsigned char* lds, const Gemm g, const Sched& S, const Epi& E) {
;     ...
;         for (int t = 0; t < nt; t += 2) {
;             const bool last = (t == nt - 2);
;             const char* a1 = cA + (size_t)(t + 1) * kstep;
;             const char* a2 = last ? nA : cA + (size_t)(t + 2) * kstep; const char* b2 = last ? nB : cB + (size_t)(t + 2) * kstep;
;             const char* a3 = a2 + kstep; const char* b3 = b2 + kstep;
;             if (last && has_next) S.a_ready(nxt);
;             if constexpr (SP2) {
;             PG8_LDB(B0, 0, 0); PG8_LDB(B1, 0, 1); PG8_SCHED; PG8_LDA(At, 0, 0); PG8_STAGE(PG8_SA(1, 1), a1 + hstepA, voffA);
;             PG8_WAIT_V(8); PG8_WAIT_L(0); PG8_BAR; PG8_MMA(0, 0, At, B0); PG8_MMA(0, 1, At, B1); PG8_BAR; PG8_SCHED;
;             PG8_LDA(At, 0, 1); PG8_STAGE(PG8_SB(0, 0), b2, voffB); PG8_STAGE(PG8_SB(0, 1), b2 + hstepB, voffB); PG8_STAGE(PG8_SA(0, 0), a2, voffA);
;             PG8_WAIT_V(8); PG8_WAIT_L(0); PG8_BAR; PG8_MMA(1, 0, At, B0); PG8_MMA(1, 1, At, B1); PG8_BAR; PG8_SCHED;
.Lpk_bh:
	s_setprio 1
	s_add_i32 s73, s52, 2
	s_add_u32 s82, s44, 0x80
	s_addc_u32 s53, s45, 0
	s_add_i32 s94, 0, 0x10000
	s_cmp_eq_u32 s74, s52
	s_cselect_b32 s53, s79, s53
	s_cselect_b32 s52, s78, s82
	s_cselect_b32 s83, s55, s72
	s_cselect_b32 s82, s54, s24
	s_add_i32 s95, 0, 0x14000
	ds_read_b128 v[130:133], v155
	ds_read_b128 v[134:137], v155 offset:1024
	ds_read_b128 v[138:141], v155 offset:2048
	ds_read_b128 v[142:145], v155 offset:3072
	ds_read_b128 v[146:149], v157
	ds_read_b128 v[150:153], v157 offset:1024
	ds_read_b128 v[182:185], v157 offset:2048
	ds_read_b128 v[186:189], v157 offset:3072
	s_add_i32 m0, s35, 0xc000
	ds_read_b128 v[190:193], v204
	ds_read_b128 v[194:197], v204 offset:1024
	ds_read_b128 v[206:209], v204 offset:2048
	ds_read_b128 v[210:213], v204 offset:3072
	ds_read_b128 v[214:217], v204 offset:4096
	ds_read_b128 v[218:221], v204 offset:5120
	ds_read_b128 v[222:225], v204 offset:6144
	ds_read_b128 v[226:229], v204 offset:7168
	global_load_lds_dwordx4 v168, s[44:45]
	s_add_i32 m0, s35, 0xe000
	s_nop 0
	global_load_lds_dwordx4 v170, s[44:45]
	s_waitcnt vmcnt(8)
	s_waitcnt lgkmcnt(0)
	s_setprio 2
	s_barrier
	v_mfma_f32_16x16x32_f16 v[122:125], v[130:133], v[190:193], 0
	v_mfma_f32_16x16x32_f16 v[126:129], v[138:141], v[190:193], 0
	v_mfma_f32_16x16x32_f16 v[110:113], v[130:133], v[206:209], 0
	v_mfma_f32_16x16x32_f16 v[106:109], v[138:141], v[206:209], 0
	v_mfma_f32_16x16x32_f16 v[94:97], v[130:133], v[214:217], 0
	v_mfma_f32_16x16x32_f16 v[90:93], v[138:141], v[214:217], 0
	v_mfma_f32_16x16x32_f16 v[78:81], v[130:133], v[222:225], 0
	v_mfma_f32_16x16x32_f16 v[74:77], v[138:141], v[222:225], 0
	v_mfma_f32_16x16x32_f16 v[122:125], v[134:137], v[194:197], v[122:125]
	v_mfma_f32_16x16x32_f16 v[126:129], v[142:145], v[194:197], v[126:129]
	v_mfma_f32_16x16x32_f16 v[110:113], v[134:137], v[210:213], v[110:113]
	v_mfma_f32_16x16x32_f16 v[106:109], v[142:145], v[210:213], v[106:109]
	v_mfma_f32_16x16x32_f16 v[94:97], v[134:137], v[218:221], v[94:97]
	v_mfma_f32_16x16x32_f16 v[90:93], v[142:145], v[218:221], v[90:93]
	v_mfma_f32_16x16x32_f16 v[78:81], v[134:137], v[226:229], v[78:81]
	v_mfma_f32_16x16x32_f16 v[74:77], v[142:145], v[226:229], v[74:77]
	v_mfma_f32_16x16x32_f16 v[118:121], v[146:149], v[190:193], 0
	v_mfma_f32_16x16x32_f16 v[114:117], v[182:185], v[190:193], 0
	v_mfma_f32_16x16x32_f16 v[102:105], v[146:149], v[206:209], 0
	v_mfma_f32_16x16x32_f16 v[98:101], v[182:185], v[206:209], 0
	v_mfma_f32_16x16x32_f16 v[86:89], v[146:149], v[214:217], 0
	v_mfma_f32_16x16x32_f16 v[82:85], v[182:185], v[214:217], 0
	v_mfma_f32_16x16x32_f16 v[70:73], v[146:149], v[222:225], 0
	v_mfma_f32_16x16x32_f16 v[66:69], v[182:185], v[222:225], 0
	v_mfma_f32_16x16x32_f16 v[118:121], v[150:153], v[194:197], v[118:121]
	v_mfma_f32_16x16x32_f16 v[114:117], v[186:189], v[194:197], v[114:117]
	v_mfma_f32_16x16x32_f16 v[102:105], v[150:153], v[210:213], v[102:105]
	v_mfma_f32_16x16x32_f16 v[98:101], v[186:189], v[210:213], v[98:101]
	v_mfma_f32_16x16x32_f16 v[86:89], v[150:153], v[218:221], v[86:89]
	v_mfma_f32_16x16x32_f16 v[82:85], v[186:189], v[218:221], v[82:85]
	v_mfma_f32_16x16x32_f16 v[70:73], v[150:153], v[226:229], v[70:73]
	v_mfma_f32_16x16x32_f16 v[66:69], v[186:189], v[226:229], v[66:69]
	s_barrier
	s_setprio 1
	s_add_i32 s94, s94, s75
	s_mov_b32 m0, s94
	s_nop 0
	global_load_lds_dwordx4 v156, s[82:83]
	ds_read_b128 v[190:193], v204 offset:16384
	ds_read_b128 v[194:197], v204 offset:17408
	ds_read_b128 v[206:209], v204 offset:18432
	ds_read_b128 v[210:213], v204 offset:19456
	ds_read_b128 v[214:217], v204 offset:20480
	ds_read_b128 v[218:221], v204 offset:21504
	ds_read_b128 v[222:225], v204 offset:22528
	ds_read_b128 v[226:229], v204 offset:23552
	s_add_i32 m0, s94, 0x2000
	s_nop 0
	global_load_lds_dwordx4 v160, s[82:83]
	s_add_i32 s94, s95, s75
	s_add_u32 s82, s82, s48
	s_addc_u32 s83, s83, 0
	s_mov_b32 m0, s94
	s_nop 0
	global_load_lds_dwordx4 v156, s[82:83]
	s_add_i32 m0, s94, 0x2000
	s_nop 0
	global_load_lds_dwordx4 v160, s[82:83]
	s_mov_b32 m0, s35
	s_nop 0
	global_load_lds_dwordx4 v154, s[52:53]
	s_mov_b32 m0, s2
	s_nop 0
	global_load_lds_dwordx4 v158, s[52:53]
	s_waitcnt vmcnt(8)
	s_waitcnt lgkmcnt(0)
	s_setprio 2
	s_barrier
	v_mfma_f32_16x16x32_f16 v[62:65], v[130:133], v[190:193], 0
	v_mfma_f32_16x16x32_f16 v[58:61], v[138:141], v[190:193], 0
	v_mfma_f32_16x16x32_f16 v[46:49], v[130:133], v[206:209], 0
	v_mfma_f32_16x16x32_f16 v[42:45], v[138:141], v[206:209], 0
	v_mfma_f32_16x16x32_f16 v[30:33], v[130:133], v[214:217], 0
	v_mfma_f32_16x16x32_f16 v[26:29], v[138:141], v[214:217], 0
	v_mfma_f32_16x16x32_f16 v[14:17], v[130:133], v[222:225], 0
	v_mfma_f32_16x16x32_f16 v[10:13], v[138:141], v[222:225], 0
	v_mfma_f32_16x16x32_f16 v[62:65], v[134:137], v[194:197], v[62:65]
	v_mfma_f32_16x16x32_f16 v[58:61], v[142:145], v[194:197], v[58:61]
	v_mfma_f32_16x16x32_f16 v[46:49], v[134:137], v[210:213], v[46:49]
	v_mfma_f32_16x16x32_f16 v[42:45], v[142:145], v[210:213], v[42:45]
	v_mfma_f32_16x16x32_f16 v[30:33], v[134:137], v[218:221], v[30:33]
	v_mfma_f32_16x16x32_f16 v[26:29], v[142:145], v[218:221], v[26:29]
	v_mfma_f32_16x16x32_f16 v[14:17], v[134:137], v[226:229], v[14:17]
	v_mfma_f32_16x16x32_f16 v[10:13], v[142:145], v[226:229], v[10:13]
	v_mfma_f32_16x16x32_f16 v[54:57], v[146:149], v[190:193], 0
	v_mfma_f32_16x16x32_f16 v[50:53], v[182:185], v[190:193], 0
	v_mfma_f32_16x16x32_f16 v[38:41], v[146:149], v[206:209], 0
	v_mfma_f32_16x16x32_f16 v[34:37], v[182:185], v[206:209], 0
	v_mfma_f32_16x16x32_f16 v[22:25], v[146:149], v[214:217], 0
	v_mfma_f32_16x16x32_f16 v[18:21], v[182:185], v[214:217], 0
	v_mfma_f32_16x16x32_f16 v[6:9], v[146:149], v[222:225], 0
	v_mfma_f32_16x16x32_f16 v[2:5], v[182:185], v[222:225], 0
	v_mfma_f32_16x16x32_f16 v[54:57], v[150:153], v[194:197], v[54:57]
	v_mfma_f32_16x16x32_f16 v[50:53], v[186:189], v[194:197], v[50:53]
	v_mfma_f32_16x16x32_f16 v[38:41], v[150:153], v[210:213], v[38:41]
	v_mfma_f32_16x16x32_f16 v[34:37], v[186:189], v[210:213], v[34:37]
	v_mfma_f32_16x16x32_f16 v[22:25], v[150:153], v[218:221], v[22:25]
	v_mfma_f32_16x16x32_f16 v[18:21], v[186:189], v[218:221], v[18:21]
	v_mfma_f32_16x16x32_f16 v[6:9], v[150:153], v[226:229], v[6:9]
	v_mfma_f32_16x16x32_f16 v[2:5], v[186:189], v[226:229], v[2:5]
	s_barrier
; #define PG8_STAGE(bufoff, gbase, voff) do { _Pragma("unroll") for (int _i = 0; _i < 2; ++_i) \
;         __builtin_amdgcn_global_load_lds((const unsigned*)((const char*)(gbase) + (voff)[_i]), (PG8_LAS unsigned*)(lds + (bufoff) + ldsw + _i * 8192), 16, 0, 0); } while (0)
; #define PG8_LDA(dst, b, h) do { _Pragma("unroll") for (int m = 0; m < 4; ++m) _Pragma("unroll") for (int k = 0; k < 2; ++k) dst[m][k] = *(const PG8_LAS bf16x8*)(lds + PG8_SA(b, h) + aoff + m * 2048 + k * 1024); } while (0)
; #define PG8_LDB(dst, b, h) do { _Pragma("unroll") for (int n = 0; n < 2; ++n) _Pragma("unroll") for (int k = 0; k < 2; ++k) dst[n][k] = *(const PG8_LAS bf16x8*)(lds + PG8_SB(b, h) + boff + n * 2048 + k * 1024); } while (0)
; #define PG8_WAIT_V(n) asm volatile("s_waitcnt vmcnt(" #n ")" ::: "memory")
; #define PG8_WAIT_L(n) asm volatile("s_waitcnt lgkmcnt(" #n ")" ::: "memory")
; #define PG8_BAR __builtin_amdgcn_s_barrier()
; #define PG8_SCHED __builtin_amdgcn_sched_barrier(0)
; template <class Epi, class Sched, bool ALIGN_EPI = false, bool SP2 = false, bool F16 = false>
; __device__ __forceinline__ void gemm_phase(PG8_LAS unsigned char* lds, const Gemm g, const Sched& S, const Epi& E) {
;     ...
;             PG8_LDB(B0, 1, 0); PG8_LDB(B1, 1, 1); PG8_SCHED; PG8_LDA(At, 1, 0); PG8_STAGE(PG8_SA(0, 1), a2 + hstepA, voffA);
;             PG8_WAIT_V(8); PG8_WAIT_L(0); PG8_BAR; PG8_MMA(0, 0, At, B0); PG8_MMA(0, 1, At, B1); PG8_BAR; PG8_SCHED;
;             PG8_LDA(At, 1, 1); PG8_STAGE(PG8_SB(1, 0), b3, voffB); PG8_STAGE(PG8_SB(1, 1), b3 + hstepB, voffB); PG8_STAGE(PG8_SA(1, 0), a3, voffA);
;             PG8_WAIT_V(8); PG8_WAIT_L(0); PG8_BAR; PG8_MMA(1, 0, At, B0); PG8_MMA(1, 1, At, B1); PG8_BAR; PG8_SCHED;
	s_setprio 1
	s_add_i32 s82, 0, 0x18000
	s_add_i32 s83, 0, 0x1c000
	ds_read_b128 v[130:133], v159
	ds_read_b128 v[134:137], v159 offset:1024
	ds_read_b128 v[138:141], v159 offset:2048
	ds_read_b128 v[142:145], v159 offset:3072
	ds_read_b128 v[146:149], v161
	ds_read_b128 v[150:153], v161 offset:1024
	ds_read_b128 v[182:185], v161 offset:2048
	ds_read_b128 v[186:189], v161 offset:3072
	s_add_u32 s52, s52, s8
	s_addc_u32 s53, s53, 0
	s_mov_b32 m0, s22
	ds_read_b128 v[190:193], v204 offset:32768
	ds_read_b128 v[194:197], v204 offset:33792
	ds_read_b128 v[206:209], v204 offset:34816
	ds_read_b128 v[210:213], v204 offset:35840
	ds_read_b128 v[214:217], v204 offset:36864
	ds_read_b128 v[218:221], v204 offset:37888
	ds_read_b128 v[222:225], v204 offset:38912
	ds_read_b128 v[226:229], v204 offset:39936
	global_load_lds_dwordx4 v154, s[52:53]
	s_mov_b32 m0, s23
	s_nop 0
	global_load_lds_dwordx4 v158, s[52:53]
	s_waitcnt vmcnt(8)
	s_waitcnt lgkmcnt(0)
	s_setprio 2
	s_barrier
	v_mfma_f32_16x16x32_f16 v[122:125], v[130:133], v[190:193], v[122:125]
	v_mfma_f32_16x16x32_f16 v[126:129], v[138:141], v[190:193], v[126:129]
	v_mfma_f32_16x16x32_f16 v[110:113], v[130:133], v[206:209], v[110:113]
	v_mfma_f32_16x16x32_f16 v[106:109], v[138:141], v[206:209], v[106:109]
	v_mfma_f32_16x16x32_f16 v[94:97], v[130:133], v[214:217], v[94:97]
	v_mfma_f32_16x16x32_f16 v[90:93], v[138:141], v[214:217], v[90:93]
	v_mfma_f32_16x16x32_f16 v[78:81], v[130:133], v[222:225], v[78:81]
	v_mfma_f32_16x16x32_f16 v[74:77], v[138:141], v[222:225], v[74:77]
	v_mfma_f32_16x16x32_f16 v[122:125], v[134:137], v[194:197], v[122:125]
	v_mfma_f32_16x16x32_f16 v[126:129], v[142:145], v[194:197], v[126:129]
	v_mfma_f32_16x16x32_f16 v[110:113], v[134:137], v[210:213], v[110:113]
	v_mfma_f32_16x16x32_f16 v[106:109], v[142:145], v[210:213], v[106:109]
	v_mfma_f32_16x16x32_f16 v[94:97], v[134:137], v[218:221], v[94:97]
	v_mfma_f32_16x16x32_f16 v[90:93], v[142:145], v[218:221], v[90:93]
	v_mfma_f32_16x16x32_f16 v[78:81], v[134:137], v[226:229], v[78:81]
	v_mfma_f32_16x16x32_f16 v[74:77], v[142:145], v[226:229], v[74:77]
	v_mfma_f32_16x16x32_f16 v[118:121], v[146:149], v[190:193], v[118:121]
	v_mfma_f32_16x16x32_f16 v[114:117], v[182:185], v[190:193], v[114:117]
	v_mfma_f32_16x16x32_f16 v[102:105], v[146:149], v[206:209], v[102:105]
	v_mfma_f32_16x16x32_f16 v[98:101], v[182:185], v[206:209], v[98:101]
	v_mfma_f32_16x16x32_f16 v[86:89], v[146:149], v[214:217], v[86:89]
	v_mfma_f32_16x16x32_f16 v[82:85], v[182:185], v[214:217], v[82:85]
	v_mfma_f32_16x16x32_f16 v[70:73], v[146:149], v[222:225], v[70:73]
	v_mfma_f32_16x16x32_f16 v[66:69], v[182:185], v[222:225], v[66:69]
	v_mfma_f32_16x16x32_f16 v[118:121], v[150:153], v[194:197], v[118:121]
	v_mfma_f32_16x16x32_f16 v[114:117], v[186:189], v[194:197], v[114:117]
	v_mfma_f32_16x16x32_f16 v[102:105], v[150:153], v[210:213], v[102:105]
	v_mfma_f32_16x16x32_f16 v[98:101], v[186:189], v[210:213], v[98:101]
	v_mfma_f32_16x16x32_f16 v[86:89], v[150:153], v[218:221], v[86:89]
	v_mfma_f32_16x16x32_f16 v[82:85], v[186:189], v[218:221], v[82:85]
	v_mfma_f32_16x16x32_f16 v[70:73], v[150:153], v[226:229], v[70:73]
	v_mfma_f32_16x16x32_f16 v[66:69], v[186:189], v[226:229], v[66:69]
	s_barrier
	s_setprio 1
	s_add_i32 s52, s82, s75
	s_add_i32 vcc_hi, s73, -2
	s_cmp_eq_u32 s74, vcc_hi
	s_cselect_b32 s99, s55, s72
	s_cselect_b32 s98, s54, s24
	s_add_u32 s98, s98, s92
	s_addc_u32 s99, s99, s93
	s_mov_b32 m0, s52
	s_nop 0
	global_load_lds_dwordx4 v156, s[98:99]
	ds_read_b128 v[190:193], v204 offset:49152
	ds_read_b128 v[194:197], v204 offset:50176
	ds_read_b128 v[206:209], v204 offset:51200
	ds_read_b128 v[210:213], v204 offset:52224
	ds_read_b128 v[214:217], v204 offset:53248
	ds_read_b128 v[218:221], v204 offset:54272
	ds_read_b128 v[222:225], v204 offset:55296
	ds_read_b128 v[226:229], v204 offset:56320
	s_add_i32 m0, s52, 0x2000
	s_nop 0
	global_load_lds_dwordx4 v160, s[98:99]
	s_add_i32 s52, s83, s75
	s_add_u32 s98, s98, s48
	s_addc_u32 s99, s99, 0
	s_mov_b32 m0, s52
	s_nop 0
	global_load_lds_dwordx4 v156, s[98:99]
	s_add_i32 m0, s52, 0x2000
	s_nop 0
	global_load_lds_dwordx4 v160, s[98:99]
	s_add_u32 s98, s44, 0x80
	s_addc_u32 s99, s45, 0
	s_cmp_eq_u32 s74, vcc_hi
	s_cselect_b32 s99, s79, s99
	s_cselect_b32 s98, s78, s98
	s_add_u32 s98, s98, s92
	s_addc_u32 s99, s99, s93
	s_mov_b32 m0, s61
	s_nop 0
	global_load_lds_dwordx4 v154, s[98:99]
	s_mov_b32 m0, s18
	s_nop 0
	global_load_lds_dwordx4 v158, s[98:99]
	s_waitcnt vmcnt(8)
	s_waitcnt lgkmcnt(0)
	s_setprio 2
	s_barrier
	v_mfma_f32_16x16x32_f16 v[62:65], v[130:133], v[190:193], v[62:65]
	v_mfma_f32_16x16x32_f16 v[58:61], v[138:141], v[190:193], v[58:61]
	v_mfma_f32_16x16x32_f16 v[46:49], v[130:133], v[206:209], v[46:49]
	v_mfma_f32_16x16x32_f16 v[42:45], v[138:141], v[206:209], v[42:45]
	v_mfma_f32_16x16x32_f16 v[30:33], v[130:133], v[214:217], v[30:33]
	v_mfma_f32_16x16x32_f16 v[26:29], v[138:141], v[214:217], v[26:29]
	v_mfma_f32_16x16x32_f16 v[14:17], v[130:133], v[222:225], v[14:17]
	v_mfma_f32_16x16x32_f16 v[10:13], v[138:141], v[222:225], v[10:13]
	v_mfma_f32_16x16x32_f16 v[62:65], v[134:137], v[194:197], v[62:65]
	v_mfma_f32_16x16x32_f16 v[58:61], v[142:145], v[194:197], v[58:61]
	v_mfma_f32_16x16x32_f16 v[46:49], v[134:137], v[210:213], v[46:49]
	v_mfma_f32_16x16x32_f16 v[42:45], v[142:145], v[210:213], v[42:45]
	v_mfma_f32_16x16x32_f16 v[30:33], v[134:137], v[218:221], v[30:33]
	v_mfma_f32_16x16x32_f16 v[26:29], v[142:145], v[218:221], v[26:29]
	v_mfma_f32_16x16x32_f16 v[14:17], v[134:137], v[226:229], v[14:17]
	v_mfma_f32_16x16x32_f16 v[10:13], v[142:145], v[226:229], v[10:13]
	v_mfma_f32_16x16x32_f16 v[54:57], v[146:149], v[190:193], v[54:57]
	v_mfma_f32_16x16x32_f16 v[50:53], v[182:185], v[190:193], v[50:53]
	v_mfma_f32_16x16x32_f16 v[38:41], v[146:149], v[206:209], v[38:41]
	v_mfma_f32_16x16x32_f16 v[34:37], v[182:185], v[206:209], v[34:37]
	v_mfma_f32_16x16x32_f16 v[22:25], v[146:149], v[214:217], v[22:25]
	v_mfma_f32_16x16x32_f16 v[18:21], v[182:185], v[214:217], v[18:21]
	v_mfma_f32_16x16x32_f16 v[6:9], v[146:149], v[222:225], v[6:9]
	v_mfma_f32_16x16x32_f16 v[2:5], v[182:185], v[222:225], v[2:5]
	v_mfma_f32_16x16x32_f16 v[54:57], v[150:153], v[194:197], v[54:57]
	v_mfma_f32_16x16x32_f16 v[50:53], v[186:189], v[194:197], v[50:53]
	v_mfma_f32_16x16x32_f16 v[38:41], v[150:153], v[210:213], v[38:41]
	v_mfma_f32_16x16x32_f16 v[34:37], v[186:189], v[210:213], v[34:37]
	v_mfma_f32_16x16x32_f16 v[22:25], v[150:153], v[218:221], v[22:25]
	v_mfma_f32_16x16x32_f16 v[18:21], v[186:189], v[218:221], v[18:21]
	v_mfma_f32_16x16x32_f16 v[6:9], v[150:153], v[226:229], v[6:9]
	v_mfma_f32_16x16x32_f16 v[2:5], v[186:189], v[226:229], v[2:5]
	s_barrier
	s_setprio 1
	s_add_u32 s44, s44, 0x100
	s_addc_u32 s45, s45, 0
	s_add_u32 s24, s24, 0x100
	s_addc_u32 s72, s72, 0
	s_cmp_ge_u32 s73, s65
	s_mov_b32 s52, s73
	s_cbranch_scc1 .LBB0_565
; #define PG8_STAGE(bufoff, gbase, voff) do { _Pragma("unroll") for (int _i = 0; _i < 2; ++_i) \
;         __builtin_amdgcn_global_load_lds((const unsigned*)((const char*)(gbase) + (voff)[_i]), (PG8_LAS unsigned*)(lds + (bufoff) + ldsw + _i * 8192), 16, 0, 0); } while (0)
; #define PG8_LDA(dst, b, h) do { _Pragma("unroll") for (int m = 0; m < 4; ++m) _Pragma("unroll") for (int k = 0; k < 2; ++k) dst[m][k] = *(const PG8_LAS bf16x8*)(lds + PG8_SA(b, h) + aoff + m * 2048 + k * 1024); } while (0)
; #define PG8_LDB(dst, b, h) do { _Pragma("unroll") for (int n = 0; n < 2; ++n) _Pragma("unroll") for (int k = 0; k < 2; ++k) dst[n][k] = *(const PG8_LAS bf16x8*)(lds + PG8_SB(b, h) + boff + n * 2048 + k * 1024); } while (0)
; #define PG8_WAIT_V(n) asm volatile("s_waitcnt vmcnt(" #n ")" ::: "memory")
; #define PG8_WAIT_L(n) asm volatile("s_waitcnt lgkmcnt(" #n ")" ::: "memory")
; #define PG8_BAR __builtin_amdgcn_s_barrier()
; #define PG8_SCHED __builtin_amdgcn_sched_barrier(0)
; template <class Epi, class Sched, bool ALIGN_EPI = false, bool SP2 = false, bool F16 = false>
; __device__ __forceinline__ void gemm_phase(PG8_LAS unsigned char* lds, const Gemm g, const Sched& S, const Epi& E) {
;     ...
;         for (int t = 0; t < nt; t += 2) {
;             const bool last = (t == nt - 2);
;             const char* a1 = cA + (size_t)(t + 1) * kstep;
;             const char* a2 = last ? nA : cA + (size_t)(t + 2) * kstep; const char* b2 = last ? nB : cB + (size_t)(t + 2) * kstep;
;             const char* a3 = a2 + kstep; const char* b3 = b2 + kstep;
;             if (last && has_next) S.a_ready(nxt);
;             if constexpr (SP2) {
;             PG8_LDB(B0, 0, 0); PG8_LDB(B1, 0, 1); PG8_SCHED; PG8_LDA(At, 0, 0); PG8_STAGE(PG8_SA(1, 1), a1 + hstepA, voffA);
;             PG8_WAIT_V(8); PG8_WAIT_L(0); PG8_BAR; PG8_MMA(0, 0, At, B0); PG8_MMA(0, 1, At, B1); PG8_BAR; PG8_SCHED;
;             PG8_LDA(At, 0, 1); PG8_STAGE(PG8_SB(0, 0), b2, voffB); PG8_STAGE(PG8_SB(0, 1), b2 + hstepB, voffB); PG8_STAGE(PG8_SA(0, 0), a2, voffA);
;             PG8_WAIT_V(8); PG8_WAIT_L(0); PG8_BAR; PG8_MMA(1, 0, At, B0); PG8_MMA(1, 1, At, B1); PG8_BAR; PG8_SCHED;
.LBB0_564:
	s_add_i32 s73, s52, 2
	s_add_u32 s82, s44, 0x80
	s_addc_u32 s53, s45, 0
	s_add_i32 s94, 0, 0x10000
	s_cmp_eq_u32 s74, s52
	s_cselect_b32 s53, s79, s53
	s_cselect_b32 s52, s78, s82
	s_cselect_b32 s83, s55, s72
	s_cselect_b32 s82, s54, s24
	s_add_i32 s95, 0, 0x14000
	ds_read_b128 v[130:133], v155
	ds_read_b128 v[134:137], v155 offset:1024
	ds_read_b128 v[138:141], v155 offset:2048
	ds_read_b128 v[142:145], v155 offset:3072
	ds_read_b128 v[146:149], v157
	ds_read_b128 v[150:153], v157 offset:1024
	ds_read_b128 v[182:185], v157 offset:2048
	ds_read_b128 v[186:189], v157 offset:3072
	s_add_i32 m0, s35, 0xc000
	ds_read_b128 v[190:193], v204
	ds_read_b128 v[194:197], v204 offset:1024
	ds_read_b128 v[206:209], v204 offset:2048
	ds_read_b128 v[210:213], v204 offset:3072
	ds_read_b128 v[214:217], v204 offset:4096
	ds_read_b128 v[218:221], v204 offset:5120
	ds_read_b128 v[222:225], v204 offset:6144
	ds_read_b128 v[226:229], v204 offset:7168
	global_load_lds_dwordx4 v168, s[44:45]
	s_add_i32 m0, s35, 0xe000
	s_nop 0
	global_load_lds_dwordx4 v170, s[44:45]
	s_waitcnt vmcnt(8)
	s_waitcnt lgkmcnt(0)
	s_setprio 2
	s_barrier
	v_mfma_f32_16x16x32_f16 v[122:125], v[130:133], v[190:193], v[122:125]
	v_mfma_f32_16x16x32_f16 v[126:129], v[138:141], v[190:193], v[126:129]
	v_mfma_f32_16x16x32_f16 v[110:113], v[130:133], v[206:209], v[110:113]
	v_mfma_f32_16x16x32_f16 v[106:109], v[138:141], v[206:209], v[106:109]
	v_mfma_f32_16x16x32_f16 v[94:97], v[130:133], v[214:217], v[94:97]
	v_mfma_f32_16x16x32_f16 v[90:93], v[138:141], v[214:217], v[90:93]
	v_mfma_f32_16x16x32_f16 v[78:81], v[130:133], v[222:225], v[78:81]
	v_mfma_f32_16x16x32_f16 v[74:77], v[138:141], v[222:225], v[74:77]
	v_mfma_f32_16x16x32_f16 v[122:125], v[134:137], v[194:197], v[122:125]
	v_mfma_f32_16x16x32_f16 v[126:129], v[142:145], v[194:197], v[126:129]
	v_mfma_f32_16x16x32_f16 v[110:113], v[134:137], v[210:213], v[110:113]
	v_mfma_f32_16x16x32_f16 v[106:109], v[142:145], v[210:213], v[106:109]
	v_mfma_f32_16x16x32_f16 v[94:97], v[134:137], v[218:221], v[94:97]
	v_mfma_f32_16x16x32_f16 v[90:93], v[142:145], v[218:221], v[90:93]
	v_mfma_f32_16x16x32_f16 v[78:81], v[134:137], v[226:229], v[78:81]
	v_mfma_f32_16x16x32_f16 v[74:77], v[142:145], v[226:229], v[74:77]
	v_mfma_f32_16x16x32_f16 v[118:121], v[146:149], v[190:193], v[118:121]
	v_mfma_f32_16x16x32_f16 v[114:117], v[182:185], v[190:193], v[114:117]
	v_mfma_f32_16x16x32_f16 v[102:105], v[146:149], v[206:209], v[102:105]
	v_mfma_f32_16x16x32_f16 v[98:101], v[182:185], v[206:209], v[98:101]
	v_mfma_f32_16x16x32_f16 v[86:89], v[146:149], v[214:217], v[86:89]
	v_mfma_f32_16x16x32_f16 v[82:85], v[182:185], v[214:217], v[82:85]
	v_mfma_f32_16x16x32_f16 v[70:73], v[146:149], v[222:225], v[70:73]
	v_mfma_f32_16x16x32_f16 v[66:69], v[182:185], v[222:225], v[66:69]
	v_mfma_f32_16x16x32_f16 v[118:121], v[150:153], v[194:197], v[118:121]
	v_mfma_f32_16x16x32_f16 v[114:117], v[186:189], v[194:197], v[114:117]
	v_mfma_f32_16x16x32_f16 v[102:105], v[150:153], v[210:213], v[102:105]
	v_mfma_f32_16x16x32_f16 v[98:101], v[186:189], v[210:213], v[98:101]
	v_mfma_f32_16x16x32_f16 v[86:89], v[150:153], v[218:221], v[86:89]
	v_mfma_f32_16x16x32_f16 v[82:85], v[186:189], v[218:221], v[82:85]
	v_mfma_f32_16x16x32_f16 v[70:73], v[150:153], v[226:229], v[70:73]
	v_mfma_f32_16x16x32_f16 v[66:69], v[186:189], v[226:229], v[66:69]
	s_barrier
	s_setprio 1
	s_add_i32 s94, s94, s75
	s_mov_b32 m0, s94
	s_nop 0
	global_load_lds_dwordx4 v156, s[82:83]
	ds_read_b128 v[190:193], v204 offset:16384
	ds_read_b128 v[194:197], v204 offset:17408
	ds_read_b128 v[206:209], v204 offset:18432
	ds_read_b128 v[210:213], v204 offset:19456
	ds_read_b128 v[214:217], v204 offset:20480
	ds_read_b128 v[218:221], v204 offset:21504
	ds_read_b128 v[222:225], v204 offset:22528
	ds_read_b128 v[226:229], v204 offset:23552
	s_add_i32 m0, s94, 0x2000
	s_nop 0
	global_load_lds_dwordx4 v160, s[82:83]
	s_add_i32 s94, s95, s75
	s_add_u32 s82, s82, s48
	s_addc_u32 s83, s83, 0
	s_mov_b32 m0, s94
	s_nop 0
	global_load_lds_dwordx4 v156, s[82:83]
	s_add_i32 m0, s94, 0x2000
	s_nop 0
	global_load_lds_dwordx4 v160, s[82:83]
	s_mov_b32 m0, s35
	s_nop 0
	global_load_lds_dwordx4 v154, s[52:53]
	s_mov_b32 m0, s2
	s_nop 0
	global_load_lds_dwordx4 v158, s[52:53]
	s_waitcnt vmcnt(8)
	s_waitcnt lgkmcnt(0)
	s_setprio 2
	s_barrier
	v_mfma_f32_16x16x32_f16 v[62:65], v[130:133], v[190:193], v[62:65]
	v_mfma_f32_16x16x32_f16 v[58:61], v[138:141], v[190:193], v[58:61]
	v_mfma_f32_16x16x32_f16 v[46:49], v[130:133], v[206:209], v[46:49]
	v_mfma_f32_16x16x32_f16 v[42:45], v[138:141], v[206:209], v[42:45]
	v_mfma_f32_16x16x32_f16 v[30:33], v[130:133], v[214:217], v[30:33]
	v_mfma_f32_16x16x32_f16 v[26:29], v[138:141], v[214:217], v[26:29]
	v_mfma_f32_16x16x32_f16 v[14:17], v[130:133], v[222:225], v[14:17]
	v_mfma_f32_16x16x32_f16 v[10:13], v[138:141], v[222:225], v[10:13]
	v_mfma_f32_16x16x32_f16 v[62:65], v[134:137], v[194:197], v[62:65]
	v_mfma_f32_16x16x32_f16 v[58:61], v[142:145], v[194:197], v[58:61]
	v_mfma_f32_16x16x32_f16 v[46:49], v[134:137], v[210:213], v[46:49]
	v_mfma_f32_16x16x32_f16 v[42:45], v[142:145], v[210:213], v[42:45]
	v_mfma_f32_16x16x32_f16 v[30:33], v[134:137], v[218:221], v[30:33]
	v_mfma_f32_16x16x32_f16 v[26:29], v[142:145], v[218:221], v[26:29]
	v_mfma_f32_16x16x32_f16 v[14:17], v[134:137], v[226:229], v[14:17]
	v_mfma_f32_16x16x32_f16 v[10:13], v[142:145], v[226:229], v[10:13]
	v_mfma_f32_16x16x32_f16 v[54:57], v[146:149], v[190:193], v[54:57]
	v_mfma_f32_16x16x32_f16 v[50:53], v[182:185], v[190:193], v[50:53]
	v_mfma_f32_16x16x32_f16 v[38:41], v[146:149], v[206:209], v[38:41]
	v_mfma_f32_16x16x32_f16 v[34:37], v[182:185], v[206:209], v[34:37]
	v_mfma_f32_16x16x32_f16 v[22:25], v[146:149], v[214:217], v[22:25]
	v_mfma_f32_16x16x32_f16 v[18:21], v[182:185], v[214:217], v[18:21]
	v_mfma_f32_16x16x32_f16 v[6:9], v[146:149], v[222:225], v[6:9]
	v_mfma_f32_16x16x32_f16 v[2:5], v[182:185], v[222:225], v[2:5]
	v_mfma_f32_16x16x32_f16 v[54:57], v[150:153], v[194:197], v[54:57]
	v_mfma_f32_16x16x32_f16 v[50:53], v[186:189], v[194:197], v[50:53]
	v_mfma_f32_16x16x32_f16 v[38:41], v[150:153], v[210:213], v[38:41]
	v_mfma_f32_16x16x32_f16 v[34:37], v[186:189], v[210:213], v[34:37]
	v_mfma_f32_16x16x32_f16 v[22:25], v[150:153], v[218:221], v[22:25]
	v_mfma_f32_16x16x32_f16 v[18:21], v[186:189], v[218:221], v[18:21]
	v_mfma_f32_16x16x32_f16 v[6:9], v[150:153], v[226:229], v[6:9]
	v_mfma_f32_16x16x32_f16 v[2:5], v[186:189], v[226:229], v[2:5]
	s_barrier
; #define PG8_STAGE(bufoff, gbase, voff) do { _Pragma("unroll") for (int _i = 0; _i < 2; ++_i) \
;         __builtin_amdgcn_global_load_lds((const unsigned*)((const char*)(gbase) + (voff)[_i]), (PG8_LAS unsigned*)(lds + (bufoff) + ldsw + _i * 8192), 16, 0, 0); } while (0)
; #define PG8_LDA(dst, b, h) do { _Pragma("unroll") for (int m = 0; m < 4; ++m) _Pragma("unroll") for (int k = 0; k < 2; ++k) dst[m][k] = *(const PG8_LAS bf16x8*)(lds + PG8_SA(b, h) + aoff + m * 2048 + k * 1024); } while (0)
; #define PG8_LDB(dst, b, h) do { _Pragma("unroll") for (int n = 0; n < 2; ++n) _Pragma("unroll") for (int k = 0; k < 2; ++k) dst[n][k] = *(const PG8_LAS bf16x8*)(lds + PG8_SB(b, h) + boff + n * 2048 + k * 1024); } while (0)
; #define PG8_WAIT_V(n) asm volatile("s_waitcnt vmcnt(" #n ")" ::: "memory")
; #define PG8_WAIT_L(n) asm volatile("s_waitcnt lgkmcnt(" #n ")" ::: "memory")
; #define PG8_BAR __builtin_amdgcn_s_barrier()
; #define PG8_SCHED __builtin_amdgcn_sched_barrier(0)
; template <class Epi, class Sched, bool ALIGN_EPI = false, bool SP2 = false, bool F16 = false>
; __device__ __forceinline__ void gemm_phase(PG8_LAS unsigned char* lds, const Gemm g, const Sched& S, const Epi& E) {
;     ...
;             PG8_LDB(B0, 1, 0); PG8_LDB(B1, 1, 1); PG8_SCHED; PG8_LDA(At, 1, 0); PG8_STAGE(PG8_SA(0, 1), a2 + hstepA, voffA);
;             PG8_WAIT_V(8); PG8_WAIT_L(0); PG8_BAR; PG8_MMA(0, 0, At, B0); PG8_MMA(0, 1, At, B1); PG8_BAR; PG8_SCHED;
;             PG8_LDA(At, 1, 1); PG8_STAGE(PG8_SB(1, 0), b3, voffB); PG8_STAGE(PG8_SB(1, 1), b3 + hstepB, voffB); PG8_STAGE(PG8_SA(1, 0), a3, voffA);
;             PG8_WAIT_V(8); PG8_WAIT_L(0); PG8_BAR; PG8_MMA(1, 0, At, B0); PG8_MMA(1, 1, At, B1); PG8_BAR; PG8_SCHED;
;     ...
;         if constexpr (ALIGN_EPI) { if (wr == 0) PG8_BAR; }
	s_setprio 1
	s_add_i32 s82, 0, 0x18000
	s_add_i32 s83, 0, 0x1c000
	ds_read_b128 v[130:133], v159
	ds_read_b128 v[134:137], v159 offset:1024
	ds_read_b128 v[138:141], v159 offset:2048
	ds_read_b128 v[142:145], v159 offset:3072
	ds_read_b128 v[146:149], v161
	ds_read_b128 v[150:153], v161 offset:1024
	ds_read_b128 v[182:185], v161 offset:2048
	ds_read_b128 v[186:189], v161 offset:3072
	s_add_u32 s52, s52, s8
	s_addc_u32 s53, s53, 0
	s_mov_b32 m0, s22
	ds_read_b128 v[190:193], v204 offset:32768
	ds_read_b128 v[194:197], v204 offset:33792
	ds_read_b128 v[206:209], v204 offset:34816
	ds_read_b128 v[210:213], v204 offset:35840
	ds_read_b128 v[214:217], v204 offset:36864
	ds_read_b128 v[218:221], v204 offset:37888
	ds_read_b128 v[222:225], v204 offset:38912
	ds_read_b128 v[226:229], v204 offset:39936
	global_load_lds_dwordx4 v154, s[52:53]
	s_mov_b32 m0, s23
	s_nop 0
	global_load_lds_dwordx4 v158, s[52:53]
	s_waitcnt vmcnt(8)
	s_waitcnt lgkmcnt(0)
	s_setprio 2
	s_barrier
	v_mfma_f32_16x16x32_f16 v[122:125], v[130:133], v[190:193], v[122:125]
	v_mfma_f32_16x16x32_f16 v[126:129], v[138:141], v[190:193], v[126:129]
	v_mfma_f32_16x16x32_f16 v[110:113], v[130:133], v[206:209], v[110:113]
	v_mfma_f32_16x16x32_f16 v[106:109], v[138:141], v[206:209], v[106:109]
	v_mfma_f32_16x16x32_f16 v[94:97], v[130:133], v[214:217], v[94:97]
	v_mfma_f32_16x16x32_f16 v[90:93], v[138:141], v[214:217], v[90:93]
	v_mfma_f32_16x16x32_f16 v[78:81], v[130:133], v[222:225], v[78:81]
	v_mfma_f32_16x16x32_f16 v[74:77], v[138:141], v[222:225], v[74:77]
	v_mfma_f32_16x16x32_f16 v[122:125], v[134:137], v[194:197], v[122:125]
	v_mfma_f32_16x16x32_f16 v[126:129], v[142:145], v[194:197], v[126:129]
	v_mfma_f32_16x16x32_f16 v[110:113], v[134:137], v[210:213], v[110:113]
	v_mfma_f32_16x16x32_f16 v[106:109], v[142:145], v[210:213], v[106:109]
	v_mfma_f32_16x16x32_f16 v[94:97], v[134:137], v[218:221], v[94:97]
	v_mfma_f32_16x16x32_f16 v[90:93], v[142:145], v[218:221], v[90:93]
	v_mfma_f32_16x16x32_f16 v[78:81], v[134:137], v[226:229], v[78:81]
	v_mfma_f32_16x16x32_f16 v[74:77], v[142:145], v[226:229], v[74:77]
	v_mfma_f32_16x16x32_f16 v[118:121], v[146:149], v[190:193], v[118:121]
	v_mfma_f32_16x16x32_f16 v[114:117], v[182:185], v[190:193], v[114:117]
	v_mfma_f32_16x16x32_f16 v[102:105], v[146:149], v[206:209], v[102:105]
	v_mfma_f32_16x16x32_f16 v[98:101], v[182:185], v[206:209], v[98:101]
	v_mfma_f32_16x16x32_f16 v[86:89], v[146:149], v[214:217], v[86:89]
	v_mfma_f32_16x16x32_f16 v[82:85], v[182:185], v[214:217], v[82:85]
	v_mfma_f32_16x16x32_f16 v[70:73], v[146:149], v[222:225], v[70:73]
	v_mfma_f32_16x16x32_f16 v[66:69], v[182:185], v[222:225], v[66:69]
	v_mfma_f32_16x16x32_f16 v[118:121], v[150:153], v[194:197], v[118:121]
	v_mfma_f32_16x16x32_f16 v[114:117], v[186:189], v[194:197], v[114:117]
	v_mfma_f32_16x16x32_f16 v[102:105], v[150:153], v[210:213], v[102:105]
	v_mfma_f32_16x16x32_f16 v[98:101], v[186:189], v[210:213], v[98:101]
	v_mfma_f32_16x16x32_f16 v[86:89], v[150:153], v[218:221], v[86:89]
	v_mfma_f32_16x16x32_f16 v[82:85], v[186:189], v[218:221], v[82:85]
	v_mfma_f32_16x16x32_f16 v[70:73], v[150:153], v[226:229], v[70:73]
	v_mfma_f32_16x16x32_f16 v[66:69], v[186:189], v[226:229], v[66:69]
	s_barrier
	s_setprio 1
	s_add_i32 s52, s82, s75
	s_add_i32 vcc_hi, s73, -2
	s_cmp_eq_u32 s74, vcc_hi
	s_cselect_b32 s99, s55, s72
	s_cselect_b32 s98, s54, s24
	s_add_u32 s98, s98, s92
	s_addc_u32 s99, s99, s93
	s_mov_b32 m0, s52
	s_nop 0
	global_load_lds_dwordx4 v156, s[98:99]
	ds_read_b128 v[190:193], v204 offset:49152
	ds_read_b128 v[194:197], v204 offset:50176
	ds_read_b128 v[206:209], v204 offset:51200
	ds_read_b128 v[210:213], v204 offset:52224
	ds_read_b128 v[214:217], v204 offset:53248
	ds_read_b128 v[218:221], v204 offset:54272
	ds_read_b128 v[222:225], v204 offset:55296
	ds_read_b128 v[226:229], v204 offset:56320
	s_add_i32 m0, s52, 0x2000
	s_nop 0
	global_load_lds_dwordx4 v160, s[98:99]
	s_add_i32 s52, s83, s75
	s_add_u32 s98, s98, s48
	s_addc_u32 s99, s99, 0
	s_mov_b32 m0, s52
	s_nop 0
	global_load_lds_dwordx4 v156, s[98:99]
	s_add_i32 m0, s52, 0x2000
	s_nop 0
	global_load_lds_dwordx4 v160, s[98:99]
	s_add_u32 s98, s44, 0x80
	s_addc_u32 s99, s45, 0
	s_cmp_eq_u32 s74, vcc_hi
	s_cselect_b32 s99, s79, s99
	s_cselect_b32 s98, s78, s98
	s_add_u32 s98, s98, s92
	s_addc_u32 s99, s99, s93
	s_mov_b32 m0, s61
	s_nop 0
	global_load_lds_dwordx4 v154, s[98:99]
	s_mov_b32 m0, s18
	s_nop 0
	global_load_lds_dwordx4 v158, s[98:99]
	s_waitcnt vmcnt(8)
	s_waitcnt lgkmcnt(0)
	s_setprio 2
	s_barrier
	v_mfma_f32_16x16x32_f16 v[62:65], v[130:133], v[190:193], v[62:65]
	v_mfma_f32_16x16x32_f16 v[58:61], v[138:141], v[190:193], v[58:61]
	v_mfma_f32_16x16x32_f16 v[46:49], v[130:133], v[206:209], v[46:49]
	v_mfma_f32_16x16x32_f16 v[42:45], v[138:141], v[206:209], v[42:45]
	v_mfma_f32_16x16x32_f16 v[30:33], v[130:133], v[214:217], v[30:33]
	v_mfma_f32_16x16x32_f16 v[26:29], v[138:141], v[214:217], v[26:29]
	v_mfma_f32_16x16x32_f16 v[14:17], v[130:133], v[222:225], v[14:17]
	v_mfma_f32_16x16x32_f16 v[10:13], v[138:141], v[222:225], v[10:13]
	v_mfma_f32_16x16x32_f16 v[62:65], v[134:137], v[194:197], v[62:65]
	v_mfma_f32_16x16x32_f16 v[58:61], v[142:145], v[194:197], v[58:61]
	v_mfma_f32_16x16x32_f16 v[46:49], v[134:137], v[210:213], v[46:49]
	v_mfma_f32_16x16x32_f16 v[42:45], v[142:145], v[210:213], v[42:45]
	v_mfma_f32_16x16x32_f16 v[30:33], v[134:137], v[218:221], v[30:33]
	v_mfma_f32_16x16x32_f16 v[26:29], v[142:145], v[218:221], v[26:29]
	v_mfma_f32_16x16x32_f16 v[14:17], v[134:137], v[226:229], v[14:17]
	v_mfma_f32_16x16x32_f16 v[10:13], v[142:145], v[226:229], v[10:13]
	v_mfma_f32_16x16x32_f16 v[54:57], v[146:149], v[190:193], v[54:57]
	v_mfma_f32_16x16x32_f16 v[50:53], v[182:185], v[190:193], v[50:53]
	v_mfma_f32_16x16x32_f16 v[38:41], v[146:149], v[206:209], v[38:41]
	v_mfma_f32_16x16x32_f16 v[34:37], v[182:185], v[206:209], v[34:37]
	v_mfma_f32_16x16x32_f16 v[22:25], v[146:149], v[214:217], v[22:25]
	v_mfma_f32_16x16x32_f16 v[18:21], v[182:185], v[214:217], v[18:21]
	v_mfma_f32_16x16x32_f16 v[6:9], v[146:149], v[222:225], v[6:9]
	v_mfma_f32_16x16x32_f16 v[2:5], v[182:185], v[222:225], v[2:5]
	v_mfma_f32_16x16x32_f16 v[54:57], v[150:153], v[194:197], v[54:57]
	v_mfma_f32_16x16x32_f16 v[50:53], v[186:189], v[194:197], v[50:53]
	v_mfma_f32_16x16x32_f16 v[38:41], v[150:153], v[210:213], v[38:41]
	v_mfma_f32_16x16x32_f16 v[34:37], v[186:189], v[210:213], v[34:37]
	v_mfma_f32_16x16x32_f16 v[22:25], v[150:153], v[218:221], v[22:25]
	v_mfma_f32_16x16x32_f16 v[18:21], v[186:189], v[218:221], v[18:21]
	v_mfma_f32_16x16x32_f16 v[6:9], v[150:153], v[226:229], v[6:9]
	v_mfma_f32_16x16x32_f16 v[2:5], v[186:189], v[226:229], v[2:5]
	s_barrier
	s_setprio 1
	s_add_u32 s44, s44, 0x100
	s_addc_u32 s45, s45, 0
	s_add_u32 s24, s24, 0x100
	s_addc_u32 s72, s72, 0
	s_cmp_ge_u32 s73, s65
	s_mov_b32 s52, s73
	s_cbranch_scc0 .LBB0_564
.LBB0_565:
	s_setprio 0
	s_and_b64 vcc, exec, s[46:47]
	s_cbranch_vccz .LBB0_567
	s_barrier
